# v42: gdn_prep forward substitution rewritten by hand: 4-row blocks, v_pk_fma_f32 (f32) on the rectangular part, L rows through a ds_read_b128 ring, rhs operands prefetched
# speedup vs baseline: 1.1913x; 1.0161x over previous
.LBB0_3018:
	s_or_b64 exec, exec, s[0:1]
	s_and_saveexec_b64 s[0:1], s[20:21]
	s_cbranch_execz .LBB0_2859
	v_mov_b32_e32 v20, 0x8000
	ds_read_b32 v240, v88 offset:0
	ds_read_b32 v242, v88 offset:260
	ds_read_b32 v244, v88 offset:520
	ds_read_b32 v246, v88 offset:780
	ds_read_b128 v[234:237], v95
	ds_read_b128 v[248:251], v96
	ds_read_b128 v[214:217], v21 offset:50176
	ds_read_b128 v[218:221], v21 offset:50432
	ds_read_b128 v[222:225], v21 offset:50688
	ds_read_b128 v[226:229], v21 offset:50944
	ds_read_b128 v[230:233], v21 offset:51200
	s_waitcnt lgkmcnt(5)
	v_mul_f32_e32 v240, v240, v234
	v_mul_f32_e32 v242, v242, v235
	v_mul_f32_e32 v244, v244, v236
	v_mul_f32_e32 v246, v246, v237
	v_mul_f32_e32 v238, v240, v248
	v_cndmask_b32_e64 v240, v240, v238, s[26:27]
	v_mov_b32_e32 v241, 0
	v_mul_f32_e32 v6, v242, v249
	v_cndmask_b32_e64 v242, v242, v6, s[26:27]
	v_mov_b32_e32 v243, 0
	v_mul_f32_e32 v7, v244, v250
	v_cndmask_b32_e64 v244, v244, v7, s[26:27]
	v_mov_b32_e32 v245, 0
	v_mul_f32_e32 v238, v246, v251
	v_cndmask_b32_e64 v246, v246, v238, s[26:27]
	v_mov_b32_e32 v247, 0
	ds_read_b32 v200, v88 offset:1040
	ds_read_b32 v201, v88 offset:1300
	ds_read_b32 v202, v88 offset:1560
	ds_read_b32 v203, v88 offset:1820
	ds_read_b128 v[204:207], v97
	ds_read_b128 v[0:3], v98
	v_add_f32_e32 v8, v240, v241
	s_waitcnt lgkmcnt(10)
	v_fma_f32 v242, -v8, v214, v242
	v_add_f32_e32 v9, v242, v243
	ds_read_b128 v[214:217], v21 offset:51456
	s_waitcnt lgkmcnt(10)
	v_pk_fma_f32 v[244:245], v[218:219], v[8:9], v[244:245] neg_lo:[1,0,0] neg_hi:[1,0,0]
	v_add_f32_e32 v10, v244, v245
	ds_read_b128 v[218:221], v21 offset:51712
	s_waitcnt lgkmcnt(10)
	v_pk_fma_f32 v[246:247], v[222:223], v[8:9], v[246:247] neg_lo:[1,0,0] neg_hi:[1,0,0]
	v_mul_f32_e64 v254, -v10, v224
	v_add_f32_e32 v11, v246, v247
	v_add_f32_e32 v11, v11, v254
	ds_read_b128 v[222:225], v21 offset:51216
	s_waitcnt lgkmcnt(3)
	v_mul_f32_e32 v240, v200, v204
	v_mul_f32_e32 v242, v201, v205
	v_mul_f32_e32 v244, v202, v206
	v_mul_f32_e32 v246, v203, v207
	v_mul_f32_e32 v238, v240, v0
	v_cndmask_b32_e64 v240, v240, v238, s[26:27]
	v_mov_b32_e32 v241, 0
	v_mul_f32_e32 v6, v242, v1
	v_cndmask_b32_e64 v242, v242, v6, s[26:27]
	v_mov_b32_e32 v243, 0
	v_mul_f32_e32 v7, v244, v2
	v_cndmask_b32_e64 v244, v244, v7, s[26:27]
	v_mov_b32_e32 v245, 0
	v_mul_f32_e32 v238, v246, v3
	v_cndmask_b32_e64 v246, v246, v238, s[26:27]
	v_mov_b32_e32 v247, 0
	ds_read_b32 v200, v88 offset:2080
	ds_read_b32 v201, v88 offset:2340
	ds_read_b32 v202, v88 offset:2600
	ds_read_b32 v203, v88 offset:2860
	ds_read_b128 v[204:207], v99
	ds_read_b128 v[0:3], v100
	v_pk_fma_f32 v[240:241], v[226:227], v[8:9], v[240:241] neg_lo:[1,0,0] neg_hi:[1,0,0]
	v_pk_fma_f32 v[248:249], v[228:229], v[10:11], 0 neg_lo:[1,0,0] neg_hi:[1,0,0]
	ds_read_b128 v[226:229], v21 offset:51472
	v_pk_fma_f32 v[242:243], v[230:231], v[8:9], v[242:243] neg_lo:[1,0,0] neg_hi:[1,0,0]
	v_pk_fma_f32 v[250:251], v[232:233], v[10:11], 0 neg_lo:[1,0,0] neg_hi:[1,0,0]
	ds_read_b128 v[230:233], v21 offset:51728
	s_waitcnt lgkmcnt(10)
	v_pk_fma_f32 v[244:245], v[214:215], v[8:9], v[244:245] neg_lo:[1,0,0] neg_hi:[1,0,0]
	v_pk_fma_f32 v[252:253], v[216:217], v[10:11], 0 neg_lo:[1,0,0] neg_hi:[1,0,0]
	ds_read_b128 v[214:217], v21 offset:51968
	s_waitcnt lgkmcnt(10)
	v_pk_fma_f32 v[246:247], v[218:219], v[8:9], v[246:247] neg_lo:[1,0,0] neg_hi:[1,0,0]
	v_pk_fma_f32 v[254:255], v[220:221], v[10:11], 0 neg_lo:[1,0,0] neg_hi:[1,0,0]
	v_pk_add_f32 v[240:241], v[240:241], v[248:249]
	v_add_f32_e32 v12, v240, v241
	ds_read_b128 v[218:221], v21 offset:52224
	s_waitcnt lgkmcnt(10)
	v_fma_f32 v242, -v12, v222, v242
	v_pk_add_f32 v[242:243], v[242:243], v[250:251]
	v_add_f32_e32 v13, v242, v243
	ds_read_b128 v[222:225], v21 offset:52480
	s_waitcnt lgkmcnt(4)
	v_pk_fma_f32 v[244:245], v[226:227], v[12:13], v[244:245] neg_lo:[1,0,0] neg_hi:[1,0,0]
	v_pk_add_f32 v[244:245], v[244:245], v[252:253]
	v_add_f32_e32 v14, v244, v245
	ds_read_b128 v[226:229], v21 offset:52736
	s_waitcnt lgkmcnt(4)
	v_pk_fma_f32 v[246:247], v[230:231], v[12:13], v[246:247] neg_lo:[1,0,0] neg_hi:[1,0,0]
	v_fma_f32 v254, -v14, v232, v254
	v_pk_add_f32 v[246:247], v[246:247], v[254:255]
	v_add_f32_e32 v15, v246, v247
	ds_read_b128 v[230:233], v21 offset:51984
	v_mul_f32_e32 v240, v200, v204
	v_mul_f32_e32 v242, v201, v205
	v_mul_f32_e32 v244, v202, v206
	v_mul_f32_e32 v246, v203, v207
	v_mul_f32_e32 v238, v240, v0
	v_cndmask_b32_e64 v240, v240, v238, s[26:27]
	v_mov_b32_e32 v241, 0
	v_mul_f32_e32 v6, v242, v1
	v_cndmask_b32_e64 v242, v242, v6, s[26:27]
	v_mov_b32_e32 v243, 0
	v_mul_f32_e32 v7, v244, v2
	v_cndmask_b32_e64 v244, v244, v7, s[26:27]
	v_mov_b32_e32 v245, 0
	v_mul_f32_e32 v238, v246, v3
	v_cndmask_b32_e64 v246, v246, v238, s[26:27]
	v_mov_b32_e32 v247, 0
	ds_read_b32 v200, v88 offset:3120
	ds_read_b32 v201, v88 offset:3380
	ds_read_b32 v202, v88 offset:3640
	ds_read_b32 v203, v88 offset:3900
	ds_read_b128 v[204:207], v101
	ds_read_b128 v[0:3], v102
	s_waitcnt lgkmcnt(10)
	v_pk_fma_f32 v[240:241], v[214:215], v[8:9], v[240:241] neg_lo:[1,0,0] neg_hi:[1,0,0]
	v_pk_fma_f32 v[248:249], v[216:217], v[10:11], 0 neg_lo:[1,0,0] neg_hi:[1,0,0]
	ds_read_b128 v[214:217], v21 offset:52240
	s_waitcnt lgkmcnt(10)
	v_pk_fma_f32 v[242:243], v[218:219], v[8:9], v[242:243] neg_lo:[1,0,0] neg_hi:[1,0,0]
	v_pk_fma_f32 v[250:251], v[220:221], v[10:11], 0 neg_lo:[1,0,0] neg_hi:[1,0,0]
	ds_read_b128 v[218:221], v21 offset:52496
	s_waitcnt lgkmcnt(10)
	v_pk_fma_f32 v[244:245], v[222:223], v[8:9], v[244:245] neg_lo:[1,0,0] neg_hi:[1,0,0]
	v_pk_fma_f32 v[252:253], v[224:225], v[10:11], 0 neg_lo:[1,0,0] neg_hi:[1,0,0]
	ds_read_b128 v[222:225], v21 offset:52752
	s_waitcnt lgkmcnt(10)
	v_pk_fma_f32 v[246:247], v[226:227], v[8:9], v[246:247] neg_lo:[1,0,0] neg_hi:[1,0,0]
	v_pk_fma_f32 v[254:255], v[228:229], v[10:11], 0 neg_lo:[1,0,0] neg_hi:[1,0,0]
	ds_read_b128 v[226:229], v21 offset:52256
	s_waitcnt lgkmcnt(10)
	v_pk_fma_f32 v[240:241], v[230:231], v[12:13], v[240:241] neg_lo:[1,0,0] neg_hi:[1,0,0]
	v_pk_fma_f32 v[248:249], v[232:233], v[14:15], v[248:249] neg_lo:[1,0,0] neg_hi:[1,0,0]
	ds_read_b128 v[230:233], v21 offset:52512
	s_waitcnt lgkmcnt(4)
	v_pk_fma_f32 v[242:243], v[214:215], v[12:13], v[242:243] neg_lo:[1,0,0] neg_hi:[1,0,0]
	v_pk_fma_f32 v[250:251], v[216:217], v[14:15], v[250:251] neg_lo:[1,0,0] neg_hi:[1,0,0]
	ds_read_b128 v[214:217], v21 offset:52768
	s_waitcnt lgkmcnt(4)
	v_pk_fma_f32 v[244:245], v[218:219], v[12:13], v[244:245] neg_lo:[1,0,0] neg_hi:[1,0,0]
	v_pk_fma_f32 v[252:253], v[220:221], v[14:15], v[252:253] neg_lo:[1,0,0] neg_hi:[1,0,0]
	ds_read_b128 v[218:221], v21 offset:52992
	s_waitcnt lgkmcnt(4)
	v_pk_fma_f32 v[246:247], v[222:223], v[12:13], v[246:247] neg_lo:[1,0,0] neg_hi:[1,0,0]
	v_pk_fma_f32 v[254:255], v[224:225], v[14:15], v[254:255] neg_lo:[1,0,0] neg_hi:[1,0,0]
	v_pk_add_f32 v[240:241], v[240:241], v[248:249]
	v_add_f32_e32 v4, v240, v241
	ds_read_b128 v[222:225], v21 offset:53248
	s_waitcnt lgkmcnt(4)
	v_fma_f32 v242, -v4, v226, v242
	v_pk_add_f32 v[242:243], v[242:243], v[250:251]
	v_add_f32_e32 v5, v242, v243
	ds_read_b128 v[226:229], v21 offset:53504
	s_waitcnt lgkmcnt(4)
	v_pk_fma_f32 v[244:245], v[230:231], v[4:5], v[244:245] neg_lo:[1,0,0] neg_hi:[1,0,0]
	v_pk_add_f32 v[244:245], v[244:245], v[252:253]
	v_add_f32_e32 v44, v244, v245
	ds_read_b128 v[230:233], v21 offset:53760
	s_waitcnt lgkmcnt(4)
	v_pk_fma_f32 v[246:247], v[214:215], v[4:5], v[246:247] neg_lo:[1,0,0] neg_hi:[1,0,0]
	v_fma_f32 v254, -v44, v216, v254
	v_pk_add_f32 v[246:247], v[246:247], v[254:255]
	v_add_f32_e32 v45, v246, v247
	ds_read_b128 v[214:217], v21 offset:53008
	v_mul_f32_e32 v240, v200, v204
	v_mul_f32_e32 v242, v201, v205
	v_mul_f32_e32 v244, v202, v206
	v_mul_f32_e32 v246, v203, v207
	v_mul_f32_e32 v238, v240, v0
	v_cndmask_b32_e64 v240, v240, v238, s[26:27]
	v_mov_b32_e32 v241, 0
	v_mul_f32_e32 v6, v242, v1
	v_cndmask_b32_e64 v242, v242, v6, s[26:27]
	v_mov_b32_e32 v243, 0
	v_mul_f32_e32 v7, v244, v2
	v_cndmask_b32_e64 v244, v244, v7, s[26:27]
	v_mov_b32_e32 v245, 0
	v_mul_f32_e32 v238, v246, v3
	v_cndmask_b32_e64 v246, v246, v238, s[26:27]
	v_mov_b32_e32 v247, 0
	ds_read_b32 v200, v88 offset:4160
	ds_read_b32 v201, v88 offset:4420
	ds_read_b32 v202, v88 offset:4680
	ds_read_b32 v203, v88 offset:4940
	ds_read_b128 v[204:207], v103
	ds_read_b128 v[0:3], v104
	s_waitcnt lgkmcnt(10)
	v_pk_fma_f32 v[240:241], v[218:219], v[8:9], v[240:241] neg_lo:[1,0,0] neg_hi:[1,0,0]
	v_pk_fma_f32 v[248:249], v[220:221], v[10:11], 0 neg_lo:[1,0,0] neg_hi:[1,0,0]
	ds_read_b128 v[218:221], v21 offset:53264
	s_waitcnt lgkmcnt(10)
	v_pk_fma_f32 v[242:243], v[222:223], v[8:9], v[242:243] neg_lo:[1,0,0] neg_hi:[1,0,0]
	v_pk_fma_f32 v[250:251], v[224:225], v[10:11], 0 neg_lo:[1,0,0] neg_hi:[1,0,0]
	ds_read_b128 v[222:225], v21 offset:53520
	s_waitcnt lgkmcnt(10)
	v_pk_fma_f32 v[244:245], v[226:227], v[8:9], v[244:245] neg_lo:[1,0,0] neg_hi:[1,0,0]
	v_pk_fma_f32 v[252:253], v[228:229], v[10:11], 0 neg_lo:[1,0,0] neg_hi:[1,0,0]
	ds_read_b128 v[226:229], v21 offset:53776
	s_waitcnt lgkmcnt(10)
	v_pk_fma_f32 v[246:247], v[230:231], v[8:9], v[246:247] neg_lo:[1,0,0] neg_hi:[1,0,0]
	v_pk_fma_f32 v[254:255], v[232:233], v[10:11], 0 neg_lo:[1,0,0] neg_hi:[1,0,0]
	ds_read_b128 v[230:233], v21 offset:53024
	s_waitcnt lgkmcnt(10)
	v_pk_fma_f32 v[240:241], v[214:215], v[12:13], v[240:241] neg_lo:[1,0,0] neg_hi:[1,0,0]
	v_pk_fma_f32 v[248:249], v[216:217], v[14:15], v[248:249] neg_lo:[1,0,0] neg_hi:[1,0,0]
	ds_read_b128 v[214:217], v21 offset:53280
	s_waitcnt lgkmcnt(4)
	v_pk_fma_f32 v[242:243], v[218:219], v[12:13], v[242:243] neg_lo:[1,0,0] neg_hi:[1,0,0]
	v_pk_fma_f32 v[250:251], v[220:221], v[14:15], v[250:251] neg_lo:[1,0,0] neg_hi:[1,0,0]
	ds_read_b128 v[218:221], v21 offset:53536
	s_waitcnt lgkmcnt(4)
	v_pk_fma_f32 v[244:245], v[222:223], v[12:13], v[244:245] neg_lo:[1,0,0] neg_hi:[1,0,0]
	v_pk_fma_f32 v[252:253], v[224:225], v[14:15], v[252:253] neg_lo:[1,0,0] neg_hi:[1,0,0]
	ds_read_b128 v[222:225], v21 offset:53792
	s_waitcnt lgkmcnt(4)
	v_pk_fma_f32 v[246:247], v[226:227], v[12:13], v[246:247] neg_lo:[1,0,0] neg_hi:[1,0,0]
	v_pk_fma_f32 v[254:255], v[228:229], v[14:15], v[254:255] neg_lo:[1,0,0] neg_hi:[1,0,0]
	ds_read_b128 v[226:229], v21 offset:53296
	s_waitcnt lgkmcnt(4)
	v_pk_fma_f32 v[240:241], v[230:231], v[4:5], v[240:241] neg_lo:[1,0,0] neg_hi:[1,0,0]
	v_pk_fma_f32 v[248:249], v[232:233], v[44:45], v[248:249] neg_lo:[1,0,0] neg_hi:[1,0,0]
	ds_read_b128 v[230:233], v21 offset:53552
	s_waitcnt lgkmcnt(4)
	v_pk_fma_f32 v[242:243], v[214:215], v[4:5], v[242:243] neg_lo:[1,0,0] neg_hi:[1,0,0]
	v_pk_fma_f32 v[250:251], v[216:217], v[44:45], v[250:251] neg_lo:[1,0,0] neg_hi:[1,0,0]
	ds_read_b128 v[214:217], v21 offset:53808
	s_waitcnt lgkmcnt(4)
	v_pk_fma_f32 v[244:245], v[218:219], v[4:5], v[244:245] neg_lo:[1,0,0] neg_hi:[1,0,0]
	v_pk_fma_f32 v[252:253], v[220:221], v[44:45], v[252:253] neg_lo:[1,0,0] neg_hi:[1,0,0]
	ds_read_b128 v[218:221], v21 offset:54016
	s_waitcnt lgkmcnt(4)
	v_pk_fma_f32 v[246:247], v[222:223], v[4:5], v[246:247] neg_lo:[1,0,0] neg_hi:[1,0,0]
	v_pk_fma_f32 v[254:255], v[224:225], v[44:45], v[254:255] neg_lo:[1,0,0] neg_hi:[1,0,0]
	v_pk_add_f32 v[240:241], v[240:241], v[248:249]
	v_add_f32_e32 v46, v240, v241
	ds_read_b128 v[222:225], v21 offset:54272
	s_waitcnt lgkmcnt(4)
	v_fma_f32 v242, -v46, v226, v242
	v_pk_add_f32 v[242:243], v[242:243], v[250:251]
	v_add_f32_e32 v47, v242, v243
	ds_read_b128 v[226:229], v21 offset:54528
	s_waitcnt lgkmcnt(4)
	v_pk_fma_f32 v[244:245], v[230:231], v[46:47], v[244:245] neg_lo:[1,0,0] neg_hi:[1,0,0]
	v_pk_add_f32 v[244:245], v[244:245], v[252:253]
	v_add_f32_e32 v48, v244, v245
	ds_read_b128 v[230:233], v21 offset:54784
	s_waitcnt lgkmcnt(4)
	v_pk_fma_f32 v[246:247], v[214:215], v[46:47], v[246:247] neg_lo:[1,0,0] neg_hi:[1,0,0]
	v_fma_f32 v254, -v48, v216, v254
	v_pk_add_f32 v[246:247], v[246:247], v[254:255]
	v_add_f32_e32 v49, v246, v247
	ds_read_b128 v[214:217], v21 offset:54032
	v_mul_f32_e32 v240, v200, v204
	v_mul_f32_e32 v242, v201, v205
	v_mul_f32_e32 v244, v202, v206
	v_mul_f32_e32 v246, v203, v207
	v_mul_f32_e32 v238, v240, v0
	v_cndmask_b32_e64 v240, v240, v238, s[26:27]
	v_mov_b32_e32 v241, 0
	v_mul_f32_e32 v6, v242, v1
	v_cndmask_b32_e64 v242, v242, v6, s[26:27]
	v_mov_b32_e32 v243, 0
	v_mul_f32_e32 v7, v244, v2
	v_cndmask_b32_e64 v244, v244, v7, s[26:27]
	v_mov_b32_e32 v245, 0
	v_mul_f32_e32 v238, v246, v3
	v_cndmask_b32_e64 v246, v246, v238, s[26:27]
	v_mov_b32_e32 v247, 0
	ds_read_b32 v200, v88 offset:5200
	ds_read_b32 v201, v88 offset:5460
	ds_read_b32 v202, v88 offset:5720
	ds_read_b32 v203, v88 offset:5980
	ds_read_b128 v[204:207], v105
	ds_read_b128 v[0:3], v106
	s_waitcnt lgkmcnt(10)
	v_pk_fma_f32 v[240:241], v[218:219], v[8:9], v[240:241] neg_lo:[1,0,0] neg_hi:[1,0,0]
	v_pk_fma_f32 v[248:249], v[220:221], v[10:11], 0 neg_lo:[1,0,0] neg_hi:[1,0,0]
	ds_read_b128 v[218:221], v21 offset:54288
	s_waitcnt lgkmcnt(10)
	v_pk_fma_f32 v[242:243], v[222:223], v[8:9], v[242:243] neg_lo:[1,0,0] neg_hi:[1,0,0]
	v_pk_fma_f32 v[250:251], v[224:225], v[10:11], 0 neg_lo:[1,0,0] neg_hi:[1,0,0]
	ds_read_b128 v[222:225], v21 offset:54544
	s_waitcnt lgkmcnt(10)
	v_pk_fma_f32 v[244:245], v[226:227], v[8:9], v[244:245] neg_lo:[1,0,0] neg_hi:[1,0,0]
	v_pk_fma_f32 v[252:253], v[228:229], v[10:11], 0 neg_lo:[1,0,0] neg_hi:[1,0,0]
	ds_read_b128 v[226:229], v21 offset:54800
	s_waitcnt lgkmcnt(10)
	v_pk_fma_f32 v[246:247], v[230:231], v[8:9], v[246:247] neg_lo:[1,0,0] neg_hi:[1,0,0]
	v_pk_fma_f32 v[254:255], v[232:233], v[10:11], 0 neg_lo:[1,0,0] neg_hi:[1,0,0]
	ds_read_b128 v[230:233], v21 offset:54048
	s_waitcnt lgkmcnt(10)
	v_pk_fma_f32 v[240:241], v[214:215], v[12:13], v[240:241] neg_lo:[1,0,0] neg_hi:[1,0,0]
	v_pk_fma_f32 v[248:249], v[216:217], v[14:15], v[248:249] neg_lo:[1,0,0] neg_hi:[1,0,0]
	ds_read_b128 v[214:217], v21 offset:54304
	s_waitcnt lgkmcnt(4)
	v_pk_fma_f32 v[242:243], v[218:219], v[12:13], v[242:243] neg_lo:[1,0,0] neg_hi:[1,0,0]
	v_pk_fma_f32 v[250:251], v[220:221], v[14:15], v[250:251] neg_lo:[1,0,0] neg_hi:[1,0,0]
	ds_read_b128 v[218:221], v21 offset:54560
	s_waitcnt lgkmcnt(4)
	v_pk_fma_f32 v[244:245], v[222:223], v[12:13], v[244:245] neg_lo:[1,0,0] neg_hi:[1,0,0]
	v_pk_fma_f32 v[252:253], v[224:225], v[14:15], v[252:253] neg_lo:[1,0,0] neg_hi:[1,0,0]
	ds_read_b128 v[222:225], v21 offset:54816
	s_waitcnt lgkmcnt(4)
	v_pk_fma_f32 v[246:247], v[226:227], v[12:13], v[246:247] neg_lo:[1,0,0] neg_hi:[1,0,0]
	v_pk_fma_f32 v[254:255], v[228:229], v[14:15], v[254:255] neg_lo:[1,0,0] neg_hi:[1,0,0]
	ds_read_b128 v[226:229], v21 offset:54064
	s_waitcnt lgkmcnt(4)
	v_pk_fma_f32 v[240:241], v[230:231], v[4:5], v[240:241] neg_lo:[1,0,0] neg_hi:[1,0,0]
	v_pk_fma_f32 v[248:249], v[232:233], v[44:45], v[248:249] neg_lo:[1,0,0] neg_hi:[1,0,0]
	ds_read_b128 v[230:233], v21 offset:54320
	s_waitcnt lgkmcnt(4)
	v_pk_fma_f32 v[242:243], v[214:215], v[4:5], v[242:243] neg_lo:[1,0,0] neg_hi:[1,0,0]
	v_pk_fma_f32 v[250:251], v[216:217], v[44:45], v[250:251] neg_lo:[1,0,0] neg_hi:[1,0,0]
	ds_read_b128 v[214:217], v21 offset:54576
	s_waitcnt lgkmcnt(4)
	v_pk_fma_f32 v[244:245], v[218:219], v[4:5], v[244:245] neg_lo:[1,0,0] neg_hi:[1,0,0]
	v_pk_fma_f32 v[252:253], v[220:221], v[44:45], v[252:253] neg_lo:[1,0,0] neg_hi:[1,0,0]
	ds_read_b128 v[218:221], v21 offset:54832
	s_waitcnt lgkmcnt(4)
	v_pk_fma_f32 v[246:247], v[222:223], v[4:5], v[246:247] neg_lo:[1,0,0] neg_hi:[1,0,0]
	v_pk_fma_f32 v[254:255], v[224:225], v[44:45], v[254:255] neg_lo:[1,0,0] neg_hi:[1,0,0]
	ds_read_b128 v[222:225], v21 offset:54336
	s_waitcnt lgkmcnt(4)
	v_pk_fma_f32 v[240:241], v[226:227], v[46:47], v[240:241] neg_lo:[1,0,0] neg_hi:[1,0,0]
	v_pk_fma_f32 v[248:249], v[228:229], v[48:49], v[248:249] neg_lo:[1,0,0] neg_hi:[1,0,0]
	ds_read_b128 v[226:229], v21 offset:54592
	s_waitcnt lgkmcnt(4)
	v_pk_fma_f32 v[242:243], v[230:231], v[46:47], v[242:243] neg_lo:[1,0,0] neg_hi:[1,0,0]
	v_pk_fma_f32 v[250:251], v[232:233], v[48:49], v[250:251] neg_lo:[1,0,0] neg_hi:[1,0,0]
	ds_read_b128 v[230:233], v21 offset:54848
	s_waitcnt lgkmcnt(4)
	v_pk_fma_f32 v[244:245], v[214:215], v[46:47], v[244:245] neg_lo:[1,0,0] neg_hi:[1,0,0]
	v_pk_fma_f32 v[252:253], v[216:217], v[48:49], v[252:253] neg_lo:[1,0,0] neg_hi:[1,0,0]
	ds_read_b128 v[214:217], v21 offset:55040
	s_waitcnt lgkmcnt(4)
	v_pk_fma_f32 v[246:247], v[218:219], v[46:47], v[246:247] neg_lo:[1,0,0] neg_hi:[1,0,0]
	v_pk_fma_f32 v[254:255], v[220:221], v[48:49], v[254:255] neg_lo:[1,0,0] neg_hi:[1,0,0]
	v_pk_add_f32 v[240:241], v[240:241], v[248:249]
	v_add_f32_e32 v50, v240, v241
	ds_read_b128 v[218:221], v21 offset:55296
	s_waitcnt lgkmcnt(4)
	v_fma_f32 v242, -v50, v222, v242
	v_pk_add_f32 v[242:243], v[242:243], v[250:251]
	v_add_f32_e32 v51, v242, v243
	ds_read_b128 v[222:225], v21 offset:55552
	s_waitcnt lgkmcnt(4)
	v_pk_fma_f32 v[244:245], v[226:227], v[50:51], v[244:245] neg_lo:[1,0,0] neg_hi:[1,0,0]
	v_pk_add_f32 v[244:245], v[244:245], v[252:253]
	v_add_f32_e32 v52, v244, v245
	ds_read_b128 v[226:229], v21 offset:55808
	s_waitcnt lgkmcnt(4)
	v_pk_fma_f32 v[246:247], v[230:231], v[50:51], v[246:247] neg_lo:[1,0,0] neg_hi:[1,0,0]
	v_fma_f32 v254, -v52, v232, v254
	v_pk_add_f32 v[246:247], v[246:247], v[254:255]
	v_add_f32_e32 v53, v246, v247
	ds_read_b128 v[230:233], v21 offset:55056
	v_mul_f32_e32 v240, v200, v204
	v_mul_f32_e32 v242, v201, v205
	v_mul_f32_e32 v244, v202, v206
	v_mul_f32_e32 v246, v203, v207
	v_mul_f32_e32 v238, v240, v0
	v_cndmask_b32_e64 v240, v240, v238, s[26:27]
	v_mov_b32_e32 v241, 0
	v_mul_f32_e32 v6, v242, v1
	v_cndmask_b32_e64 v242, v242, v6, s[26:27]
	v_mov_b32_e32 v243, 0
	v_mul_f32_e32 v7, v244, v2
	v_cndmask_b32_e64 v244, v244, v7, s[26:27]
	v_mov_b32_e32 v245, 0
	v_mul_f32_e32 v238, v246, v3
	v_cndmask_b32_e64 v246, v246, v238, s[26:27]
	v_mov_b32_e32 v247, 0
	ds_read_b32 v200, v88 offset:6240
	ds_read_b32 v201, v88 offset:6500
	ds_read_b32 v202, v88 offset:6760
	ds_read_b32 v203, v88 offset:7020
	ds_read_b128 v[204:207], v107
	ds_read_b128 v[0:3], v108
	s_waitcnt lgkmcnt(10)
	v_pk_fma_f32 v[240:241], v[214:215], v[8:9], v[240:241] neg_lo:[1,0,0] neg_hi:[1,0,0]
	v_pk_fma_f32 v[248:249], v[216:217], v[10:11], 0 neg_lo:[1,0,0] neg_hi:[1,0,0]
	ds_read_b128 v[214:217], v21 offset:55312
	s_waitcnt lgkmcnt(10)
	v_pk_fma_f32 v[242:243], v[218:219], v[8:9], v[242:243] neg_lo:[1,0,0] neg_hi:[1,0,0]
	v_pk_fma_f32 v[250:251], v[220:221], v[10:11], 0 neg_lo:[1,0,0] neg_hi:[1,0,0]
	ds_read_b128 v[218:221], v21 offset:55568
	s_waitcnt lgkmcnt(10)
	v_pk_fma_f32 v[244:245], v[222:223], v[8:9], v[244:245] neg_lo:[1,0,0] neg_hi:[1,0,0]
	v_pk_fma_f32 v[252:253], v[224:225], v[10:11], 0 neg_lo:[1,0,0] neg_hi:[1,0,0]
	ds_read_b128 v[222:225], v21 offset:55824
	s_waitcnt lgkmcnt(10)
	v_pk_fma_f32 v[246:247], v[226:227], v[8:9], v[246:247] neg_lo:[1,0,0] neg_hi:[1,0,0]
	v_pk_fma_f32 v[254:255], v[228:229], v[10:11], 0 neg_lo:[1,0,0] neg_hi:[1,0,0]
	ds_read_b128 v[226:229], v21 offset:55072
	s_waitcnt lgkmcnt(10)
	v_pk_fma_f32 v[240:241], v[230:231], v[12:13], v[240:241] neg_lo:[1,0,0] neg_hi:[1,0,0]
	v_pk_fma_f32 v[248:249], v[232:233], v[14:15], v[248:249] neg_lo:[1,0,0] neg_hi:[1,0,0]
	ds_read_b128 v[230:233], v21 offset:55328
	s_waitcnt lgkmcnt(4)
	v_pk_fma_f32 v[242:243], v[214:215], v[12:13], v[242:243] neg_lo:[1,0,0] neg_hi:[1,0,0]
	v_pk_fma_f32 v[250:251], v[216:217], v[14:15], v[250:251] neg_lo:[1,0,0] neg_hi:[1,0,0]
	ds_read_b128 v[214:217], v21 offset:55584
	s_waitcnt lgkmcnt(4)
	v_pk_fma_f32 v[244:245], v[218:219], v[12:13], v[244:245] neg_lo:[1,0,0] neg_hi:[1,0,0]
	v_pk_fma_f32 v[252:253], v[220:221], v[14:15], v[252:253] neg_lo:[1,0,0] neg_hi:[1,0,0]
	ds_read_b128 v[218:221], v21 offset:55840
	s_waitcnt lgkmcnt(4)
	v_pk_fma_f32 v[246:247], v[222:223], v[12:13], v[246:247] neg_lo:[1,0,0] neg_hi:[1,0,0]
	v_pk_fma_f32 v[254:255], v[224:225], v[14:15], v[254:255] neg_lo:[1,0,0] neg_hi:[1,0,0]
	ds_read_b128 v[222:225], v21 offset:55088
	s_waitcnt lgkmcnt(4)
	v_pk_fma_f32 v[240:241], v[226:227], v[4:5], v[240:241] neg_lo:[1,0,0] neg_hi:[1,0,0]
	v_pk_fma_f32 v[248:249], v[228:229], v[44:45], v[248:249] neg_lo:[1,0,0] neg_hi:[1,0,0]
	ds_read_b128 v[226:229], v21 offset:55344
	s_waitcnt lgkmcnt(4)
	v_pk_fma_f32 v[242:243], v[230:231], v[4:5], v[242:243] neg_lo:[1,0,0] neg_hi:[1,0,0]
	v_pk_fma_f32 v[250:251], v[232:233], v[44:45], v[250:251] neg_lo:[1,0,0] neg_hi:[1,0,0]
	ds_read_b128 v[230:233], v21 offset:55600
	s_waitcnt lgkmcnt(4)
	v_pk_fma_f32 v[244:245], v[214:215], v[4:5], v[244:245] neg_lo:[1,0,0] neg_hi:[1,0,0]
	v_pk_fma_f32 v[252:253], v[216:217], v[44:45], v[252:253] neg_lo:[1,0,0] neg_hi:[1,0,0]
	ds_read_b128 v[214:217], v21 offset:55856
	s_waitcnt lgkmcnt(4)
	v_pk_fma_f32 v[246:247], v[218:219], v[4:5], v[246:247] neg_lo:[1,0,0] neg_hi:[1,0,0]
	v_pk_fma_f32 v[254:255], v[220:221], v[44:45], v[254:255] neg_lo:[1,0,0] neg_hi:[1,0,0]
	ds_read_b128 v[218:221], v21 offset:55104
	s_waitcnt lgkmcnt(4)
	v_pk_fma_f32 v[240:241], v[222:223], v[46:47], v[240:241] neg_lo:[1,0,0] neg_hi:[1,0,0]
	v_pk_fma_f32 v[248:249], v[224:225], v[48:49], v[248:249] neg_lo:[1,0,0] neg_hi:[1,0,0]
	ds_read_b128 v[222:225], v21 offset:55360
	s_waitcnt lgkmcnt(4)
	v_pk_fma_f32 v[242:243], v[226:227], v[46:47], v[242:243] neg_lo:[1,0,0] neg_hi:[1,0,0]
	v_pk_fma_f32 v[250:251], v[228:229], v[48:49], v[250:251] neg_lo:[1,0,0] neg_hi:[1,0,0]
	ds_read_b128 v[226:229], v21 offset:55616
	s_waitcnt lgkmcnt(4)
	v_pk_fma_f32 v[244:245], v[230:231], v[46:47], v[244:245] neg_lo:[1,0,0] neg_hi:[1,0,0]
	v_pk_fma_f32 v[252:253], v[232:233], v[48:49], v[252:253] neg_lo:[1,0,0] neg_hi:[1,0,0]
	ds_read_b128 v[230:233], v21 offset:55872
	s_waitcnt lgkmcnt(4)
	v_pk_fma_f32 v[246:247], v[214:215], v[46:47], v[246:247] neg_lo:[1,0,0] neg_hi:[1,0,0]
	v_pk_fma_f32 v[254:255], v[216:217], v[48:49], v[254:255] neg_lo:[1,0,0] neg_hi:[1,0,0]
	ds_read_b128 v[214:217], v21 offset:55376
	s_waitcnt lgkmcnt(4)
	v_pk_fma_f32 v[240:241], v[218:219], v[50:51], v[240:241] neg_lo:[1,0,0] neg_hi:[1,0,0]
	v_pk_fma_f32 v[248:249], v[220:221], v[52:53], v[248:249] neg_lo:[1,0,0] neg_hi:[1,0,0]
	ds_read_b128 v[218:221], v21 offset:55632
	s_waitcnt lgkmcnt(4)
	v_pk_fma_f32 v[242:243], v[222:223], v[50:51], v[242:243] neg_lo:[1,0,0] neg_hi:[1,0,0]
	v_pk_fma_f32 v[250:251], v[224:225], v[52:53], v[250:251] neg_lo:[1,0,0] neg_hi:[1,0,0]
	ds_read_b128 v[222:225], v21 offset:55888
	s_waitcnt lgkmcnt(4)
	v_pk_fma_f32 v[244:245], v[226:227], v[50:51], v[244:245] neg_lo:[1,0,0] neg_hi:[1,0,0]
	v_pk_fma_f32 v[252:253], v[228:229], v[52:53], v[252:253] neg_lo:[1,0,0] neg_hi:[1,0,0]
	ds_read_b128 v[226:229], v21 offset:56064
	s_waitcnt lgkmcnt(4)
	v_pk_fma_f32 v[246:247], v[230:231], v[50:51], v[246:247] neg_lo:[1,0,0] neg_hi:[1,0,0]
	v_pk_fma_f32 v[254:255], v[232:233], v[52:53], v[254:255] neg_lo:[1,0,0] neg_hi:[1,0,0]
	v_pk_add_f32 v[240:241], v[240:241], v[248:249]
	v_add_f32_e32 v54, v240, v241
	ds_read_b128 v[230:233], v21 offset:56320
	s_waitcnt lgkmcnt(4)
	v_fma_f32 v242, -v54, v214, v242
	v_pk_add_f32 v[242:243], v[242:243], v[250:251]
	v_add_f32_e32 v55, v242, v243
	ds_read_b128 v[214:217], v21 offset:56576
	s_waitcnt lgkmcnt(4)
	v_pk_fma_f32 v[244:245], v[218:219], v[54:55], v[244:245] neg_lo:[1,0,0] neg_hi:[1,0,0]
	v_pk_add_f32 v[244:245], v[244:245], v[252:253]
	v_add_f32_e32 v56, v244, v245
	ds_read_b128 v[218:221], v21 offset:56832
	s_waitcnt lgkmcnt(4)
	v_pk_fma_f32 v[246:247], v[222:223], v[54:55], v[246:247] neg_lo:[1,0,0] neg_hi:[1,0,0]
	v_fma_f32 v254, -v56, v224, v254
	v_pk_add_f32 v[246:247], v[246:247], v[254:255]
	v_add_f32_e32 v57, v246, v247
	ds_read_b128 v[222:225], v21 offset:56080
	v_mul_f32_e32 v240, v200, v204
	v_mul_f32_e32 v242, v201, v205
	v_mul_f32_e32 v244, v202, v206
	v_mul_f32_e32 v246, v203, v207
	v_mul_f32_e32 v238, v240, v0
	v_cndmask_b32_e64 v240, v240, v238, s[26:27]
	v_mov_b32_e32 v241, 0
	v_mul_f32_e32 v6, v242, v1
	v_cndmask_b32_e64 v242, v242, v6, s[26:27]
	v_mov_b32_e32 v243, 0
	v_mul_f32_e32 v7, v244, v2
	v_cndmask_b32_e64 v244, v244, v7, s[26:27]
	v_mov_b32_e32 v245, 0
	v_mul_f32_e32 v238, v246, v3
	v_cndmask_b32_e64 v246, v246, v238, s[26:27]
	v_mov_b32_e32 v247, 0
	ds_read_b32 v200, v88 offset:7280
	ds_read_b32 v201, v88 offset:7540
	ds_read_b32 v202, v88 offset:7800
	ds_read_b32 v203, v88 offset:8060
	ds_read_b128 v[204:207], v109
	ds_read_b128 v[0:3], v110
	s_waitcnt lgkmcnt(10)
	v_pk_fma_f32 v[240:241], v[226:227], v[8:9], v[240:241] neg_lo:[1,0,0] neg_hi:[1,0,0]
	v_pk_fma_f32 v[248:249], v[228:229], v[10:11], 0 neg_lo:[1,0,0] neg_hi:[1,0,0]
	ds_read_b128 v[226:229], v21 offset:56336
	s_waitcnt lgkmcnt(10)
	v_pk_fma_f32 v[242:243], v[230:231], v[8:9], v[242:243] neg_lo:[1,0,0] neg_hi:[1,0,0]
	v_pk_fma_f32 v[250:251], v[232:233], v[10:11], 0 neg_lo:[1,0,0] neg_hi:[1,0,0]
	ds_read_b128 v[230:233], v21 offset:56592
	s_waitcnt lgkmcnt(10)
	v_pk_fma_f32 v[244:245], v[214:215], v[8:9], v[244:245] neg_lo:[1,0,0] neg_hi:[1,0,0]
	v_pk_fma_f32 v[252:253], v[216:217], v[10:11], 0 neg_lo:[1,0,0] neg_hi:[1,0,0]
	ds_read_b128 v[214:217], v21 offset:56848
	s_waitcnt lgkmcnt(10)
	v_pk_fma_f32 v[246:247], v[218:219], v[8:9], v[246:247] neg_lo:[1,0,0] neg_hi:[1,0,0]
	v_pk_fma_f32 v[254:255], v[220:221], v[10:11], 0 neg_lo:[1,0,0] neg_hi:[1,0,0]
	ds_read_b128 v[218:221], v21 offset:56096
	s_waitcnt lgkmcnt(10)
	v_pk_fma_f32 v[240:241], v[222:223], v[12:13], v[240:241] neg_lo:[1,0,0] neg_hi:[1,0,0]
	v_pk_fma_f32 v[248:249], v[224:225], v[14:15], v[248:249] neg_lo:[1,0,0] neg_hi:[1,0,0]
	ds_read_b128 v[222:225], v21 offset:56352
	s_waitcnt lgkmcnt(4)
	v_pk_fma_f32 v[242:243], v[226:227], v[12:13], v[242:243] neg_lo:[1,0,0] neg_hi:[1,0,0]
	v_pk_fma_f32 v[250:251], v[228:229], v[14:15], v[250:251] neg_lo:[1,0,0] neg_hi:[1,0,0]
	ds_read_b128 v[226:229], v21 offset:56608
	s_waitcnt lgkmcnt(4)
	v_pk_fma_f32 v[244:245], v[230:231], v[12:13], v[244:245] neg_lo:[1,0,0] neg_hi:[1,0,0]
	v_pk_fma_f32 v[252:253], v[232:233], v[14:15], v[252:253] neg_lo:[1,0,0] neg_hi:[1,0,0]
	ds_read_b128 v[230:233], v21 offset:56864
	s_waitcnt lgkmcnt(4)
	v_pk_fma_f32 v[246:247], v[214:215], v[12:13], v[246:247] neg_lo:[1,0,0] neg_hi:[1,0,0]
	v_pk_fma_f32 v[254:255], v[216:217], v[14:15], v[254:255] neg_lo:[1,0,0] neg_hi:[1,0,0]
	ds_read_b128 v[214:217], v21 offset:56112
	s_waitcnt lgkmcnt(4)
	v_pk_fma_f32 v[240:241], v[218:219], v[4:5], v[240:241] neg_lo:[1,0,0] neg_hi:[1,0,0]
	v_pk_fma_f32 v[248:249], v[220:221], v[44:45], v[248:249] neg_lo:[1,0,0] neg_hi:[1,0,0]
	ds_read_b128 v[218:221], v21 offset:56368
	s_waitcnt lgkmcnt(4)
	v_pk_fma_f32 v[242:243], v[222:223], v[4:5], v[242:243] neg_lo:[1,0,0] neg_hi:[1,0,0]
	v_pk_fma_f32 v[250:251], v[224:225], v[44:45], v[250:251] neg_lo:[1,0,0] neg_hi:[1,0,0]
	ds_read_b128 v[222:225], v21 offset:56624
	s_waitcnt lgkmcnt(4)
	v_pk_fma_f32 v[244:245], v[226:227], v[4:5], v[244:245] neg_lo:[1,0,0] neg_hi:[1,0,0]
	v_pk_fma_f32 v[252:253], v[228:229], v[44:45], v[252:253] neg_lo:[1,0,0] neg_hi:[1,0,0]
	ds_read_b128 v[226:229], v21 offset:56880
	s_waitcnt lgkmcnt(4)
	v_pk_fma_f32 v[246:247], v[230:231], v[4:5], v[246:247] neg_lo:[1,0,0] neg_hi:[1,0,0]
	v_pk_fma_f32 v[254:255], v[232:233], v[44:45], v[254:255] neg_lo:[1,0,0] neg_hi:[1,0,0]
	ds_read_b128 v[230:233], v21 offset:56128
	s_waitcnt lgkmcnt(4)
	v_pk_fma_f32 v[240:241], v[214:215], v[46:47], v[240:241] neg_lo:[1,0,0] neg_hi:[1,0,0]
	v_pk_fma_f32 v[248:249], v[216:217], v[48:49], v[248:249] neg_lo:[1,0,0] neg_hi:[1,0,0]
	ds_read_b128 v[214:217], v21 offset:56384
	s_waitcnt lgkmcnt(4)
	v_pk_fma_f32 v[242:243], v[218:219], v[46:47], v[242:243] neg_lo:[1,0,0] neg_hi:[1,0,0]
	v_pk_fma_f32 v[250:251], v[220:221], v[48:49], v[250:251] neg_lo:[1,0,0] neg_hi:[1,0,0]
	ds_read_b128 v[218:221], v21 offset:56640
	s_waitcnt lgkmcnt(4)
	v_pk_fma_f32 v[244:245], v[222:223], v[46:47], v[244:245] neg_lo:[1,0,0] neg_hi:[1,0,0]
	v_pk_fma_f32 v[252:253], v[224:225], v[48:49], v[252:253] neg_lo:[1,0,0] neg_hi:[1,0,0]
	ds_read_b128 v[222:225], v21 offset:56896
	s_waitcnt lgkmcnt(4)
	v_pk_fma_f32 v[246:247], v[226:227], v[46:47], v[246:247] neg_lo:[1,0,0] neg_hi:[1,0,0]
	v_pk_fma_f32 v[254:255], v[228:229], v[48:49], v[254:255] neg_lo:[1,0,0] neg_hi:[1,0,0]
	ds_read_b128 v[226:229], v21 offset:56144
	s_waitcnt lgkmcnt(4)
	v_pk_fma_f32 v[240:241], v[230:231], v[50:51], v[240:241] neg_lo:[1,0,0] neg_hi:[1,0,0]
	v_pk_fma_f32 v[248:249], v[232:233], v[52:53], v[248:249] neg_lo:[1,0,0] neg_hi:[1,0,0]
	ds_read_b128 v[230:233], v21 offset:56400
	s_waitcnt lgkmcnt(4)
	v_pk_fma_f32 v[242:243], v[214:215], v[50:51], v[242:243] neg_lo:[1,0,0] neg_hi:[1,0,0]
	v_pk_fma_f32 v[250:251], v[216:217], v[52:53], v[250:251] neg_lo:[1,0,0] neg_hi:[1,0,0]
	ds_read_b128 v[214:217], v21 offset:56656
	s_waitcnt lgkmcnt(4)
	v_pk_fma_f32 v[244:245], v[218:219], v[50:51], v[244:245] neg_lo:[1,0,0] neg_hi:[1,0,0]
	v_pk_fma_f32 v[252:253], v[220:221], v[52:53], v[252:253] neg_lo:[1,0,0] neg_hi:[1,0,0]
	ds_read_b128 v[218:221], v21 offset:56912
	s_waitcnt lgkmcnt(4)
	v_pk_fma_f32 v[246:247], v[222:223], v[50:51], v[246:247] neg_lo:[1,0,0] neg_hi:[1,0,0]
	v_pk_fma_f32 v[254:255], v[224:225], v[52:53], v[254:255] neg_lo:[1,0,0] neg_hi:[1,0,0]
	ds_read_b128 v[222:225], v21 offset:56416
	s_waitcnt lgkmcnt(4)
	v_pk_fma_f32 v[240:241], v[226:227], v[54:55], v[240:241] neg_lo:[1,0,0] neg_hi:[1,0,0]
	v_pk_fma_f32 v[248:249], v[228:229], v[56:57], v[248:249] neg_lo:[1,0,0] neg_hi:[1,0,0]
	ds_read_b128 v[226:229], v21 offset:56672
	s_waitcnt lgkmcnt(4)
	v_pk_fma_f32 v[242:243], v[230:231], v[54:55], v[242:243] neg_lo:[1,0,0] neg_hi:[1,0,0]
	v_pk_fma_f32 v[250:251], v[232:233], v[56:57], v[250:251] neg_lo:[1,0,0] neg_hi:[1,0,0]
	ds_read_b128 v[230:233], v21 offset:56928
	s_waitcnt lgkmcnt(4)
	v_pk_fma_f32 v[244:245], v[214:215], v[54:55], v[244:245] neg_lo:[1,0,0] neg_hi:[1,0,0]
	v_pk_fma_f32 v[252:253], v[216:217], v[56:57], v[252:253] neg_lo:[1,0,0] neg_hi:[1,0,0]
	ds_read_b128 v[214:217], v21 offset:57088
	s_waitcnt lgkmcnt(4)
	v_pk_fma_f32 v[246:247], v[218:219], v[54:55], v[246:247] neg_lo:[1,0,0] neg_hi:[1,0,0]
	v_pk_fma_f32 v[254:255], v[220:221], v[56:57], v[254:255] neg_lo:[1,0,0] neg_hi:[1,0,0]
	v_pk_add_f32 v[240:241], v[240:241], v[248:249]
	v_add_f32_e32 v58, v240, v241
	ds_read_b128 v[218:221], v21 offset:57344
	s_waitcnt lgkmcnt(4)
	v_fma_f32 v242, -v58, v222, v242
	v_pk_add_f32 v[242:243], v[242:243], v[250:251]
	v_add_f32_e32 v59, v242, v243
	ds_read_b128 v[222:225], v21 offset:57600
	s_waitcnt lgkmcnt(4)
	v_pk_fma_f32 v[244:245], v[226:227], v[58:59], v[244:245] neg_lo:[1,0,0] neg_hi:[1,0,0]
	v_pk_add_f32 v[244:245], v[244:245], v[252:253]
	v_add_f32_e32 v60, v244, v245
	ds_read_b128 v[226:229], v21 offset:57856
	s_waitcnt lgkmcnt(4)
	v_pk_fma_f32 v[246:247], v[230:231], v[58:59], v[246:247] neg_lo:[1,0,0] neg_hi:[1,0,0]
	v_fma_f32 v254, -v60, v232, v254
	v_pk_add_f32 v[246:247], v[246:247], v[254:255]
	v_add_f32_e32 v61, v246, v247
	ds_read_b128 v[230:233], v21 offset:57104
	v_mul_f32_e32 v240, v200, v204
	v_mul_f32_e32 v242, v201, v205
	v_mul_f32_e32 v244, v202, v206
	v_mul_f32_e32 v246, v203, v207
	v_mul_f32_e32 v238, v240, v0
	v_cndmask_b32_e64 v240, v240, v238, s[26:27]
	v_mov_b32_e32 v241, 0
	v_mul_f32_e32 v6, v242, v1
	v_cndmask_b32_e64 v242, v242, v6, s[26:27]
	v_mov_b32_e32 v243, 0
	v_mul_f32_e32 v7, v244, v2
	v_cndmask_b32_e64 v244, v244, v7, s[26:27]
	v_mov_b32_e32 v245, 0
	v_mul_f32_e32 v238, v246, v3
	v_cndmask_b32_e64 v246, v246, v238, s[26:27]
	v_mov_b32_e32 v247, 0
	ds_read_b32 v200, v88 offset:8320
	ds_read_b32 v201, v88 offset:8580
	ds_read_b32 v202, v88 offset:8840
	ds_read_b32 v203, v88 offset:9100
	ds_read_b128 v[204:207], v111
	ds_read_b128 v[0:3], v112
	s_waitcnt lgkmcnt(10)
	v_pk_fma_f32 v[240:241], v[214:215], v[8:9], v[240:241] neg_lo:[1,0,0] neg_hi:[1,0,0]
	v_pk_fma_f32 v[248:249], v[216:217], v[10:11], 0 neg_lo:[1,0,0] neg_hi:[1,0,0]
	ds_read_b128 v[214:217], v21 offset:57360
	s_waitcnt lgkmcnt(10)
	v_pk_fma_f32 v[242:243], v[218:219], v[8:9], v[242:243] neg_lo:[1,0,0] neg_hi:[1,0,0]
	v_pk_fma_f32 v[250:251], v[220:221], v[10:11], 0 neg_lo:[1,0,0] neg_hi:[1,0,0]
	ds_read_b128 v[218:221], v21 offset:57616
	s_waitcnt lgkmcnt(10)
	v_pk_fma_f32 v[244:245], v[222:223], v[8:9], v[244:245] neg_lo:[1,0,0] neg_hi:[1,0,0]
	v_pk_fma_f32 v[252:253], v[224:225], v[10:11], 0 neg_lo:[1,0,0] neg_hi:[1,0,0]
	ds_read_b128 v[222:225], v21 offset:57872
	s_waitcnt lgkmcnt(10)
	v_pk_fma_f32 v[246:247], v[226:227], v[8:9], v[246:247] neg_lo:[1,0,0] neg_hi:[1,0,0]
	v_pk_fma_f32 v[254:255], v[228:229], v[10:11], 0 neg_lo:[1,0,0] neg_hi:[1,0,0]
	ds_read_b128 v[226:229], v21 offset:57120
	s_waitcnt lgkmcnt(10)
	v_pk_fma_f32 v[240:241], v[230:231], v[12:13], v[240:241] neg_lo:[1,0,0] neg_hi:[1,0,0]
	v_pk_fma_f32 v[248:249], v[232:233], v[14:15], v[248:249] neg_lo:[1,0,0] neg_hi:[1,0,0]
	ds_read_b128 v[230:233], v21 offset:57376
	s_waitcnt lgkmcnt(4)
	v_pk_fma_f32 v[242:243], v[214:215], v[12:13], v[242:243] neg_lo:[1,0,0] neg_hi:[1,0,0]
	v_pk_fma_f32 v[250:251], v[216:217], v[14:15], v[250:251] neg_lo:[1,0,0] neg_hi:[1,0,0]
	ds_read_b128 v[214:217], v21 offset:57632
	s_waitcnt lgkmcnt(4)
	v_pk_fma_f32 v[244:245], v[218:219], v[12:13], v[244:245] neg_lo:[1,0,0] neg_hi:[1,0,0]
	v_pk_fma_f32 v[252:253], v[220:221], v[14:15], v[252:253] neg_lo:[1,0,0] neg_hi:[1,0,0]
	ds_read_b128 v[218:221], v21 offset:57888
	s_waitcnt lgkmcnt(4)
	v_pk_fma_f32 v[246:247], v[222:223], v[12:13], v[246:247] neg_lo:[1,0,0] neg_hi:[1,0,0]
	v_pk_fma_f32 v[254:255], v[224:225], v[14:15], v[254:255] neg_lo:[1,0,0] neg_hi:[1,0,0]
	ds_read_b128 v[222:225], v21 offset:57136
	s_waitcnt lgkmcnt(4)
	v_pk_fma_f32 v[240:241], v[226:227], v[4:5], v[240:241] neg_lo:[1,0,0] neg_hi:[1,0,0]
	v_pk_fma_f32 v[248:249], v[228:229], v[44:45], v[248:249] neg_lo:[1,0,0] neg_hi:[1,0,0]
	ds_read_b128 v[226:229], v21 offset:57392
	s_waitcnt lgkmcnt(4)
	v_pk_fma_f32 v[242:243], v[230:231], v[4:5], v[242:243] neg_lo:[1,0,0] neg_hi:[1,0,0]
	v_pk_fma_f32 v[250:251], v[232:233], v[44:45], v[250:251] neg_lo:[1,0,0] neg_hi:[1,0,0]
	ds_read_b128 v[230:233], v21 offset:57648
	s_waitcnt lgkmcnt(4)
	v_pk_fma_f32 v[244:245], v[214:215], v[4:5], v[244:245] neg_lo:[1,0,0] neg_hi:[1,0,0]
	v_pk_fma_f32 v[252:253], v[216:217], v[44:45], v[252:253] neg_lo:[1,0,0] neg_hi:[1,0,0]
	ds_read_b128 v[214:217], v21 offset:57904
	s_waitcnt lgkmcnt(4)
	v_pk_fma_f32 v[246:247], v[218:219], v[4:5], v[246:247] neg_lo:[1,0,0] neg_hi:[1,0,0]
	v_pk_fma_f32 v[254:255], v[220:221], v[44:45], v[254:255] neg_lo:[1,0,0] neg_hi:[1,0,0]
	ds_read_b128 v[218:221], v21 offset:57152
	s_waitcnt lgkmcnt(4)
	v_pk_fma_f32 v[240:241], v[222:223], v[46:47], v[240:241] neg_lo:[1,0,0] neg_hi:[1,0,0]
	v_pk_fma_f32 v[248:249], v[224:225], v[48:49], v[248:249] neg_lo:[1,0,0] neg_hi:[1,0,0]
	ds_read_b128 v[222:225], v21 offset:57408
	s_waitcnt lgkmcnt(4)
	v_pk_fma_f32 v[242:243], v[226:227], v[46:47], v[242:243] neg_lo:[1,0,0] neg_hi:[1,0,0]
	v_pk_fma_f32 v[250:251], v[228:229], v[48:49], v[250:251] neg_lo:[1,0,0] neg_hi:[1,0,0]
	ds_read_b128 v[226:229], v21 offset:57664
	s_waitcnt lgkmcnt(4)
	v_pk_fma_f32 v[244:245], v[230:231], v[46:47], v[244:245] neg_lo:[1,0,0] neg_hi:[1,0,0]
	v_pk_fma_f32 v[252:253], v[232:233], v[48:49], v[252:253] neg_lo:[1,0,0] neg_hi:[1,0,0]
	ds_read_b128 v[230:233], v21 offset:57920
	s_waitcnt lgkmcnt(4)
	v_pk_fma_f32 v[246:247], v[214:215], v[46:47], v[246:247] neg_lo:[1,0,0] neg_hi:[1,0,0]
	v_pk_fma_f32 v[254:255], v[216:217], v[48:49], v[254:255] neg_lo:[1,0,0] neg_hi:[1,0,0]
	ds_read_b128 v[214:217], v21 offset:57168
	s_waitcnt lgkmcnt(4)
	v_pk_fma_f32 v[240:241], v[218:219], v[50:51], v[240:241] neg_lo:[1,0,0] neg_hi:[1,0,0]
	v_pk_fma_f32 v[248:249], v[220:221], v[52:53], v[248:249] neg_lo:[1,0,0] neg_hi:[1,0,0]
	ds_read_b128 v[218:221], v21 offset:57424
	s_waitcnt lgkmcnt(4)
	v_pk_fma_f32 v[242:243], v[222:223], v[50:51], v[242:243] neg_lo:[1,0,0] neg_hi:[1,0,0]
	v_pk_fma_f32 v[250:251], v[224:225], v[52:53], v[250:251] neg_lo:[1,0,0] neg_hi:[1,0,0]
	ds_read_b128 v[222:225], v21 offset:57680
	s_waitcnt lgkmcnt(4)
	v_pk_fma_f32 v[244:245], v[226:227], v[50:51], v[244:245] neg_lo:[1,0,0] neg_hi:[1,0,0]
	v_pk_fma_f32 v[252:253], v[228:229], v[52:53], v[252:253] neg_lo:[1,0,0] neg_hi:[1,0,0]
	ds_read_b128 v[226:229], v21 offset:57936
	s_waitcnt lgkmcnt(4)
	v_pk_fma_f32 v[246:247], v[230:231], v[50:51], v[246:247] neg_lo:[1,0,0] neg_hi:[1,0,0]
	v_pk_fma_f32 v[254:255], v[232:233], v[52:53], v[254:255] neg_lo:[1,0,0] neg_hi:[1,0,0]
	ds_read_b128 v[230:233], v21 offset:57184
	s_waitcnt lgkmcnt(4)
	v_pk_fma_f32 v[240:241], v[214:215], v[54:55], v[240:241] neg_lo:[1,0,0] neg_hi:[1,0,0]
	v_pk_fma_f32 v[248:249], v[216:217], v[56:57], v[248:249] neg_lo:[1,0,0] neg_hi:[1,0,0]
	ds_read_b128 v[214:217], v21 offset:57440
	s_waitcnt lgkmcnt(4)
	v_pk_fma_f32 v[242:243], v[218:219], v[54:55], v[242:243] neg_lo:[1,0,0] neg_hi:[1,0,0]
	v_pk_fma_f32 v[250:251], v[220:221], v[56:57], v[250:251] neg_lo:[1,0,0] neg_hi:[1,0,0]
	ds_read_b128 v[218:221], v21 offset:57696
	s_waitcnt lgkmcnt(4)
	v_pk_fma_f32 v[244:245], v[222:223], v[54:55], v[244:245] neg_lo:[1,0,0] neg_hi:[1,0,0]
	v_pk_fma_f32 v[252:253], v[224:225], v[56:57], v[252:253] neg_lo:[1,0,0] neg_hi:[1,0,0]
	ds_read_b128 v[222:225], v21 offset:57952
	s_waitcnt lgkmcnt(4)
	v_pk_fma_f32 v[246:247], v[226:227], v[54:55], v[246:247] neg_lo:[1,0,0] neg_hi:[1,0,0]
	v_pk_fma_f32 v[254:255], v[228:229], v[56:57], v[254:255] neg_lo:[1,0,0] neg_hi:[1,0,0]
	ds_read_b128 v[226:229], v21 offset:57456
	s_waitcnt lgkmcnt(4)
	v_pk_fma_f32 v[240:241], v[230:231], v[58:59], v[240:241] neg_lo:[1,0,0] neg_hi:[1,0,0]
	v_pk_fma_f32 v[248:249], v[232:233], v[60:61], v[248:249] neg_lo:[1,0,0] neg_hi:[1,0,0]
	ds_read_b128 v[230:233], v21 offset:57712
	s_waitcnt lgkmcnt(4)
	v_pk_fma_f32 v[242:243], v[214:215], v[58:59], v[242:243] neg_lo:[1,0,0] neg_hi:[1,0,0]
	v_pk_fma_f32 v[250:251], v[216:217], v[60:61], v[250:251] neg_lo:[1,0,0] neg_hi:[1,0,0]
	ds_read_b128 v[214:217], v21 offset:57968
	s_waitcnt lgkmcnt(4)
	v_pk_fma_f32 v[244:245], v[218:219], v[58:59], v[244:245] neg_lo:[1,0,0] neg_hi:[1,0,0]
	v_pk_fma_f32 v[252:253], v[220:221], v[60:61], v[252:253] neg_lo:[1,0,0] neg_hi:[1,0,0]
	ds_read_b128 v[218:221], v21 offset:58112
	s_waitcnt lgkmcnt(4)
	v_pk_fma_f32 v[246:247], v[222:223], v[58:59], v[246:247] neg_lo:[1,0,0] neg_hi:[1,0,0]
	v_pk_fma_f32 v[254:255], v[224:225], v[60:61], v[254:255] neg_lo:[1,0,0] neg_hi:[1,0,0]
	v_pk_add_f32 v[240:241], v[240:241], v[248:249]
	v_add_f32_e32 v62, v240, v241
	ds_read_b128 v[222:225], v21 offset:58368
	s_waitcnt lgkmcnt(4)
	v_fma_f32 v242, -v62, v226, v242
	v_pk_add_f32 v[242:243], v[242:243], v[250:251]
	v_add_f32_e32 v63, v242, v243
	ds_read_b128 v[226:229], v21 offset:58624
	s_waitcnt lgkmcnt(4)
	v_pk_fma_f32 v[244:245], v[230:231], v[62:63], v[244:245] neg_lo:[1,0,0] neg_hi:[1,0,0]
	v_pk_add_f32 v[244:245], v[244:245], v[252:253]
	v_add_f32_e32 v64, v244, v245
	ds_read_b128 v[230:233], v21 offset:58880
	s_waitcnt lgkmcnt(4)
	v_pk_fma_f32 v[246:247], v[214:215], v[62:63], v[246:247] neg_lo:[1,0,0] neg_hi:[1,0,0]
	v_fma_f32 v254, -v64, v216, v254
	v_pk_add_f32 v[246:247], v[246:247], v[254:255]
	v_add_f32_e32 v65, v246, v247
	ds_read_b128 v[214:217], v21 offset:58128
	v_mul_f32_e32 v240, v200, v204
	v_mul_f32_e32 v242, v201, v205
	v_mul_f32_e32 v244, v202, v206
	v_mul_f32_e32 v246, v203, v207
	v_mul_f32_e32 v238, v240, v0
	v_cndmask_b32_e64 v240, v240, v238, s[26:27]
	v_mov_b32_e32 v241, 0
	v_mul_f32_e32 v6, v242, v1
	v_cndmask_b32_e64 v242, v242, v6, s[26:27]
	v_mov_b32_e32 v243, 0
	v_mul_f32_e32 v7, v244, v2
	v_cndmask_b32_e64 v244, v244, v7, s[26:27]
	v_mov_b32_e32 v245, 0
	v_mul_f32_e32 v238, v246, v3
	v_cndmask_b32_e64 v246, v246, v238, s[26:27]
	v_mov_b32_e32 v247, 0
	ds_read_b32 v200, v88 offset:9360
	ds_read_b32 v201, v88 offset:9620
	ds_read_b32 v202, v88 offset:9880
	ds_read_b32 v203, v88 offset:10140
	ds_read_b128 v[204:207], v113
	ds_read_b128 v[0:3], v114
	s_waitcnt lgkmcnt(10)
	v_pk_fma_f32 v[240:241], v[218:219], v[8:9], v[240:241] neg_lo:[1,0,0] neg_hi:[1,0,0]
	v_pk_fma_f32 v[248:249], v[220:221], v[10:11], 0 neg_lo:[1,0,0] neg_hi:[1,0,0]
	ds_read_b128 v[218:221], v21 offset:58384
	s_waitcnt lgkmcnt(10)
	v_pk_fma_f32 v[242:243], v[222:223], v[8:9], v[242:243] neg_lo:[1,0,0] neg_hi:[1,0,0]
	v_pk_fma_f32 v[250:251], v[224:225], v[10:11], 0 neg_lo:[1,0,0] neg_hi:[1,0,0]
	ds_read_b128 v[222:225], v21 offset:58640
	s_waitcnt lgkmcnt(10)
	v_pk_fma_f32 v[244:245], v[226:227], v[8:9], v[244:245] neg_lo:[1,0,0] neg_hi:[1,0,0]
	v_pk_fma_f32 v[252:253], v[228:229], v[10:11], 0 neg_lo:[1,0,0] neg_hi:[1,0,0]
	ds_read_b128 v[226:229], v21 offset:58896
	s_waitcnt lgkmcnt(10)
	v_pk_fma_f32 v[246:247], v[230:231], v[8:9], v[246:247] neg_lo:[1,0,0] neg_hi:[1,0,0]
	v_pk_fma_f32 v[254:255], v[232:233], v[10:11], 0 neg_lo:[1,0,0] neg_hi:[1,0,0]
	ds_read_b128 v[230:233], v21 offset:58144
	s_waitcnt lgkmcnt(10)
	v_pk_fma_f32 v[240:241], v[214:215], v[12:13], v[240:241] neg_lo:[1,0,0] neg_hi:[1,0,0]
	v_pk_fma_f32 v[248:249], v[216:217], v[14:15], v[248:249] neg_lo:[1,0,0] neg_hi:[1,0,0]
	ds_read_b128 v[214:217], v21 offset:58400
	s_waitcnt lgkmcnt(4)
	v_pk_fma_f32 v[242:243], v[218:219], v[12:13], v[242:243] neg_lo:[1,0,0] neg_hi:[1,0,0]
	v_pk_fma_f32 v[250:251], v[220:221], v[14:15], v[250:251] neg_lo:[1,0,0] neg_hi:[1,0,0]
	ds_read_b128 v[218:221], v21 offset:58656
	s_waitcnt lgkmcnt(4)
	v_pk_fma_f32 v[244:245], v[222:223], v[12:13], v[244:245] neg_lo:[1,0,0] neg_hi:[1,0,0]
	v_pk_fma_f32 v[252:253], v[224:225], v[14:15], v[252:253] neg_lo:[1,0,0] neg_hi:[1,0,0]
	ds_read_b128 v[222:225], v21 offset:58912
	s_waitcnt lgkmcnt(4)
	v_pk_fma_f32 v[246:247], v[226:227], v[12:13], v[246:247] neg_lo:[1,0,0] neg_hi:[1,0,0]
	v_pk_fma_f32 v[254:255], v[228:229], v[14:15], v[254:255] neg_lo:[1,0,0] neg_hi:[1,0,0]
	ds_read_b128 v[226:229], v21 offset:58160
	s_waitcnt lgkmcnt(4)
	v_pk_fma_f32 v[240:241], v[230:231], v[4:5], v[240:241] neg_lo:[1,0,0] neg_hi:[1,0,0]
	v_pk_fma_f32 v[248:249], v[232:233], v[44:45], v[248:249] neg_lo:[1,0,0] neg_hi:[1,0,0]
	ds_read_b128 v[230:233], v21 offset:58416
	s_waitcnt lgkmcnt(4)
	v_pk_fma_f32 v[242:243], v[214:215], v[4:5], v[242:243] neg_lo:[1,0,0] neg_hi:[1,0,0]
	v_pk_fma_f32 v[250:251], v[216:217], v[44:45], v[250:251] neg_lo:[1,0,0] neg_hi:[1,0,0]
	ds_read_b128 v[214:217], v21 offset:58672
	s_waitcnt lgkmcnt(4)
	v_pk_fma_f32 v[244:245], v[218:219], v[4:5], v[244:245] neg_lo:[1,0,0] neg_hi:[1,0,0]
	v_pk_fma_f32 v[252:253], v[220:221], v[44:45], v[252:253] neg_lo:[1,0,0] neg_hi:[1,0,0]
	ds_read_b128 v[218:221], v21 offset:58928
	s_waitcnt lgkmcnt(4)
	v_pk_fma_f32 v[246:247], v[222:223], v[4:5], v[246:247] neg_lo:[1,0,0] neg_hi:[1,0,0]
	v_pk_fma_f32 v[254:255], v[224:225], v[44:45], v[254:255] neg_lo:[1,0,0] neg_hi:[1,0,0]
	ds_read_b128 v[222:225], v21 offset:58176
	s_waitcnt lgkmcnt(4)
	v_pk_fma_f32 v[240:241], v[226:227], v[46:47], v[240:241] neg_lo:[1,0,0] neg_hi:[1,0,0]
	v_pk_fma_f32 v[248:249], v[228:229], v[48:49], v[248:249] neg_lo:[1,0,0] neg_hi:[1,0,0]
	ds_read_b128 v[226:229], v21 offset:58432
	s_waitcnt lgkmcnt(4)
	v_pk_fma_f32 v[242:243], v[230:231], v[46:47], v[242:243] neg_lo:[1,0,0] neg_hi:[1,0,0]
	v_pk_fma_f32 v[250:251], v[232:233], v[48:49], v[250:251] neg_lo:[1,0,0] neg_hi:[1,0,0]
	ds_read_b128 v[230:233], v21 offset:58688
	s_waitcnt lgkmcnt(4)
	v_pk_fma_f32 v[244:245], v[214:215], v[46:47], v[244:245] neg_lo:[1,0,0] neg_hi:[1,0,0]
	v_pk_fma_f32 v[252:253], v[216:217], v[48:49], v[252:253] neg_lo:[1,0,0] neg_hi:[1,0,0]
	ds_read_b128 v[214:217], v21 offset:58944
	s_waitcnt lgkmcnt(4)
	v_pk_fma_f32 v[246:247], v[218:219], v[46:47], v[246:247] neg_lo:[1,0,0] neg_hi:[1,0,0]
	v_pk_fma_f32 v[254:255], v[220:221], v[48:49], v[254:255] neg_lo:[1,0,0] neg_hi:[1,0,0]
	ds_read_b128 v[218:221], v21 offset:58192
	s_waitcnt lgkmcnt(4)
	v_pk_fma_f32 v[240:241], v[222:223], v[50:51], v[240:241] neg_lo:[1,0,0] neg_hi:[1,0,0]
	v_pk_fma_f32 v[248:249], v[224:225], v[52:53], v[248:249] neg_lo:[1,0,0] neg_hi:[1,0,0]
	ds_read_b128 v[222:225], v21 offset:58448
	s_waitcnt lgkmcnt(4)
	v_pk_fma_f32 v[242:243], v[226:227], v[50:51], v[242:243] neg_lo:[1,0,0] neg_hi:[1,0,0]
	v_pk_fma_f32 v[250:251], v[228:229], v[52:53], v[250:251] neg_lo:[1,0,0] neg_hi:[1,0,0]
	ds_read_b128 v[226:229], v21 offset:58704
	s_waitcnt lgkmcnt(4)
	v_pk_fma_f32 v[244:245], v[230:231], v[50:51], v[244:245] neg_lo:[1,0,0] neg_hi:[1,0,0]
	v_pk_fma_f32 v[252:253], v[232:233], v[52:53], v[252:253] neg_lo:[1,0,0] neg_hi:[1,0,0]
	ds_read_b128 v[230:233], v21 offset:58960
	s_waitcnt lgkmcnt(4)
	v_pk_fma_f32 v[246:247], v[214:215], v[50:51], v[246:247] neg_lo:[1,0,0] neg_hi:[1,0,0]
	v_pk_fma_f32 v[254:255], v[216:217], v[52:53], v[254:255] neg_lo:[1,0,0] neg_hi:[1,0,0]
	ds_read_b128 v[214:217], v21 offset:58208
	s_waitcnt lgkmcnt(4)
	v_pk_fma_f32 v[240:241], v[218:219], v[54:55], v[240:241] neg_lo:[1,0,0] neg_hi:[1,0,0]
	v_pk_fma_f32 v[248:249], v[220:221], v[56:57], v[248:249] neg_lo:[1,0,0] neg_hi:[1,0,0]
	ds_read_b128 v[218:221], v21 offset:58464
	s_waitcnt lgkmcnt(4)
	v_pk_fma_f32 v[242:243], v[222:223], v[54:55], v[242:243] neg_lo:[1,0,0] neg_hi:[1,0,0]
	v_pk_fma_f32 v[250:251], v[224:225], v[56:57], v[250:251] neg_lo:[1,0,0] neg_hi:[1,0,0]
	ds_read_b128 v[222:225], v21 offset:58720
	s_waitcnt lgkmcnt(4)
	v_pk_fma_f32 v[244:245], v[226:227], v[54:55], v[244:245] neg_lo:[1,0,0] neg_hi:[1,0,0]
	v_pk_fma_f32 v[252:253], v[228:229], v[56:57], v[252:253] neg_lo:[1,0,0] neg_hi:[1,0,0]
	ds_read_b128 v[226:229], v21 offset:58976
	s_waitcnt lgkmcnt(4)
	v_pk_fma_f32 v[246:247], v[230:231], v[54:55], v[246:247] neg_lo:[1,0,0] neg_hi:[1,0,0]
	v_pk_fma_f32 v[254:255], v[232:233], v[56:57], v[254:255] neg_lo:[1,0,0] neg_hi:[1,0,0]
	ds_read_b128 v[230:233], v21 offset:58224
	s_waitcnt lgkmcnt(4)
	v_pk_fma_f32 v[240:241], v[214:215], v[58:59], v[240:241] neg_lo:[1,0,0] neg_hi:[1,0,0]
	v_pk_fma_f32 v[248:249], v[216:217], v[60:61], v[248:249] neg_lo:[1,0,0] neg_hi:[1,0,0]
	ds_read_b128 v[214:217], v21 offset:58480
	s_waitcnt lgkmcnt(4)
	v_pk_fma_f32 v[242:243], v[218:219], v[58:59], v[242:243] neg_lo:[1,0,0] neg_hi:[1,0,0]
	v_pk_fma_f32 v[250:251], v[220:221], v[60:61], v[250:251] neg_lo:[1,0,0] neg_hi:[1,0,0]
	ds_read_b128 v[218:221], v21 offset:58736
	s_waitcnt lgkmcnt(4)
	v_pk_fma_f32 v[244:245], v[222:223], v[58:59], v[244:245] neg_lo:[1,0,0] neg_hi:[1,0,0]
	v_pk_fma_f32 v[252:253], v[224:225], v[60:61], v[252:253] neg_lo:[1,0,0] neg_hi:[1,0,0]
	ds_read_b128 v[222:225], v21 offset:58992
	s_waitcnt lgkmcnt(4)
	v_pk_fma_f32 v[246:247], v[226:227], v[58:59], v[246:247] neg_lo:[1,0,0] neg_hi:[1,0,0]
	v_pk_fma_f32 v[254:255], v[228:229], v[60:61], v[254:255] neg_lo:[1,0,0] neg_hi:[1,0,0]
	ds_read_b128 v[226:229], v21 offset:58496
	s_waitcnt lgkmcnt(4)
	v_pk_fma_f32 v[240:241], v[230:231], v[62:63], v[240:241] neg_lo:[1,0,0] neg_hi:[1,0,0]
	v_pk_fma_f32 v[248:249], v[232:233], v[64:65], v[248:249] neg_lo:[1,0,0] neg_hi:[1,0,0]
	ds_read_b128 v[230:233], v21 offset:58752
	s_waitcnt lgkmcnt(4)
	v_pk_fma_f32 v[242:243], v[214:215], v[62:63], v[242:243] neg_lo:[1,0,0] neg_hi:[1,0,0]
	v_pk_fma_f32 v[250:251], v[216:217], v[64:65], v[250:251] neg_lo:[1,0,0] neg_hi:[1,0,0]
	ds_read_b128 v[214:217], v21 offset:59008
	s_waitcnt lgkmcnt(4)
	v_pk_fma_f32 v[244:245], v[218:219], v[62:63], v[244:245] neg_lo:[1,0,0] neg_hi:[1,0,0]
	v_pk_fma_f32 v[252:253], v[220:221], v[64:65], v[252:253] neg_lo:[1,0,0] neg_hi:[1,0,0]
	ds_read_b128 v[218:221], v21 offset:59136
	s_waitcnt lgkmcnt(4)
	v_pk_fma_f32 v[246:247], v[222:223], v[62:63], v[246:247] neg_lo:[1,0,0] neg_hi:[1,0,0]
	v_pk_fma_f32 v[254:255], v[224:225], v[64:65], v[254:255] neg_lo:[1,0,0] neg_hi:[1,0,0]
	v_pk_add_f32 v[240:241], v[240:241], v[248:249]
	v_add_f32_e32 v66, v240, v241
	ds_read_b128 v[222:225], v21 offset:59392
	s_waitcnt lgkmcnt(4)
	v_fma_f32 v242, -v66, v226, v242
	v_pk_add_f32 v[242:243], v[242:243], v[250:251]
	v_add_f32_e32 v67, v242, v243
	ds_read_b128 v[226:229], v21 offset:59648
	s_waitcnt lgkmcnt(4)
	v_pk_fma_f32 v[244:245], v[230:231], v[66:67], v[244:245] neg_lo:[1,0,0] neg_hi:[1,0,0]
	v_pk_add_f32 v[244:245], v[244:245], v[252:253]
	v_add_f32_e32 v68, v244, v245
	ds_read_b128 v[230:233], v21 offset:59904
	s_waitcnt lgkmcnt(4)
	v_pk_fma_f32 v[246:247], v[214:215], v[66:67], v[246:247] neg_lo:[1,0,0] neg_hi:[1,0,0]
	v_fma_f32 v254, -v68, v216, v254
	v_pk_add_f32 v[246:247], v[246:247], v[254:255]
	v_add_f32_e32 v69, v246, v247
	ds_read_b128 v[214:217], v21 offset:59152
	v_mul_f32_e32 v240, v200, v204
	v_mul_f32_e32 v242, v201, v205
	v_mul_f32_e32 v244, v202, v206
	v_mul_f32_e32 v246, v203, v207
	v_mul_f32_e32 v238, v240, v0
	v_cndmask_b32_e64 v240, v240, v238, s[26:27]
	v_mov_b32_e32 v241, 0
	v_mul_f32_e32 v6, v242, v1
	v_cndmask_b32_e64 v242, v242, v6, s[26:27]
	v_mov_b32_e32 v243, 0
	v_mul_f32_e32 v7, v244, v2
	v_cndmask_b32_e64 v244, v244, v7, s[26:27]
	v_mov_b32_e32 v245, 0
	v_mul_f32_e32 v238, v246, v3
	v_cndmask_b32_e64 v246, v246, v238, s[26:27]
	v_mov_b32_e32 v247, 0
	ds_read_b32 v200, v88 offset:10400
	ds_read_b32 v201, v88 offset:10660
	ds_read_b32 v202, v88 offset:10920
	ds_read_b32 v203, v88 offset:11180
	ds_read_b128 v[204:207], v115
	ds_read_b128 v[0:3], v116
	s_waitcnt lgkmcnt(10)
	v_pk_fma_f32 v[240:241], v[218:219], v[8:9], v[240:241] neg_lo:[1,0,0] neg_hi:[1,0,0]
	v_pk_fma_f32 v[248:249], v[220:221], v[10:11], 0 neg_lo:[1,0,0] neg_hi:[1,0,0]
	ds_read_b128 v[218:221], v21 offset:59408
	s_waitcnt lgkmcnt(10)
	v_pk_fma_f32 v[242:243], v[222:223], v[8:9], v[242:243] neg_lo:[1,0,0] neg_hi:[1,0,0]
	v_pk_fma_f32 v[250:251], v[224:225], v[10:11], 0 neg_lo:[1,0,0] neg_hi:[1,0,0]
	ds_read_b128 v[222:225], v21 offset:59664
	s_waitcnt lgkmcnt(10)
	v_pk_fma_f32 v[244:245], v[226:227], v[8:9], v[244:245] neg_lo:[1,0,0] neg_hi:[1,0,0]
	v_pk_fma_f32 v[252:253], v[228:229], v[10:11], 0 neg_lo:[1,0,0] neg_hi:[1,0,0]
	ds_read_b128 v[226:229], v21 offset:59920
	s_waitcnt lgkmcnt(10)
	v_pk_fma_f32 v[246:247], v[230:231], v[8:9], v[246:247] neg_lo:[1,0,0] neg_hi:[1,0,0]
	v_pk_fma_f32 v[254:255], v[232:233], v[10:11], 0 neg_lo:[1,0,0] neg_hi:[1,0,0]
	ds_read_b128 v[230:233], v21 offset:59168
	s_waitcnt lgkmcnt(10)
	v_pk_fma_f32 v[240:241], v[214:215], v[12:13], v[240:241] neg_lo:[1,0,0] neg_hi:[1,0,0]
	v_pk_fma_f32 v[248:249], v[216:217], v[14:15], v[248:249] neg_lo:[1,0,0] neg_hi:[1,0,0]
	ds_read_b128 v[214:217], v21 offset:59424
	s_waitcnt lgkmcnt(4)
	v_pk_fma_f32 v[242:243], v[218:219], v[12:13], v[242:243] neg_lo:[1,0,0] neg_hi:[1,0,0]
	v_pk_fma_f32 v[250:251], v[220:221], v[14:15], v[250:251] neg_lo:[1,0,0] neg_hi:[1,0,0]
	ds_read_b128 v[218:221], v21 offset:59680
	s_waitcnt lgkmcnt(4)
	v_pk_fma_f32 v[244:245], v[222:223], v[12:13], v[244:245] neg_lo:[1,0,0] neg_hi:[1,0,0]
	v_pk_fma_f32 v[252:253], v[224:225], v[14:15], v[252:253] neg_lo:[1,0,0] neg_hi:[1,0,0]
	ds_read_b128 v[222:225], v21 offset:59936
	s_waitcnt lgkmcnt(4)
	v_pk_fma_f32 v[246:247], v[226:227], v[12:13], v[246:247] neg_lo:[1,0,0] neg_hi:[1,0,0]
	v_pk_fma_f32 v[254:255], v[228:229], v[14:15], v[254:255] neg_lo:[1,0,0] neg_hi:[1,0,0]
	ds_read_b128 v[226:229], v21 offset:59184
	s_waitcnt lgkmcnt(4)
	v_pk_fma_f32 v[240:241], v[230:231], v[4:5], v[240:241] neg_lo:[1,0,0] neg_hi:[1,0,0]
	v_pk_fma_f32 v[248:249], v[232:233], v[44:45], v[248:249] neg_lo:[1,0,0] neg_hi:[1,0,0]
	ds_read_b128 v[230:233], v21 offset:59440
	s_waitcnt lgkmcnt(4)
	v_pk_fma_f32 v[242:243], v[214:215], v[4:5], v[242:243] neg_lo:[1,0,0] neg_hi:[1,0,0]
	v_pk_fma_f32 v[250:251], v[216:217], v[44:45], v[250:251] neg_lo:[1,0,0] neg_hi:[1,0,0]
	ds_read_b128 v[214:217], v21 offset:59696
	s_waitcnt lgkmcnt(4)
	v_pk_fma_f32 v[244:245], v[218:219], v[4:5], v[244:245] neg_lo:[1,0,0] neg_hi:[1,0,0]
	v_pk_fma_f32 v[252:253], v[220:221], v[44:45], v[252:253] neg_lo:[1,0,0] neg_hi:[1,0,0]
	ds_read_b128 v[218:221], v21 offset:59952
	s_waitcnt lgkmcnt(4)
	v_pk_fma_f32 v[246:247], v[222:223], v[4:5], v[246:247] neg_lo:[1,0,0] neg_hi:[1,0,0]
	v_pk_fma_f32 v[254:255], v[224:225], v[44:45], v[254:255] neg_lo:[1,0,0] neg_hi:[1,0,0]
	ds_read_b128 v[222:225], v21 offset:59200
	s_waitcnt lgkmcnt(4)
	v_pk_fma_f32 v[240:241], v[226:227], v[46:47], v[240:241] neg_lo:[1,0,0] neg_hi:[1,0,0]
	v_pk_fma_f32 v[248:249], v[228:229], v[48:49], v[248:249] neg_lo:[1,0,0] neg_hi:[1,0,0]
	ds_read_b128 v[226:229], v21 offset:59456
	s_waitcnt lgkmcnt(4)
	v_pk_fma_f32 v[242:243], v[230:231], v[46:47], v[242:243] neg_lo:[1,0,0] neg_hi:[1,0,0]
	v_pk_fma_f32 v[250:251], v[232:233], v[48:49], v[250:251] neg_lo:[1,0,0] neg_hi:[1,0,0]
	ds_read_b128 v[230:233], v21 offset:59712
	s_waitcnt lgkmcnt(4)
	v_pk_fma_f32 v[244:245], v[214:215], v[46:47], v[244:245] neg_lo:[1,0,0] neg_hi:[1,0,0]
	v_pk_fma_f32 v[252:253], v[216:217], v[48:49], v[252:253] neg_lo:[1,0,0] neg_hi:[1,0,0]
	ds_read_b128 v[214:217], v21 offset:59968
	s_waitcnt lgkmcnt(4)
	v_pk_fma_f32 v[246:247], v[218:219], v[46:47], v[246:247] neg_lo:[1,0,0] neg_hi:[1,0,0]
	v_pk_fma_f32 v[254:255], v[220:221], v[48:49], v[254:255] neg_lo:[1,0,0] neg_hi:[1,0,0]
	ds_read_b128 v[218:221], v21 offset:59216
	s_waitcnt lgkmcnt(4)
	v_pk_fma_f32 v[240:241], v[222:223], v[50:51], v[240:241] neg_lo:[1,0,0] neg_hi:[1,0,0]
	v_pk_fma_f32 v[248:249], v[224:225], v[52:53], v[248:249] neg_lo:[1,0,0] neg_hi:[1,0,0]
	ds_read_b128 v[222:225], v21 offset:59472
	s_waitcnt lgkmcnt(4)
	v_pk_fma_f32 v[242:243], v[226:227], v[50:51], v[242:243] neg_lo:[1,0,0] neg_hi:[1,0,0]
	v_pk_fma_f32 v[250:251], v[228:229], v[52:53], v[250:251] neg_lo:[1,0,0] neg_hi:[1,0,0]
	ds_read_b128 v[226:229], v21 offset:59728
	s_waitcnt lgkmcnt(4)
	v_pk_fma_f32 v[244:245], v[230:231], v[50:51], v[244:245] neg_lo:[1,0,0] neg_hi:[1,0,0]
	v_pk_fma_f32 v[252:253], v[232:233], v[52:53], v[252:253] neg_lo:[1,0,0] neg_hi:[1,0,0]
	ds_read_b128 v[230:233], v21 offset:59984
	s_waitcnt lgkmcnt(4)
	v_pk_fma_f32 v[246:247], v[214:215], v[50:51], v[246:247] neg_lo:[1,0,0] neg_hi:[1,0,0]
	v_pk_fma_f32 v[254:255], v[216:217], v[52:53], v[254:255] neg_lo:[1,0,0] neg_hi:[1,0,0]
	ds_read_b128 v[214:217], v21 offset:59232
	s_waitcnt lgkmcnt(4)
	v_pk_fma_f32 v[240:241], v[218:219], v[54:55], v[240:241] neg_lo:[1,0,0] neg_hi:[1,0,0]
	v_pk_fma_f32 v[248:249], v[220:221], v[56:57], v[248:249] neg_lo:[1,0,0] neg_hi:[1,0,0]
	ds_read_b128 v[218:221], v21 offset:59488
	s_waitcnt lgkmcnt(4)
	v_pk_fma_f32 v[242:243], v[222:223], v[54:55], v[242:243] neg_lo:[1,0,0] neg_hi:[1,0,0]
	v_pk_fma_f32 v[250:251], v[224:225], v[56:57], v[250:251] neg_lo:[1,0,0] neg_hi:[1,0,0]
	ds_read_b128 v[222:225], v21 offset:59744
	s_waitcnt lgkmcnt(4)
	v_pk_fma_f32 v[244:245], v[226:227], v[54:55], v[244:245] neg_lo:[1,0,0] neg_hi:[1,0,0]
	v_pk_fma_f32 v[252:253], v[228:229], v[56:57], v[252:253] neg_lo:[1,0,0] neg_hi:[1,0,0]
	ds_read_b128 v[226:229], v21 offset:60000
	s_waitcnt lgkmcnt(4)
	v_pk_fma_f32 v[246:247], v[230:231], v[54:55], v[246:247] neg_lo:[1,0,0] neg_hi:[1,0,0]
	v_pk_fma_f32 v[254:255], v[232:233], v[56:57], v[254:255] neg_lo:[1,0,0] neg_hi:[1,0,0]
	ds_read_b128 v[230:233], v21 offset:59248
	s_waitcnt lgkmcnt(4)
	v_pk_fma_f32 v[240:241], v[214:215], v[58:59], v[240:241] neg_lo:[1,0,0] neg_hi:[1,0,0]
	v_pk_fma_f32 v[248:249], v[216:217], v[60:61], v[248:249] neg_lo:[1,0,0] neg_hi:[1,0,0]
	ds_read_b128 v[214:217], v21 offset:59504
	s_waitcnt lgkmcnt(4)
	v_pk_fma_f32 v[242:243], v[218:219], v[58:59], v[242:243] neg_lo:[1,0,0] neg_hi:[1,0,0]
	v_pk_fma_f32 v[250:251], v[220:221], v[60:61], v[250:251] neg_lo:[1,0,0] neg_hi:[1,0,0]
	ds_read_b128 v[218:221], v21 offset:59760
	s_waitcnt lgkmcnt(4)
	v_pk_fma_f32 v[244:245], v[222:223], v[58:59], v[244:245] neg_lo:[1,0,0] neg_hi:[1,0,0]
	v_pk_fma_f32 v[252:253], v[224:225], v[60:61], v[252:253] neg_lo:[1,0,0] neg_hi:[1,0,0]
	ds_read_b128 v[222:225], v21 offset:60016
	s_waitcnt lgkmcnt(4)
	v_pk_fma_f32 v[246:247], v[226:227], v[58:59], v[246:247] neg_lo:[1,0,0] neg_hi:[1,0,0]
	v_pk_fma_f32 v[254:255], v[228:229], v[60:61], v[254:255] neg_lo:[1,0,0] neg_hi:[1,0,0]
	ds_read_b128 v[226:229], v21 offset:59264
	s_waitcnt lgkmcnt(4)
	v_pk_fma_f32 v[240:241], v[230:231], v[62:63], v[240:241] neg_lo:[1,0,0] neg_hi:[1,0,0]
	v_pk_fma_f32 v[248:249], v[232:233], v[64:65], v[248:249] neg_lo:[1,0,0] neg_hi:[1,0,0]
	ds_read_b128 v[230:233], v21 offset:59520
	s_waitcnt lgkmcnt(4)
	v_pk_fma_f32 v[242:243], v[214:215], v[62:63], v[242:243] neg_lo:[1,0,0] neg_hi:[1,0,0]
	v_pk_fma_f32 v[250:251], v[216:217], v[64:65], v[250:251] neg_lo:[1,0,0] neg_hi:[1,0,0]
	ds_read_b128 v[214:217], v21 offset:59776
	s_waitcnt lgkmcnt(4)
	v_pk_fma_f32 v[244:245], v[218:219], v[62:63], v[244:245] neg_lo:[1,0,0] neg_hi:[1,0,0]
	v_pk_fma_f32 v[252:253], v[220:221], v[64:65], v[252:253] neg_lo:[1,0,0] neg_hi:[1,0,0]
	ds_read_b128 v[218:221], v21 offset:60032
	s_waitcnt lgkmcnt(4)
	v_pk_fma_f32 v[246:247], v[222:223], v[62:63], v[246:247] neg_lo:[1,0,0] neg_hi:[1,0,0]
	v_pk_fma_f32 v[254:255], v[224:225], v[64:65], v[254:255] neg_lo:[1,0,0] neg_hi:[1,0,0]
	ds_read_b128 v[222:225], v21 offset:59536
	s_waitcnt lgkmcnt(4)
	v_pk_fma_f32 v[240:241], v[226:227], v[66:67], v[240:241] neg_lo:[1,0,0] neg_hi:[1,0,0]
	v_pk_fma_f32 v[248:249], v[228:229], v[68:69], v[248:249] neg_lo:[1,0,0] neg_hi:[1,0,0]
	ds_read_b128 v[226:229], v21 offset:59792
	s_waitcnt lgkmcnt(4)
	v_pk_fma_f32 v[242:243], v[230:231], v[66:67], v[242:243] neg_lo:[1,0,0] neg_hi:[1,0,0]
	v_pk_fma_f32 v[250:251], v[232:233], v[68:69], v[250:251] neg_lo:[1,0,0] neg_hi:[1,0,0]
	ds_read_b128 v[230:233], v21 offset:60048
	s_waitcnt lgkmcnt(4)
	v_pk_fma_f32 v[244:245], v[214:215], v[66:67], v[244:245] neg_lo:[1,0,0] neg_hi:[1,0,0]
	v_pk_fma_f32 v[252:253], v[216:217], v[68:69], v[252:253] neg_lo:[1,0,0] neg_hi:[1,0,0]
	ds_read_b128 v[214:217], v21 offset:60160
	s_waitcnt lgkmcnt(4)
	v_pk_fma_f32 v[246:247], v[218:219], v[66:67], v[246:247] neg_lo:[1,0,0] neg_hi:[1,0,0]
	v_pk_fma_f32 v[254:255], v[220:221], v[68:69], v[254:255] neg_lo:[1,0,0] neg_hi:[1,0,0]
	v_pk_add_f32 v[240:241], v[240:241], v[248:249]
	v_add_f32_e32 v184, v240, v241
	ds_read_b128 v[218:221], v21 offset:60416
	s_waitcnt lgkmcnt(4)
	v_fma_f32 v242, -v184, v222, v242
	v_pk_add_f32 v[242:243], v[242:243], v[250:251]
	v_add_f32_e32 v185, v242, v243
	ds_read_b128 v[222:225], v21 offset:60672
	s_waitcnt lgkmcnt(4)
	v_pk_fma_f32 v[244:245], v[226:227], v[184:185], v[244:245] neg_lo:[1,0,0] neg_hi:[1,0,0]
	v_pk_add_f32 v[244:245], v[244:245], v[252:253]
	v_add_f32_e32 v186, v244, v245
	ds_read_b128 v[226:229], v21 offset:60928
	s_waitcnt lgkmcnt(4)
	v_pk_fma_f32 v[246:247], v[230:231], v[184:185], v[246:247] neg_lo:[1,0,0] neg_hi:[1,0,0]
	v_fma_f32 v254, -v186, v232, v254
	v_pk_add_f32 v[246:247], v[246:247], v[254:255]
	v_add_f32_e32 v187, v246, v247
	ds_read_b128 v[230:233], v21 offset:60176
	v_mul_f32_e32 v240, v200, v204
	v_mul_f32_e32 v242, v201, v205
	v_mul_f32_e32 v244, v202, v206
	v_mul_f32_e32 v246, v203, v207
	v_mul_f32_e32 v238, v240, v0
	v_cndmask_b32_e64 v240, v240, v238, s[26:27]
	v_mov_b32_e32 v241, 0
	v_mul_f32_e32 v6, v242, v1
	v_cndmask_b32_e64 v242, v242, v6, s[26:27]
	v_mov_b32_e32 v243, 0
	v_mul_f32_e32 v7, v244, v2
	v_cndmask_b32_e64 v244, v244, v7, s[26:27]
	v_mov_b32_e32 v245, 0
	v_mul_f32_e32 v238, v246, v3
	v_cndmask_b32_e64 v246, v246, v238, s[26:27]
	v_mov_b32_e32 v247, 0
	ds_read_b32 v200, v88 offset:11440
	ds_read_b32 v201, v88 offset:11700
	ds_read_b32 v202, v88 offset:11960
	ds_read_b32 v203, v88 offset:12220
	ds_read_b128 v[204:207], v117
	ds_read_b128 v[0:3], v118
	s_waitcnt lgkmcnt(10)
	v_pk_fma_f32 v[240:241], v[214:215], v[8:9], v[240:241] neg_lo:[1,0,0] neg_hi:[1,0,0]
	v_pk_fma_f32 v[248:249], v[216:217], v[10:11], 0 neg_lo:[1,0,0] neg_hi:[1,0,0]
	ds_read_b128 v[214:217], v21 offset:60432
	s_waitcnt lgkmcnt(10)
	v_pk_fma_f32 v[242:243], v[218:219], v[8:9], v[242:243] neg_lo:[1,0,0] neg_hi:[1,0,0]
	v_pk_fma_f32 v[250:251], v[220:221], v[10:11], 0 neg_lo:[1,0,0] neg_hi:[1,0,0]
	ds_read_b128 v[218:221], v21 offset:60688
	s_waitcnt lgkmcnt(10)
	v_pk_fma_f32 v[244:245], v[222:223], v[8:9], v[244:245] neg_lo:[1,0,0] neg_hi:[1,0,0]
	v_pk_fma_f32 v[252:253], v[224:225], v[10:11], 0 neg_lo:[1,0,0] neg_hi:[1,0,0]
	ds_read_b128 v[222:225], v21 offset:60944
	s_waitcnt lgkmcnt(10)
	v_pk_fma_f32 v[246:247], v[226:227], v[8:9], v[246:247] neg_lo:[1,0,0] neg_hi:[1,0,0]
	v_pk_fma_f32 v[254:255], v[228:229], v[10:11], 0 neg_lo:[1,0,0] neg_hi:[1,0,0]
	ds_read_b128 v[226:229], v21 offset:60192
	s_waitcnt lgkmcnt(10)
	v_pk_fma_f32 v[240:241], v[230:231], v[12:13], v[240:241] neg_lo:[1,0,0] neg_hi:[1,0,0]
	v_pk_fma_f32 v[248:249], v[232:233], v[14:15], v[248:249] neg_lo:[1,0,0] neg_hi:[1,0,0]
	ds_read_b128 v[230:233], v21 offset:60448
	s_waitcnt lgkmcnt(4)
	v_pk_fma_f32 v[242:243], v[214:215], v[12:13], v[242:243] neg_lo:[1,0,0] neg_hi:[1,0,0]
	v_pk_fma_f32 v[250:251], v[216:217], v[14:15], v[250:251] neg_lo:[1,0,0] neg_hi:[1,0,0]
	ds_read_b128 v[214:217], v21 offset:60704
	s_waitcnt lgkmcnt(4)
	v_pk_fma_f32 v[244:245], v[218:219], v[12:13], v[244:245] neg_lo:[1,0,0] neg_hi:[1,0,0]
	v_pk_fma_f32 v[252:253], v[220:221], v[14:15], v[252:253] neg_lo:[1,0,0] neg_hi:[1,0,0]
	ds_read_b128 v[218:221], v21 offset:60960
	s_waitcnt lgkmcnt(4)
	v_pk_fma_f32 v[246:247], v[222:223], v[12:13], v[246:247] neg_lo:[1,0,0] neg_hi:[1,0,0]
	v_pk_fma_f32 v[254:255], v[224:225], v[14:15], v[254:255] neg_lo:[1,0,0] neg_hi:[1,0,0]
	ds_read_b128 v[222:225], v21 offset:60208
	s_waitcnt lgkmcnt(4)
	v_pk_fma_f32 v[240:241], v[226:227], v[4:5], v[240:241] neg_lo:[1,0,0] neg_hi:[1,0,0]
	v_pk_fma_f32 v[248:249], v[228:229], v[44:45], v[248:249] neg_lo:[1,0,0] neg_hi:[1,0,0]
	ds_read_b128 v[226:229], v21 offset:60464
	s_waitcnt lgkmcnt(4)
	v_pk_fma_f32 v[242:243], v[230:231], v[4:5], v[242:243] neg_lo:[1,0,0] neg_hi:[1,0,0]
	v_pk_fma_f32 v[250:251], v[232:233], v[44:45], v[250:251] neg_lo:[1,0,0] neg_hi:[1,0,0]
	ds_read_b128 v[230:233], v21 offset:60720
	s_waitcnt lgkmcnt(4)
	v_pk_fma_f32 v[244:245], v[214:215], v[4:5], v[244:245] neg_lo:[1,0,0] neg_hi:[1,0,0]
	v_pk_fma_f32 v[252:253], v[216:217], v[44:45], v[252:253] neg_lo:[1,0,0] neg_hi:[1,0,0]
	ds_read_b128 v[214:217], v21 offset:60976
	s_waitcnt lgkmcnt(4)
	v_pk_fma_f32 v[246:247], v[218:219], v[4:5], v[246:247] neg_lo:[1,0,0] neg_hi:[1,0,0]
	v_pk_fma_f32 v[254:255], v[220:221], v[44:45], v[254:255] neg_lo:[1,0,0] neg_hi:[1,0,0]
	ds_read_b128 v[218:221], v21 offset:60224
	s_waitcnt lgkmcnt(4)
	v_pk_fma_f32 v[240:241], v[222:223], v[46:47], v[240:241] neg_lo:[1,0,0] neg_hi:[1,0,0]
	v_pk_fma_f32 v[248:249], v[224:225], v[48:49], v[248:249] neg_lo:[1,0,0] neg_hi:[1,0,0]
	ds_read_b128 v[222:225], v21 offset:60480
	s_waitcnt lgkmcnt(4)
	v_pk_fma_f32 v[242:243], v[226:227], v[46:47], v[242:243] neg_lo:[1,0,0] neg_hi:[1,0,0]
	v_pk_fma_f32 v[250:251], v[228:229], v[48:49], v[250:251] neg_lo:[1,0,0] neg_hi:[1,0,0]
	ds_read_b128 v[226:229], v21 offset:60736
	s_waitcnt lgkmcnt(4)
	v_pk_fma_f32 v[244:245], v[230:231], v[46:47], v[244:245] neg_lo:[1,0,0] neg_hi:[1,0,0]
	v_pk_fma_f32 v[252:253], v[232:233], v[48:49], v[252:253] neg_lo:[1,0,0] neg_hi:[1,0,0]
	ds_read_b128 v[230:233], v21 offset:60992
	s_waitcnt lgkmcnt(4)
	v_pk_fma_f32 v[246:247], v[214:215], v[46:47], v[246:247] neg_lo:[1,0,0] neg_hi:[1,0,0]
	v_pk_fma_f32 v[254:255], v[216:217], v[48:49], v[254:255] neg_lo:[1,0,0] neg_hi:[1,0,0]
	ds_read_b128 v[214:217], v21 offset:60240
	s_waitcnt lgkmcnt(4)
	v_pk_fma_f32 v[240:241], v[218:219], v[50:51], v[240:241] neg_lo:[1,0,0] neg_hi:[1,0,0]
	v_pk_fma_f32 v[248:249], v[220:221], v[52:53], v[248:249] neg_lo:[1,0,0] neg_hi:[1,0,0]
	ds_read_b128 v[218:221], v21 offset:60496
	s_waitcnt lgkmcnt(4)
	v_pk_fma_f32 v[242:243], v[222:223], v[50:51], v[242:243] neg_lo:[1,0,0] neg_hi:[1,0,0]
	v_pk_fma_f32 v[250:251], v[224:225], v[52:53], v[250:251] neg_lo:[1,0,0] neg_hi:[1,0,0]
	ds_read_b128 v[222:225], v21 offset:60752
	s_waitcnt lgkmcnt(4)
	v_pk_fma_f32 v[244:245], v[226:227], v[50:51], v[244:245] neg_lo:[1,0,0] neg_hi:[1,0,0]
	v_pk_fma_f32 v[252:253], v[228:229], v[52:53], v[252:253] neg_lo:[1,0,0] neg_hi:[1,0,0]
	ds_read_b128 v[226:229], v21 offset:61008
	s_waitcnt lgkmcnt(4)
	v_pk_fma_f32 v[246:247], v[230:231], v[50:51], v[246:247] neg_lo:[1,0,0] neg_hi:[1,0,0]
	v_pk_fma_f32 v[254:255], v[232:233], v[52:53], v[254:255] neg_lo:[1,0,0] neg_hi:[1,0,0]
	ds_read_b128 v[230:233], v21 offset:60256
	s_waitcnt lgkmcnt(4)
	v_pk_fma_f32 v[240:241], v[214:215], v[54:55], v[240:241] neg_lo:[1,0,0] neg_hi:[1,0,0]
	v_pk_fma_f32 v[248:249], v[216:217], v[56:57], v[248:249] neg_lo:[1,0,0] neg_hi:[1,0,0]
	ds_read_b128 v[214:217], v21 offset:60512
	s_waitcnt lgkmcnt(4)
	v_pk_fma_f32 v[242:243], v[218:219], v[54:55], v[242:243] neg_lo:[1,0,0] neg_hi:[1,0,0]
	v_pk_fma_f32 v[250:251], v[220:221], v[56:57], v[250:251] neg_lo:[1,0,0] neg_hi:[1,0,0]
	ds_read_b128 v[218:221], v21 offset:60768
	s_waitcnt lgkmcnt(4)
	v_pk_fma_f32 v[244:245], v[222:223], v[54:55], v[244:245] neg_lo:[1,0,0] neg_hi:[1,0,0]
	v_pk_fma_f32 v[252:253], v[224:225], v[56:57], v[252:253] neg_lo:[1,0,0] neg_hi:[1,0,0]
	ds_read_b128 v[222:225], v21 offset:61024
	s_waitcnt lgkmcnt(4)
	v_pk_fma_f32 v[246:247], v[226:227], v[54:55], v[246:247] neg_lo:[1,0,0] neg_hi:[1,0,0]
	v_pk_fma_f32 v[254:255], v[228:229], v[56:57], v[254:255] neg_lo:[1,0,0] neg_hi:[1,0,0]
	ds_read_b128 v[226:229], v21 offset:60272
	s_waitcnt lgkmcnt(4)
	v_pk_fma_f32 v[240:241], v[230:231], v[58:59], v[240:241] neg_lo:[1,0,0] neg_hi:[1,0,0]
	v_pk_fma_f32 v[248:249], v[232:233], v[60:61], v[248:249] neg_lo:[1,0,0] neg_hi:[1,0,0]
	ds_read_b128 v[230:233], v21 offset:60528
	s_waitcnt lgkmcnt(4)
	v_pk_fma_f32 v[242:243], v[214:215], v[58:59], v[242:243] neg_lo:[1,0,0] neg_hi:[1,0,0]
	v_pk_fma_f32 v[250:251], v[216:217], v[60:61], v[250:251] neg_lo:[1,0,0] neg_hi:[1,0,0]
	ds_read_b128 v[214:217], v21 offset:60784
	s_waitcnt lgkmcnt(4)
	v_pk_fma_f32 v[244:245], v[218:219], v[58:59], v[244:245] neg_lo:[1,0,0] neg_hi:[1,0,0]
	v_pk_fma_f32 v[252:253], v[220:221], v[60:61], v[252:253] neg_lo:[1,0,0] neg_hi:[1,0,0]
	ds_read_b128 v[218:221], v21 offset:61040
	s_waitcnt lgkmcnt(4)
	v_pk_fma_f32 v[246:247], v[222:223], v[58:59], v[246:247] neg_lo:[1,0,0] neg_hi:[1,0,0]
	v_pk_fma_f32 v[254:255], v[224:225], v[60:61], v[254:255] neg_lo:[1,0,0] neg_hi:[1,0,0]
	ds_read_b128 v[222:225], v21 offset:60288
	s_waitcnt lgkmcnt(4)
	v_pk_fma_f32 v[240:241], v[226:227], v[62:63], v[240:241] neg_lo:[1,0,0] neg_hi:[1,0,0]
	v_pk_fma_f32 v[248:249], v[228:229], v[64:65], v[248:249] neg_lo:[1,0,0] neg_hi:[1,0,0]
	ds_read_b128 v[226:229], v21 offset:60544
	s_waitcnt lgkmcnt(4)
	v_pk_fma_f32 v[242:243], v[230:231], v[62:63], v[242:243] neg_lo:[1,0,0] neg_hi:[1,0,0]
	v_pk_fma_f32 v[250:251], v[232:233], v[64:65], v[250:251] neg_lo:[1,0,0] neg_hi:[1,0,0]
	ds_read_b128 v[230:233], v21 offset:60800
	s_waitcnt lgkmcnt(4)
	v_pk_fma_f32 v[244:245], v[214:215], v[62:63], v[244:245] neg_lo:[1,0,0] neg_hi:[1,0,0]
	v_pk_fma_f32 v[252:253], v[216:217], v[64:65], v[252:253] neg_lo:[1,0,0] neg_hi:[1,0,0]
	ds_read_b128 v[214:217], v21 offset:61056
	s_waitcnt lgkmcnt(4)
	v_pk_fma_f32 v[246:247], v[218:219], v[62:63], v[246:247] neg_lo:[1,0,0] neg_hi:[1,0,0]
	v_pk_fma_f32 v[254:255], v[220:221], v[64:65], v[254:255] neg_lo:[1,0,0] neg_hi:[1,0,0]
	ds_read_b128 v[218:221], v21 offset:60304
	s_waitcnt lgkmcnt(4)
	v_pk_fma_f32 v[240:241], v[222:223], v[66:67], v[240:241] neg_lo:[1,0,0] neg_hi:[1,0,0]
	v_pk_fma_f32 v[248:249], v[224:225], v[68:69], v[248:249] neg_lo:[1,0,0] neg_hi:[1,0,0]
	ds_read_b128 v[222:225], v21 offset:60560
	s_waitcnt lgkmcnt(4)
	v_pk_fma_f32 v[242:243], v[226:227], v[66:67], v[242:243] neg_lo:[1,0,0] neg_hi:[1,0,0]
	v_pk_fma_f32 v[250:251], v[228:229], v[68:69], v[250:251] neg_lo:[1,0,0] neg_hi:[1,0,0]
	ds_read_b128 v[226:229], v21 offset:60816
	s_waitcnt lgkmcnt(4)
	v_pk_fma_f32 v[244:245], v[230:231], v[66:67], v[244:245] neg_lo:[1,0,0] neg_hi:[1,0,0]
	v_pk_fma_f32 v[252:253], v[232:233], v[68:69], v[252:253] neg_lo:[1,0,0] neg_hi:[1,0,0]
	ds_read_b128 v[230:233], v21 offset:61072
	s_waitcnt lgkmcnt(4)
	v_pk_fma_f32 v[246:247], v[214:215], v[66:67], v[246:247] neg_lo:[1,0,0] neg_hi:[1,0,0]
	v_pk_fma_f32 v[254:255], v[216:217], v[68:69], v[254:255] neg_lo:[1,0,0] neg_hi:[1,0,0]
	ds_read_b128 v[214:217], v21 offset:60576
	s_waitcnt lgkmcnt(4)
	v_pk_fma_f32 v[240:241], v[218:219], v[184:185], v[240:241] neg_lo:[1,0,0] neg_hi:[1,0,0]
	v_pk_fma_f32 v[248:249], v[220:221], v[186:187], v[248:249] neg_lo:[1,0,0] neg_hi:[1,0,0]
	ds_read_b128 v[218:221], v21 offset:60832
	s_waitcnt lgkmcnt(4)
	v_pk_fma_f32 v[242:243], v[222:223], v[184:185], v[242:243] neg_lo:[1,0,0] neg_hi:[1,0,0]
	v_pk_fma_f32 v[250:251], v[224:225], v[186:187], v[250:251] neg_lo:[1,0,0] neg_hi:[1,0,0]
	ds_read_b128 v[222:225], v21 offset:61088
	s_waitcnt lgkmcnt(4)
	v_pk_fma_f32 v[244:245], v[226:227], v[184:185], v[244:245] neg_lo:[1,0,0] neg_hi:[1,0,0]
	v_pk_fma_f32 v[252:253], v[228:229], v[186:187], v[252:253] neg_lo:[1,0,0] neg_hi:[1,0,0]
	ds_read_b128 v[226:229], v21 offset:61184
	s_waitcnt lgkmcnt(4)
	v_pk_fma_f32 v[246:247], v[230:231], v[184:185], v[246:247] neg_lo:[1,0,0] neg_hi:[1,0,0]
	v_pk_fma_f32 v[254:255], v[232:233], v[186:187], v[254:255] neg_lo:[1,0,0] neg_hi:[1,0,0]
	v_pk_add_f32 v[240:241], v[240:241], v[248:249]
	v_add_f32_e32 v188, v240, v241
	ds_read_b128 v[230:233], v21 offset:61440
	s_waitcnt lgkmcnt(4)
	v_fma_f32 v242, -v188, v214, v242
	v_pk_add_f32 v[242:243], v[242:243], v[250:251]
	v_add_f32_e32 v189, v242, v243
	ds_read_b128 v[214:217], v21 offset:61696
	s_waitcnt lgkmcnt(4)
	v_pk_fma_f32 v[244:245], v[218:219], v[188:189], v[244:245] neg_lo:[1,0,0] neg_hi:[1,0,0]
	v_pk_add_f32 v[244:245], v[244:245], v[252:253]
	v_add_f32_e32 v190, v244, v245
	ds_read_b128 v[218:221], v21 offset:61952
	s_waitcnt lgkmcnt(4)
	v_pk_fma_f32 v[246:247], v[222:223], v[188:189], v[246:247] neg_lo:[1,0,0] neg_hi:[1,0,0]
	v_fma_f32 v254, -v190, v224, v254
	v_pk_add_f32 v[246:247], v[246:247], v[254:255]
	v_add_f32_e32 v191, v246, v247
	ds_read_b128 v[222:225], v21 offset:61200
	v_mul_f32_e32 v240, v200, v204
	v_mul_f32_e32 v242, v201, v205
	v_mul_f32_e32 v244, v202, v206
	v_mul_f32_e32 v246, v203, v207
	v_mul_f32_e32 v238, v240, v0
	v_cndmask_b32_e64 v240, v240, v238, s[26:27]
	v_mov_b32_e32 v241, 0
	v_mul_f32_e32 v6, v242, v1
	v_cndmask_b32_e64 v242, v242, v6, s[26:27]
	v_mov_b32_e32 v243, 0
	v_mul_f32_e32 v7, v244, v2
	v_cndmask_b32_e64 v244, v244, v7, s[26:27]
	v_mov_b32_e32 v245, 0
	v_mul_f32_e32 v238, v246, v3
	v_cndmask_b32_e64 v246, v246, v238, s[26:27]
	v_mov_b32_e32 v247, 0
	ds_read_b32 v200, v88 offset:12480
	ds_read_b32 v201, v88 offset:12740
	ds_read_b32 v202, v88 offset:13000
	ds_read_b32 v203, v88 offset:13260
	ds_read_b128 v[204:207], v119
	ds_read_b128 v[0:3], v120
	s_waitcnt lgkmcnt(10)
	v_pk_fma_f32 v[240:241], v[226:227], v[8:9], v[240:241] neg_lo:[1,0,0] neg_hi:[1,0,0]
	v_pk_fma_f32 v[248:249], v[228:229], v[10:11], 0 neg_lo:[1,0,0] neg_hi:[1,0,0]
	ds_read_b128 v[226:229], v21 offset:61456
	s_waitcnt lgkmcnt(10)
	v_pk_fma_f32 v[242:243], v[230:231], v[8:9], v[242:243] neg_lo:[1,0,0] neg_hi:[1,0,0]
	v_pk_fma_f32 v[250:251], v[232:233], v[10:11], 0 neg_lo:[1,0,0] neg_hi:[1,0,0]
	ds_read_b128 v[230:233], v21 offset:61712
	s_waitcnt lgkmcnt(10)
	v_pk_fma_f32 v[244:245], v[214:215], v[8:9], v[244:245] neg_lo:[1,0,0] neg_hi:[1,0,0]
	v_pk_fma_f32 v[252:253], v[216:217], v[10:11], 0 neg_lo:[1,0,0] neg_hi:[1,0,0]
	ds_read_b128 v[214:217], v21 offset:61968
	s_waitcnt lgkmcnt(10)
	v_pk_fma_f32 v[246:247], v[218:219], v[8:9], v[246:247] neg_lo:[1,0,0] neg_hi:[1,0,0]
	v_pk_fma_f32 v[254:255], v[220:221], v[10:11], 0 neg_lo:[1,0,0] neg_hi:[1,0,0]
	ds_read_b128 v[218:221], v21 offset:61216
	s_waitcnt lgkmcnt(10)
	v_pk_fma_f32 v[240:241], v[222:223], v[12:13], v[240:241] neg_lo:[1,0,0] neg_hi:[1,0,0]
	v_pk_fma_f32 v[248:249], v[224:225], v[14:15], v[248:249] neg_lo:[1,0,0] neg_hi:[1,0,0]
	ds_read_b128 v[222:225], v21 offset:61472
	s_waitcnt lgkmcnt(4)
	v_pk_fma_f32 v[242:243], v[226:227], v[12:13], v[242:243] neg_lo:[1,0,0] neg_hi:[1,0,0]
	v_pk_fma_f32 v[250:251], v[228:229], v[14:15], v[250:251] neg_lo:[1,0,0] neg_hi:[1,0,0]
	ds_read_b128 v[226:229], v21 offset:61728
	s_waitcnt lgkmcnt(4)
	v_pk_fma_f32 v[244:245], v[230:231], v[12:13], v[244:245] neg_lo:[1,0,0] neg_hi:[1,0,0]
	v_pk_fma_f32 v[252:253], v[232:233], v[14:15], v[252:253] neg_lo:[1,0,0] neg_hi:[1,0,0]
	ds_read_b128 v[230:233], v21 offset:61984
	s_waitcnt lgkmcnt(4)
	v_pk_fma_f32 v[246:247], v[214:215], v[12:13], v[246:247] neg_lo:[1,0,0] neg_hi:[1,0,0]
	v_pk_fma_f32 v[254:255], v[216:217], v[14:15], v[254:255] neg_lo:[1,0,0] neg_hi:[1,0,0]
	ds_read_b128 v[214:217], v21 offset:61232
	s_waitcnt lgkmcnt(4)
	v_pk_fma_f32 v[240:241], v[218:219], v[4:5], v[240:241] neg_lo:[1,0,0] neg_hi:[1,0,0]
	v_pk_fma_f32 v[248:249], v[220:221], v[44:45], v[248:249] neg_lo:[1,0,0] neg_hi:[1,0,0]
	ds_read_b128 v[218:221], v21 offset:61488
	s_waitcnt lgkmcnt(4)
	v_pk_fma_f32 v[242:243], v[222:223], v[4:5], v[242:243] neg_lo:[1,0,0] neg_hi:[1,0,0]
	v_pk_fma_f32 v[250:251], v[224:225], v[44:45], v[250:251] neg_lo:[1,0,0] neg_hi:[1,0,0]
	ds_read_b128 v[222:225], v21 offset:61744
	s_waitcnt lgkmcnt(4)
	v_pk_fma_f32 v[244:245], v[226:227], v[4:5], v[244:245] neg_lo:[1,0,0] neg_hi:[1,0,0]
	v_pk_fma_f32 v[252:253], v[228:229], v[44:45], v[252:253] neg_lo:[1,0,0] neg_hi:[1,0,0]
	ds_read_b128 v[226:229], v21 offset:62000
	s_waitcnt lgkmcnt(4)
	v_pk_fma_f32 v[246:247], v[230:231], v[4:5], v[246:247] neg_lo:[1,0,0] neg_hi:[1,0,0]
	v_pk_fma_f32 v[254:255], v[232:233], v[44:45], v[254:255] neg_lo:[1,0,0] neg_hi:[1,0,0]
	ds_read_b128 v[230:233], v21 offset:61248
	s_waitcnt lgkmcnt(4)
	v_pk_fma_f32 v[240:241], v[214:215], v[46:47], v[240:241] neg_lo:[1,0,0] neg_hi:[1,0,0]
	v_pk_fma_f32 v[248:249], v[216:217], v[48:49], v[248:249] neg_lo:[1,0,0] neg_hi:[1,0,0]
	ds_read_b128 v[214:217], v21 offset:61504
	s_waitcnt lgkmcnt(4)
	v_pk_fma_f32 v[242:243], v[218:219], v[46:47], v[242:243] neg_lo:[1,0,0] neg_hi:[1,0,0]
	v_pk_fma_f32 v[250:251], v[220:221], v[48:49], v[250:251] neg_lo:[1,0,0] neg_hi:[1,0,0]
	ds_read_b128 v[218:221], v21 offset:61760
	s_waitcnt lgkmcnt(4)
	v_pk_fma_f32 v[244:245], v[222:223], v[46:47], v[244:245] neg_lo:[1,0,0] neg_hi:[1,0,0]
	v_pk_fma_f32 v[252:253], v[224:225], v[48:49], v[252:253] neg_lo:[1,0,0] neg_hi:[1,0,0]
	ds_read_b128 v[222:225], v21 offset:62016
	s_waitcnt lgkmcnt(4)
	v_pk_fma_f32 v[246:247], v[226:227], v[46:47], v[246:247] neg_lo:[1,0,0] neg_hi:[1,0,0]
	v_pk_fma_f32 v[254:255], v[228:229], v[48:49], v[254:255] neg_lo:[1,0,0] neg_hi:[1,0,0]
	ds_read_b128 v[226:229], v21 offset:61264
	s_waitcnt lgkmcnt(4)
	v_pk_fma_f32 v[240:241], v[230:231], v[50:51], v[240:241] neg_lo:[1,0,0] neg_hi:[1,0,0]
	v_pk_fma_f32 v[248:249], v[232:233], v[52:53], v[248:249] neg_lo:[1,0,0] neg_hi:[1,0,0]
	ds_read_b128 v[230:233], v21 offset:61520
	s_waitcnt lgkmcnt(4)
	v_pk_fma_f32 v[242:243], v[214:215], v[50:51], v[242:243] neg_lo:[1,0,0] neg_hi:[1,0,0]
	v_pk_fma_f32 v[250:251], v[216:217], v[52:53], v[250:251] neg_lo:[1,0,0] neg_hi:[1,0,0]
	ds_read_b128 v[214:217], v21 offset:61776
	s_waitcnt lgkmcnt(4)
	v_pk_fma_f32 v[244:245], v[218:219], v[50:51], v[244:245] neg_lo:[1,0,0] neg_hi:[1,0,0]
	v_pk_fma_f32 v[252:253], v[220:221], v[52:53], v[252:253] neg_lo:[1,0,0] neg_hi:[1,0,0]
	ds_read_b128 v[218:221], v21 offset:62032
	s_waitcnt lgkmcnt(4)
	v_pk_fma_f32 v[246:247], v[222:223], v[50:51], v[246:247] neg_lo:[1,0,0] neg_hi:[1,0,0]
	v_pk_fma_f32 v[254:255], v[224:225], v[52:53], v[254:255] neg_lo:[1,0,0] neg_hi:[1,0,0]
	ds_read_b128 v[222:225], v21 offset:61280
	s_waitcnt lgkmcnt(4)
	v_pk_fma_f32 v[240:241], v[226:227], v[54:55], v[240:241] neg_lo:[1,0,0] neg_hi:[1,0,0]
	v_pk_fma_f32 v[248:249], v[228:229], v[56:57], v[248:249] neg_lo:[1,0,0] neg_hi:[1,0,0]
	ds_read_b128 v[226:229], v21 offset:61536
	s_waitcnt lgkmcnt(4)
	v_pk_fma_f32 v[242:243], v[230:231], v[54:55], v[242:243] neg_lo:[1,0,0] neg_hi:[1,0,0]
	v_pk_fma_f32 v[250:251], v[232:233], v[56:57], v[250:251] neg_lo:[1,0,0] neg_hi:[1,0,0]
	ds_read_b128 v[230:233], v21 offset:61792
	s_waitcnt lgkmcnt(4)
	v_pk_fma_f32 v[244:245], v[214:215], v[54:55], v[244:245] neg_lo:[1,0,0] neg_hi:[1,0,0]
	v_pk_fma_f32 v[252:253], v[216:217], v[56:57], v[252:253] neg_lo:[1,0,0] neg_hi:[1,0,0]
	ds_read_b128 v[214:217], v21 offset:62048
	s_waitcnt lgkmcnt(4)
	v_pk_fma_f32 v[246:247], v[218:219], v[54:55], v[246:247] neg_lo:[1,0,0] neg_hi:[1,0,0]
	v_pk_fma_f32 v[254:255], v[220:221], v[56:57], v[254:255] neg_lo:[1,0,0] neg_hi:[1,0,0]
	ds_read_b128 v[218:221], v21 offset:61296
	s_waitcnt lgkmcnt(4)
	v_pk_fma_f32 v[240:241], v[222:223], v[58:59], v[240:241] neg_lo:[1,0,0] neg_hi:[1,0,0]
	v_pk_fma_f32 v[248:249], v[224:225], v[60:61], v[248:249] neg_lo:[1,0,0] neg_hi:[1,0,0]
	ds_read_b128 v[222:225], v21 offset:61552
	s_waitcnt lgkmcnt(4)
	v_pk_fma_f32 v[242:243], v[226:227], v[58:59], v[242:243] neg_lo:[1,0,0] neg_hi:[1,0,0]
	v_pk_fma_f32 v[250:251], v[228:229], v[60:61], v[250:251] neg_lo:[1,0,0] neg_hi:[1,0,0]
	ds_read_b128 v[226:229], v21 offset:61808
	s_waitcnt lgkmcnt(4)
	v_pk_fma_f32 v[244:245], v[230:231], v[58:59], v[244:245] neg_lo:[1,0,0] neg_hi:[1,0,0]
	v_pk_fma_f32 v[252:253], v[232:233], v[60:61], v[252:253] neg_lo:[1,0,0] neg_hi:[1,0,0]
	ds_read_b128 v[230:233], v21 offset:62064
	s_waitcnt lgkmcnt(4)
	v_pk_fma_f32 v[246:247], v[214:215], v[58:59], v[246:247] neg_lo:[1,0,0] neg_hi:[1,0,0]
	v_pk_fma_f32 v[254:255], v[216:217], v[60:61], v[254:255] neg_lo:[1,0,0] neg_hi:[1,0,0]
	ds_read_b128 v[214:217], v21 offset:61312
	s_waitcnt lgkmcnt(4)
	v_pk_fma_f32 v[240:241], v[218:219], v[62:63], v[240:241] neg_lo:[1,0,0] neg_hi:[1,0,0]
	v_pk_fma_f32 v[248:249], v[220:221], v[64:65], v[248:249] neg_lo:[1,0,0] neg_hi:[1,0,0]
	ds_read_b128 v[218:221], v21 offset:61568
	s_waitcnt lgkmcnt(4)
	v_pk_fma_f32 v[242:243], v[222:223], v[62:63], v[242:243] neg_lo:[1,0,0] neg_hi:[1,0,0]
	v_pk_fma_f32 v[250:251], v[224:225], v[64:65], v[250:251] neg_lo:[1,0,0] neg_hi:[1,0,0]
	ds_read_b128 v[222:225], v21 offset:61824
	s_waitcnt lgkmcnt(4)
	v_pk_fma_f32 v[244:245], v[226:227], v[62:63], v[244:245] neg_lo:[1,0,0] neg_hi:[1,0,0]
	v_pk_fma_f32 v[252:253], v[228:229], v[64:65], v[252:253] neg_lo:[1,0,0] neg_hi:[1,0,0]
	ds_read_b128 v[226:229], v21 offset:62080
	s_waitcnt lgkmcnt(4)
	v_pk_fma_f32 v[246:247], v[230:231], v[62:63], v[246:247] neg_lo:[1,0,0] neg_hi:[1,0,0]
	v_pk_fma_f32 v[254:255], v[232:233], v[64:65], v[254:255] neg_lo:[1,0,0] neg_hi:[1,0,0]
	ds_read_b128 v[230:233], v21 offset:61328
	s_waitcnt lgkmcnt(4)
	v_pk_fma_f32 v[240:241], v[214:215], v[66:67], v[240:241] neg_lo:[1,0,0] neg_hi:[1,0,0]
	v_pk_fma_f32 v[248:249], v[216:217], v[68:69], v[248:249] neg_lo:[1,0,0] neg_hi:[1,0,0]
	ds_read_b128 v[214:217], v21 offset:61584
	s_waitcnt lgkmcnt(4)
	v_pk_fma_f32 v[242:243], v[218:219], v[66:67], v[242:243] neg_lo:[1,0,0] neg_hi:[1,0,0]
	v_pk_fma_f32 v[250:251], v[220:221], v[68:69], v[250:251] neg_lo:[1,0,0] neg_hi:[1,0,0]
	ds_read_b128 v[218:221], v21 offset:61840
	s_waitcnt lgkmcnt(4)
	v_pk_fma_f32 v[244:245], v[222:223], v[66:67], v[244:245] neg_lo:[1,0,0] neg_hi:[1,0,0]
	v_pk_fma_f32 v[252:253], v[224:225], v[68:69], v[252:253] neg_lo:[1,0,0] neg_hi:[1,0,0]
	ds_read_b128 v[222:225], v21 offset:62096
	s_waitcnt lgkmcnt(4)
	v_pk_fma_f32 v[246:247], v[226:227], v[66:67], v[246:247] neg_lo:[1,0,0] neg_hi:[1,0,0]
	v_pk_fma_f32 v[254:255], v[228:229], v[68:69], v[254:255] neg_lo:[1,0,0] neg_hi:[1,0,0]
	ds_read_b128 v[226:229], v21 offset:61344
	s_waitcnt lgkmcnt(4)
	v_pk_fma_f32 v[240:241], v[230:231], v[184:185], v[240:241] neg_lo:[1,0,0] neg_hi:[1,0,0]
	v_pk_fma_f32 v[248:249], v[232:233], v[186:187], v[248:249] neg_lo:[1,0,0] neg_hi:[1,0,0]
	ds_read_b128 v[230:233], v21 offset:61600
	s_waitcnt lgkmcnt(4)
	v_pk_fma_f32 v[242:243], v[214:215], v[184:185], v[242:243] neg_lo:[1,0,0] neg_hi:[1,0,0]
	v_pk_fma_f32 v[250:251], v[216:217], v[186:187], v[250:251] neg_lo:[1,0,0] neg_hi:[1,0,0]
	ds_read_b128 v[214:217], v21 offset:61856
	s_waitcnt lgkmcnt(4)
	v_pk_fma_f32 v[244:245], v[218:219], v[184:185], v[244:245] neg_lo:[1,0,0] neg_hi:[1,0,0]
	v_pk_fma_f32 v[252:253], v[220:221], v[186:187], v[252:253] neg_lo:[1,0,0] neg_hi:[1,0,0]
	ds_read_b128 v[218:221], v21 offset:62112
	s_waitcnt lgkmcnt(4)
	v_pk_fma_f32 v[246:247], v[222:223], v[184:185], v[246:247] neg_lo:[1,0,0] neg_hi:[1,0,0]
	v_pk_fma_f32 v[254:255], v[224:225], v[186:187], v[254:255] neg_lo:[1,0,0] neg_hi:[1,0,0]
	ds_read_b128 v[222:225], v21 offset:61616
	s_waitcnt lgkmcnt(4)
	v_pk_fma_f32 v[240:241], v[226:227], v[188:189], v[240:241] neg_lo:[1,0,0] neg_hi:[1,0,0]
	v_pk_fma_f32 v[248:249], v[228:229], v[190:191], v[248:249] neg_lo:[1,0,0] neg_hi:[1,0,0]
	ds_read_b128 v[226:229], v21 offset:61872
	s_waitcnt lgkmcnt(4)
	v_pk_fma_f32 v[242:243], v[230:231], v[188:189], v[242:243] neg_lo:[1,0,0] neg_hi:[1,0,0]
	v_pk_fma_f32 v[250:251], v[232:233], v[190:191], v[250:251] neg_lo:[1,0,0] neg_hi:[1,0,0]
	ds_read_b128 v[230:233], v21 offset:62128
	s_waitcnt lgkmcnt(4)
	v_pk_fma_f32 v[244:245], v[214:215], v[188:189], v[244:245] neg_lo:[1,0,0] neg_hi:[1,0,0]
	v_pk_fma_f32 v[252:253], v[216:217], v[190:191], v[252:253] neg_lo:[1,0,0] neg_hi:[1,0,0]
	ds_read_b128 v[214:217], v21 offset:62208
	s_waitcnt lgkmcnt(4)
	v_pk_fma_f32 v[246:247], v[218:219], v[188:189], v[246:247] neg_lo:[1,0,0] neg_hi:[1,0,0]
	v_pk_fma_f32 v[254:255], v[220:221], v[190:191], v[254:255] neg_lo:[1,0,0] neg_hi:[1,0,0]
	v_pk_add_f32 v[240:241], v[240:241], v[248:249]
	v_add_f32_e32 v192, v240, v241
	ds_read_b128 v[218:221], v21 offset:62464
	s_waitcnt lgkmcnt(4)
	v_fma_f32 v242, -v192, v222, v242
	v_pk_add_f32 v[242:243], v[242:243], v[250:251]
	v_add_f32_e32 v193, v242, v243
	ds_read_b128 v[222:225], v21 offset:62720
	s_waitcnt lgkmcnt(4)
	v_pk_fma_f32 v[244:245], v[226:227], v[192:193], v[244:245] neg_lo:[1,0,0] neg_hi:[1,0,0]
	v_pk_add_f32 v[244:245], v[244:245], v[252:253]
	v_add_f32_e32 v194, v244, v245
	ds_read_b128 v[226:229], v21 offset:62976
	s_waitcnt lgkmcnt(4)
	v_pk_fma_f32 v[246:247], v[230:231], v[192:193], v[246:247] neg_lo:[1,0,0] neg_hi:[1,0,0]
	v_fma_f32 v254, -v194, v232, v254
	v_pk_add_f32 v[246:247], v[246:247], v[254:255]
	v_add_f32_e32 v195, v246, v247
	ds_read_b128 v[230:233], v21 offset:62224
	v_mul_f32_e32 v240, v200, v204
	v_mul_f32_e32 v242, v201, v205
	v_mul_f32_e32 v244, v202, v206
	v_mul_f32_e32 v246, v203, v207
	v_mul_f32_e32 v238, v240, v0
	v_cndmask_b32_e64 v240, v240, v238, s[26:27]
	v_mov_b32_e32 v241, 0
	v_mul_f32_e32 v6, v242, v1
	v_cndmask_b32_e64 v242, v242, v6, s[26:27]
	v_mov_b32_e32 v243, 0
	v_mul_f32_e32 v7, v244, v2
	v_cndmask_b32_e64 v244, v244, v7, s[26:27]
	v_mov_b32_e32 v245, 0
	v_mul_f32_e32 v238, v246, v3
	v_cndmask_b32_e64 v246, v246, v238, s[26:27]
	v_mov_b32_e32 v247, 0
	s_waitcnt lgkmcnt(4)
	v_pk_fma_f32 v[240:241], v[214:215], v[8:9], v[240:241] neg_lo:[1,0,0] neg_hi:[1,0,0]
	v_pk_fma_f32 v[248:249], v[216:217], v[10:11], 0 neg_lo:[1,0,0] neg_hi:[1,0,0]
	ds_read_b128 v[214:217], v21 offset:62480
	s_waitcnt lgkmcnt(4)
	v_pk_fma_f32 v[242:243], v[218:219], v[8:9], v[242:243] neg_lo:[1,0,0] neg_hi:[1,0,0]
	v_pk_fma_f32 v[250:251], v[220:221], v[10:11], 0 neg_lo:[1,0,0] neg_hi:[1,0,0]
	ds_read_b128 v[218:221], v21 offset:62736
	s_waitcnt lgkmcnt(4)
	v_pk_fma_f32 v[244:245], v[222:223], v[8:9], v[244:245] neg_lo:[1,0,0] neg_hi:[1,0,0]
	v_pk_fma_f32 v[252:253], v[224:225], v[10:11], 0 neg_lo:[1,0,0] neg_hi:[1,0,0]
	ds_read_b128 v[222:225], v21 offset:62992
	s_waitcnt lgkmcnt(4)
	v_pk_fma_f32 v[246:247], v[226:227], v[8:9], v[246:247] neg_lo:[1,0,0] neg_hi:[1,0,0]
	v_pk_fma_f32 v[254:255], v[228:229], v[10:11], 0 neg_lo:[1,0,0] neg_hi:[1,0,0]
	ds_read_b128 v[226:229], v21 offset:62240
	s_waitcnt lgkmcnt(4)
	v_pk_fma_f32 v[240:241], v[230:231], v[12:13], v[240:241] neg_lo:[1,0,0] neg_hi:[1,0,0]
	v_pk_fma_f32 v[248:249], v[232:233], v[14:15], v[248:249] neg_lo:[1,0,0] neg_hi:[1,0,0]
	ds_read_b128 v[230:233], v21 offset:62496
	s_waitcnt lgkmcnt(4)
	v_pk_fma_f32 v[242:243], v[214:215], v[12:13], v[242:243] neg_lo:[1,0,0] neg_hi:[1,0,0]
	v_pk_fma_f32 v[250:251], v[216:217], v[14:15], v[250:251] neg_lo:[1,0,0] neg_hi:[1,0,0]
	ds_read_b128 v[214:217], v21 offset:62752
	s_waitcnt lgkmcnt(4)
	v_pk_fma_f32 v[244:245], v[218:219], v[12:13], v[244:245] neg_lo:[1,0,0] neg_hi:[1,0,0]
	v_pk_fma_f32 v[252:253], v[220:221], v[14:15], v[252:253] neg_lo:[1,0,0] neg_hi:[1,0,0]
	ds_read_b128 v[218:221], v21 offset:63008
	s_waitcnt lgkmcnt(4)
	v_pk_fma_f32 v[246:247], v[222:223], v[12:13], v[246:247] neg_lo:[1,0,0] neg_hi:[1,0,0]
	v_pk_fma_f32 v[254:255], v[224:225], v[14:15], v[254:255] neg_lo:[1,0,0] neg_hi:[1,0,0]
	ds_read_b128 v[222:225], v21 offset:62256
	s_waitcnt lgkmcnt(4)
	v_pk_fma_f32 v[240:241], v[226:227], v[4:5], v[240:241] neg_lo:[1,0,0] neg_hi:[1,0,0]
	v_pk_fma_f32 v[248:249], v[228:229], v[44:45], v[248:249] neg_lo:[1,0,0] neg_hi:[1,0,0]
	ds_read_b128 v[226:229], v21 offset:62512
	s_waitcnt lgkmcnt(4)
	v_pk_fma_f32 v[242:243], v[230:231], v[4:5], v[242:243] neg_lo:[1,0,0] neg_hi:[1,0,0]
	v_pk_fma_f32 v[250:251], v[232:233], v[44:45], v[250:251] neg_lo:[1,0,0] neg_hi:[1,0,0]
	ds_read_b128 v[230:233], v21 offset:62768
	s_waitcnt lgkmcnt(4)
	v_pk_fma_f32 v[244:245], v[214:215], v[4:5], v[244:245] neg_lo:[1,0,0] neg_hi:[1,0,0]
	v_pk_fma_f32 v[252:253], v[216:217], v[44:45], v[252:253] neg_lo:[1,0,0] neg_hi:[1,0,0]
	ds_read_b128 v[214:217], v21 offset:63024
	s_waitcnt lgkmcnt(4)
	v_pk_fma_f32 v[246:247], v[218:219], v[4:5], v[246:247] neg_lo:[1,0,0] neg_hi:[1,0,0]
	v_pk_fma_f32 v[254:255], v[220:221], v[44:45], v[254:255] neg_lo:[1,0,0] neg_hi:[1,0,0]
	ds_read_b128 v[218:221], v21 offset:62272
	s_waitcnt lgkmcnt(4)
	v_pk_fma_f32 v[240:241], v[222:223], v[46:47], v[240:241] neg_lo:[1,0,0] neg_hi:[1,0,0]
	v_pk_fma_f32 v[248:249], v[224:225], v[48:49], v[248:249] neg_lo:[1,0,0] neg_hi:[1,0,0]
	ds_read_b128 v[222:225], v21 offset:62528
	s_waitcnt lgkmcnt(4)
	v_pk_fma_f32 v[242:243], v[226:227], v[46:47], v[242:243] neg_lo:[1,0,0] neg_hi:[1,0,0]
	v_pk_fma_f32 v[250:251], v[228:229], v[48:49], v[250:251] neg_lo:[1,0,0] neg_hi:[1,0,0]
	ds_read_b128 v[226:229], v21 offset:62784
	s_waitcnt lgkmcnt(4)
	v_pk_fma_f32 v[244:245], v[230:231], v[46:47], v[244:245] neg_lo:[1,0,0] neg_hi:[1,0,0]
	v_pk_fma_f32 v[252:253], v[232:233], v[48:49], v[252:253] neg_lo:[1,0,0] neg_hi:[1,0,0]
	ds_read_b128 v[230:233], v21 offset:63040
	s_waitcnt lgkmcnt(4)
	v_pk_fma_f32 v[246:247], v[214:215], v[46:47], v[246:247] neg_lo:[1,0,0] neg_hi:[1,0,0]
	v_pk_fma_f32 v[254:255], v[216:217], v[48:49], v[254:255] neg_lo:[1,0,0] neg_hi:[1,0,0]
	ds_read_b128 v[214:217], v21 offset:62288
	s_waitcnt lgkmcnt(4)
	v_pk_fma_f32 v[240:241], v[218:219], v[50:51], v[240:241] neg_lo:[1,0,0] neg_hi:[1,0,0]
	v_pk_fma_f32 v[248:249], v[220:221], v[52:53], v[248:249] neg_lo:[1,0,0] neg_hi:[1,0,0]
	ds_read_b128 v[218:221], v21 offset:62544
	s_waitcnt lgkmcnt(4)
	v_pk_fma_f32 v[242:243], v[222:223], v[50:51], v[242:243] neg_lo:[1,0,0] neg_hi:[1,0,0]
	v_pk_fma_f32 v[250:251], v[224:225], v[52:53], v[250:251] neg_lo:[1,0,0] neg_hi:[1,0,0]
	ds_read_b128 v[222:225], v21 offset:62800
	s_waitcnt lgkmcnt(4)
	v_pk_fma_f32 v[244:245], v[226:227], v[50:51], v[244:245] neg_lo:[1,0,0] neg_hi:[1,0,0]
	v_pk_fma_f32 v[252:253], v[228:229], v[52:53], v[252:253] neg_lo:[1,0,0] neg_hi:[1,0,0]
	ds_read_b128 v[226:229], v21 offset:63056
	s_waitcnt lgkmcnt(4)
	v_pk_fma_f32 v[246:247], v[230:231], v[50:51], v[246:247] neg_lo:[1,0,0] neg_hi:[1,0,0]
	v_pk_fma_f32 v[254:255], v[232:233], v[52:53], v[254:255] neg_lo:[1,0,0] neg_hi:[1,0,0]
	ds_read_b128 v[230:233], v21 offset:62304
	s_waitcnt lgkmcnt(4)
	v_pk_fma_f32 v[240:241], v[214:215], v[54:55], v[240:241] neg_lo:[1,0,0] neg_hi:[1,0,0]
	v_pk_fma_f32 v[248:249], v[216:217], v[56:57], v[248:249] neg_lo:[1,0,0] neg_hi:[1,0,0]
	ds_read_b128 v[214:217], v21 offset:62560
	s_waitcnt lgkmcnt(4)
	v_pk_fma_f32 v[242:243], v[218:219], v[54:55], v[242:243] neg_lo:[1,0,0] neg_hi:[1,0,0]
	v_pk_fma_f32 v[250:251], v[220:221], v[56:57], v[250:251] neg_lo:[1,0,0] neg_hi:[1,0,0]
	ds_read_b128 v[218:221], v21 offset:62816
	s_waitcnt lgkmcnt(4)
	v_pk_fma_f32 v[244:245], v[222:223], v[54:55], v[244:245] neg_lo:[1,0,0] neg_hi:[1,0,0]
	v_pk_fma_f32 v[252:253], v[224:225], v[56:57], v[252:253] neg_lo:[1,0,0] neg_hi:[1,0,0]
	ds_read_b128 v[222:225], v21 offset:63072
	s_waitcnt lgkmcnt(4)
	v_pk_fma_f32 v[246:247], v[226:227], v[54:55], v[246:247] neg_lo:[1,0,0] neg_hi:[1,0,0]
	v_pk_fma_f32 v[254:255], v[228:229], v[56:57], v[254:255] neg_lo:[1,0,0] neg_hi:[1,0,0]
	ds_read_b128 v[226:229], v21 offset:62320
	s_waitcnt lgkmcnt(4)
	v_pk_fma_f32 v[240:241], v[230:231], v[58:59], v[240:241] neg_lo:[1,0,0] neg_hi:[1,0,0]
	v_pk_fma_f32 v[248:249], v[232:233], v[60:61], v[248:249] neg_lo:[1,0,0] neg_hi:[1,0,0]
	ds_read_b128 v[230:233], v21 offset:62576
	s_waitcnt lgkmcnt(4)
	v_pk_fma_f32 v[242:243], v[214:215], v[58:59], v[242:243] neg_lo:[1,0,0] neg_hi:[1,0,0]
	v_pk_fma_f32 v[250:251], v[216:217], v[60:61], v[250:251] neg_lo:[1,0,0] neg_hi:[1,0,0]
	ds_read_b128 v[214:217], v21 offset:62832
	s_waitcnt lgkmcnt(4)
	v_pk_fma_f32 v[244:245], v[218:219], v[58:59], v[244:245] neg_lo:[1,0,0] neg_hi:[1,0,0]
	v_pk_fma_f32 v[252:253], v[220:221], v[60:61], v[252:253] neg_lo:[1,0,0] neg_hi:[1,0,0]
	ds_read_b128 v[218:221], v21 offset:63088
	s_waitcnt lgkmcnt(4)
	v_pk_fma_f32 v[246:247], v[222:223], v[58:59], v[246:247] neg_lo:[1,0,0] neg_hi:[1,0,0]
	v_pk_fma_f32 v[254:255], v[224:225], v[60:61], v[254:255] neg_lo:[1,0,0] neg_hi:[1,0,0]
	ds_read_b128 v[222:225], v21 offset:62336
	s_waitcnt lgkmcnt(4)
	v_pk_fma_f32 v[240:241], v[226:227], v[62:63], v[240:241] neg_lo:[1,0,0] neg_hi:[1,0,0]
	v_pk_fma_f32 v[248:249], v[228:229], v[64:65], v[248:249] neg_lo:[1,0,0] neg_hi:[1,0,0]
	ds_read_b128 v[226:229], v21 offset:62592
	s_waitcnt lgkmcnt(4)
	v_pk_fma_f32 v[242:243], v[230:231], v[62:63], v[242:243] neg_lo:[1,0,0] neg_hi:[1,0,0]
	v_pk_fma_f32 v[250:251], v[232:233], v[64:65], v[250:251] neg_lo:[1,0,0] neg_hi:[1,0,0]
	ds_read_b128 v[230:233], v21 offset:62848
	s_waitcnt lgkmcnt(4)
	v_pk_fma_f32 v[244:245], v[214:215], v[62:63], v[244:245] neg_lo:[1,0,0] neg_hi:[1,0,0]
	v_pk_fma_f32 v[252:253], v[216:217], v[64:65], v[252:253] neg_lo:[1,0,0] neg_hi:[1,0,0]
	ds_read_b128 v[214:217], v21 offset:63104
	s_waitcnt lgkmcnt(4)
	v_pk_fma_f32 v[246:247], v[218:219], v[62:63], v[246:247] neg_lo:[1,0,0] neg_hi:[1,0,0]
	v_pk_fma_f32 v[254:255], v[220:221], v[64:65], v[254:255] neg_lo:[1,0,0] neg_hi:[1,0,0]
	ds_read_b128 v[218:221], v21 offset:62352
	s_waitcnt lgkmcnt(4)
	v_pk_fma_f32 v[240:241], v[222:223], v[66:67], v[240:241] neg_lo:[1,0,0] neg_hi:[1,0,0]
	v_pk_fma_f32 v[248:249], v[224:225], v[68:69], v[248:249] neg_lo:[1,0,0] neg_hi:[1,0,0]
	ds_read_b128 v[222:225], v21 offset:62608
	s_waitcnt lgkmcnt(4)
	v_pk_fma_f32 v[242:243], v[226:227], v[66:67], v[242:243] neg_lo:[1,0,0] neg_hi:[1,0,0]
	v_pk_fma_f32 v[250:251], v[228:229], v[68:69], v[250:251] neg_lo:[1,0,0] neg_hi:[1,0,0]
	ds_read_b128 v[226:229], v21 offset:62864
	s_waitcnt lgkmcnt(4)
	v_pk_fma_f32 v[244:245], v[230:231], v[66:67], v[244:245] neg_lo:[1,0,0] neg_hi:[1,0,0]
	v_pk_fma_f32 v[252:253], v[232:233], v[68:69], v[252:253] neg_lo:[1,0,0] neg_hi:[1,0,0]
	ds_read_b128 v[230:233], v21 offset:63120
	s_waitcnt lgkmcnt(4)
	v_pk_fma_f32 v[246:247], v[214:215], v[66:67], v[246:247] neg_lo:[1,0,0] neg_hi:[1,0,0]
	v_pk_fma_f32 v[254:255], v[216:217], v[68:69], v[254:255] neg_lo:[1,0,0] neg_hi:[1,0,0]
	ds_read_b128 v[214:217], v21 offset:62368
	s_waitcnt lgkmcnt(4)
	v_pk_fma_f32 v[240:241], v[218:219], v[184:185], v[240:241] neg_lo:[1,0,0] neg_hi:[1,0,0]
	v_pk_fma_f32 v[248:249], v[220:221], v[186:187], v[248:249] neg_lo:[1,0,0] neg_hi:[1,0,0]
	ds_read_b128 v[218:221], v21 offset:62624
	s_waitcnt lgkmcnt(4)
	v_pk_fma_f32 v[242:243], v[222:223], v[184:185], v[242:243] neg_lo:[1,0,0] neg_hi:[1,0,0]
	v_pk_fma_f32 v[250:251], v[224:225], v[186:187], v[250:251] neg_lo:[1,0,0] neg_hi:[1,0,0]
	ds_read_b128 v[222:225], v21 offset:62880
	s_waitcnt lgkmcnt(4)
	v_pk_fma_f32 v[244:245], v[226:227], v[184:185], v[244:245] neg_lo:[1,0,0] neg_hi:[1,0,0]
	v_pk_fma_f32 v[252:253], v[228:229], v[186:187], v[252:253] neg_lo:[1,0,0] neg_hi:[1,0,0]
	ds_read_b128 v[226:229], v21 offset:63136
	s_waitcnt lgkmcnt(4)
	v_pk_fma_f32 v[246:247], v[230:231], v[184:185], v[246:247] neg_lo:[1,0,0] neg_hi:[1,0,0]
	v_pk_fma_f32 v[254:255], v[232:233], v[186:187], v[254:255] neg_lo:[1,0,0] neg_hi:[1,0,0]
	ds_read_b128 v[230:233], v21 offset:62384
	s_waitcnt lgkmcnt(4)
	v_pk_fma_f32 v[240:241], v[214:215], v[188:189], v[240:241] neg_lo:[1,0,0] neg_hi:[1,0,0]
	v_pk_fma_f32 v[248:249], v[216:217], v[190:191], v[248:249] neg_lo:[1,0,0] neg_hi:[1,0,0]
	ds_read_b128 v[214:217], v21 offset:62640
	s_waitcnt lgkmcnt(4)
	v_pk_fma_f32 v[242:243], v[218:219], v[188:189], v[242:243] neg_lo:[1,0,0] neg_hi:[1,0,0]
	v_pk_fma_f32 v[250:251], v[220:221], v[190:191], v[250:251] neg_lo:[1,0,0] neg_hi:[1,0,0]
	ds_read_b128 v[218:221], v21 offset:62896
	s_waitcnt lgkmcnt(4)
	v_pk_fma_f32 v[244:245], v[222:223], v[188:189], v[244:245] neg_lo:[1,0,0] neg_hi:[1,0,0]
	v_pk_fma_f32 v[252:253], v[224:225], v[190:191], v[252:253] neg_lo:[1,0,0] neg_hi:[1,0,0]
	ds_read_b128 v[222:225], v21 offset:63152
	s_waitcnt lgkmcnt(4)
	v_pk_fma_f32 v[246:247], v[226:227], v[188:189], v[246:247] neg_lo:[1,0,0] neg_hi:[1,0,0]
	v_pk_fma_f32 v[254:255], v[228:229], v[190:191], v[254:255] neg_lo:[1,0,0] neg_hi:[1,0,0]
	ds_read_b128 v[226:229], v21 offset:62656
	s_waitcnt lgkmcnt(4)
	v_pk_fma_f32 v[240:241], v[230:231], v[192:193], v[240:241] neg_lo:[1,0,0] neg_hi:[1,0,0]
	v_pk_fma_f32 v[248:249], v[232:233], v[194:195], v[248:249] neg_lo:[1,0,0] neg_hi:[1,0,0]
	ds_read_b128 v[230:233], v21 offset:62912
	s_waitcnt lgkmcnt(4)
	v_pk_fma_f32 v[242:243], v[214:215], v[192:193], v[242:243] neg_lo:[1,0,0] neg_hi:[1,0,0]
	v_pk_fma_f32 v[250:251], v[216:217], v[194:195], v[250:251] neg_lo:[1,0,0] neg_hi:[1,0,0]
	ds_read_b128 v[214:217], v21 offset:63168
	s_waitcnt lgkmcnt(4)
	v_pk_fma_f32 v[244:245], v[218:219], v[192:193], v[244:245] neg_lo:[1,0,0] neg_hi:[1,0,0]
	v_pk_fma_f32 v[252:253], v[220:221], v[194:195], v[252:253] neg_lo:[1,0,0] neg_hi:[1,0,0]
	ds_read_b128 v[218:221], v21 offset:63232
	s_waitcnt lgkmcnt(4)
	v_pk_fma_f32 v[246:247], v[222:223], v[192:193], v[246:247] neg_lo:[1,0,0] neg_hi:[1,0,0]
	v_pk_fma_f32 v[254:255], v[224:225], v[194:195], v[254:255] neg_lo:[1,0,0] neg_hi:[1,0,0]
	v_pk_add_f32 v[240:241], v[240:241], v[248:249]
	v_add_f32_e32 v196, v240, v241
	ds_read_b128 v[222:225], v21 offset:63488
	s_waitcnt lgkmcnt(4)
	v_fma_f32 v242, -v196, v226, v242
	v_pk_add_f32 v[242:243], v[242:243], v[250:251]
	v_add_f32_e32 v197, v242, v243
	ds_read_b128 v[226:229], v21 offset:63744
	s_waitcnt lgkmcnt(4)
	v_pk_fma_f32 v[244:245], v[230:231], v[196:197], v[244:245] neg_lo:[1,0,0] neg_hi:[1,0,0]
	v_pk_add_f32 v[244:245], v[244:245], v[252:253]
	v_add_f32_e32 v198, v244, v245
	ds_read_b128 v[230:233], v21 offset:64000
	s_waitcnt lgkmcnt(4)
	v_pk_fma_f32 v[246:247], v[214:215], v[196:197], v[246:247] neg_lo:[1,0,0] neg_hi:[1,0,0]
	v_fma_f32 v254, -v198, v216, v254
	v_pk_add_f32 v[246:247], v[246:247], v[254:255]
	v_add_f32_e32 v199, v246, v247
	ds_read_b32 v240, v88 offset:13520
	ds_read_b32 v242, v88 offset:13780
	ds_read_b32 v244, v88 offset:14040
	ds_read_b32 v246, v88 offset:14300
	ds_read_b128 v[234:237], v121
	ds_read_b128 v[248:251], v122
	ds_read_b128 v[214:217], v21 offset:63248
	s_waitcnt lgkmcnt(1)
	v_mul_f32_e32 v240, v240, v234
	v_mul_f32_e32 v242, v242, v235
	v_mul_f32_e32 v244, v244, v236
	v_mul_f32_e32 v246, v246, v237
	v_mul_f32_e32 v238, v240, v248
	v_cndmask_b32_e64 v240, v240, v238, s[26:27]
	v_mov_b32_e32 v241, 0
	v_mul_f32_e32 v6, v242, v249
	v_cndmask_b32_e64 v242, v242, v6, s[26:27]
	v_mov_b32_e32 v243, 0
	v_mul_f32_e32 v7, v244, v250
	v_cndmask_b32_e64 v244, v244, v7, s[26:27]
	v_mov_b32_e32 v245, 0
	v_mul_f32_e32 v238, v246, v251
	v_cndmask_b32_e64 v246, v246, v238, s[26:27]
	v_mov_b32_e32 v247, 0
	v_pk_fma_f32 v[240:241], v[218:219], v[8:9], v[240:241] neg_lo:[1,0,0] neg_hi:[1,0,0]
	v_pk_fma_f32 v[248:249], v[220:221], v[10:11], 0 neg_lo:[1,0,0] neg_hi:[1,0,0]
	ds_read_b128 v[218:221], v21 offset:63504
	v_pk_fma_f32 v[242:243], v[222:223], v[8:9], v[242:243] neg_lo:[1,0,0] neg_hi:[1,0,0]
	v_pk_fma_f32 v[250:251], v[224:225], v[10:11], 0 neg_lo:[1,0,0] neg_hi:[1,0,0]
	ds_read_b128 v[222:225], v21 offset:63760
	v_pk_fma_f32 v[244:245], v[226:227], v[8:9], v[244:245] neg_lo:[1,0,0] neg_hi:[1,0,0]
	v_pk_fma_f32 v[252:253], v[228:229], v[10:11], 0 neg_lo:[1,0,0] neg_hi:[1,0,0]
	ds_read_b128 v[226:229], v21 offset:64016
	v_pk_fma_f32 v[246:247], v[230:231], v[8:9], v[246:247] neg_lo:[1,0,0] neg_hi:[1,0,0]
	v_pk_fma_f32 v[254:255], v[232:233], v[10:11], 0 neg_lo:[1,0,0] neg_hi:[1,0,0]
	ds_read_b128 v[230:233], v21 offset:63264
	s_waitcnt lgkmcnt(4)
	v_pk_fma_f32 v[240:241], v[214:215], v[12:13], v[240:241] neg_lo:[1,0,0] neg_hi:[1,0,0]
	v_pk_fma_f32 v[248:249], v[216:217], v[14:15], v[248:249] neg_lo:[1,0,0] neg_hi:[1,0,0]
	ds_read_b128 v[214:217], v21 offset:63520
	s_waitcnt lgkmcnt(4)
	v_pk_fma_f32 v[242:243], v[218:219], v[12:13], v[242:243] neg_lo:[1,0,0] neg_hi:[1,0,0]
	v_pk_fma_f32 v[250:251], v[220:221], v[14:15], v[250:251] neg_lo:[1,0,0] neg_hi:[1,0,0]
	ds_read_b128 v[218:221], v21 offset:63776
	s_waitcnt lgkmcnt(4)
	v_pk_fma_f32 v[244:245], v[222:223], v[12:13], v[244:245] neg_lo:[1,0,0] neg_hi:[1,0,0]
	v_pk_fma_f32 v[252:253], v[224:225], v[14:15], v[252:253] neg_lo:[1,0,0] neg_hi:[1,0,0]
	ds_read_b128 v[222:225], v21 offset:64032
	s_waitcnt lgkmcnt(4)
	v_pk_fma_f32 v[246:247], v[226:227], v[12:13], v[246:247] neg_lo:[1,0,0] neg_hi:[1,0,0]
	v_pk_fma_f32 v[254:255], v[228:229], v[14:15], v[254:255] neg_lo:[1,0,0] neg_hi:[1,0,0]
	ds_read_b128 v[226:229], v21 offset:63280
	s_waitcnt lgkmcnt(4)
	v_pk_fma_f32 v[240:241], v[230:231], v[4:5], v[240:241] neg_lo:[1,0,0] neg_hi:[1,0,0]
	v_pk_fma_f32 v[248:249], v[232:233], v[44:45], v[248:249] neg_lo:[1,0,0] neg_hi:[1,0,0]
	ds_read_b128 v[230:233], v21 offset:63536
	s_waitcnt lgkmcnt(4)
	v_pk_fma_f32 v[242:243], v[214:215], v[4:5], v[242:243] neg_lo:[1,0,0] neg_hi:[1,0,0]
	v_pk_fma_f32 v[250:251], v[216:217], v[44:45], v[250:251] neg_lo:[1,0,0] neg_hi:[1,0,0]
	ds_read_b128 v[214:217], v21 offset:63792
	s_waitcnt lgkmcnt(4)
	v_pk_fma_f32 v[244:245], v[218:219], v[4:5], v[244:245] neg_lo:[1,0,0] neg_hi:[1,0,0]
	v_pk_fma_f32 v[252:253], v[220:221], v[44:45], v[252:253] neg_lo:[1,0,0] neg_hi:[1,0,0]
	ds_read_b128 v[218:221], v21 offset:64048
	s_waitcnt lgkmcnt(4)
	v_pk_fma_f32 v[246:247], v[222:223], v[4:5], v[246:247] neg_lo:[1,0,0] neg_hi:[1,0,0]
	v_pk_fma_f32 v[254:255], v[224:225], v[44:45], v[254:255] neg_lo:[1,0,0] neg_hi:[1,0,0]
	ds_read_b128 v[222:225], v21 offset:63296
	s_waitcnt lgkmcnt(4)
	v_pk_fma_f32 v[240:241], v[226:227], v[46:47], v[240:241] neg_lo:[1,0,0] neg_hi:[1,0,0]
	v_pk_fma_f32 v[248:249], v[228:229], v[48:49], v[248:249] neg_lo:[1,0,0] neg_hi:[1,0,0]
	ds_read_b128 v[226:229], v21 offset:63552
	s_waitcnt lgkmcnt(4)
	v_pk_fma_f32 v[242:243], v[230:231], v[46:47], v[242:243] neg_lo:[1,0,0] neg_hi:[1,0,0]
	v_pk_fma_f32 v[250:251], v[232:233], v[48:49], v[250:251] neg_lo:[1,0,0] neg_hi:[1,0,0]
	ds_read_b128 v[230:233], v21 offset:63808
	s_waitcnt lgkmcnt(4)
	v_pk_fma_f32 v[244:245], v[214:215], v[46:47], v[244:245] neg_lo:[1,0,0] neg_hi:[1,0,0]
	v_pk_fma_f32 v[252:253], v[216:217], v[48:49], v[252:253] neg_lo:[1,0,0] neg_hi:[1,0,0]
	ds_read_b128 v[214:217], v21 offset:64064
	s_waitcnt lgkmcnt(4)
	v_pk_fma_f32 v[246:247], v[218:219], v[46:47], v[246:247] neg_lo:[1,0,0] neg_hi:[1,0,0]
	v_pk_fma_f32 v[254:255], v[220:221], v[48:49], v[254:255] neg_lo:[1,0,0] neg_hi:[1,0,0]
	ds_read_b128 v[218:221], v21 offset:63312
	s_waitcnt lgkmcnt(4)
	v_pk_fma_f32 v[240:241], v[222:223], v[50:51], v[240:241] neg_lo:[1,0,0] neg_hi:[1,0,0]
	v_pk_fma_f32 v[248:249], v[224:225], v[52:53], v[248:249] neg_lo:[1,0,0] neg_hi:[1,0,0]
	ds_read_b128 v[222:225], v21 offset:63568
	s_waitcnt lgkmcnt(4)
	v_pk_fma_f32 v[242:243], v[226:227], v[50:51], v[242:243] neg_lo:[1,0,0] neg_hi:[1,0,0]
	v_pk_fma_f32 v[250:251], v[228:229], v[52:53], v[250:251] neg_lo:[1,0,0] neg_hi:[1,0,0]
	ds_read_b128 v[226:229], v21 offset:63824
	s_waitcnt lgkmcnt(4)
	v_pk_fma_f32 v[244:245], v[230:231], v[50:51], v[244:245] neg_lo:[1,0,0] neg_hi:[1,0,0]
	v_pk_fma_f32 v[252:253], v[232:233], v[52:53], v[252:253] neg_lo:[1,0,0] neg_hi:[1,0,0]
	ds_read_b128 v[230:233], v21 offset:64080
	s_waitcnt lgkmcnt(4)
	v_pk_fma_f32 v[246:247], v[214:215], v[50:51], v[246:247] neg_lo:[1,0,0] neg_hi:[1,0,0]
	v_pk_fma_f32 v[254:255], v[216:217], v[52:53], v[254:255] neg_lo:[1,0,0] neg_hi:[1,0,0]
	ds_read_b128 v[214:217], v21 offset:63328
	s_waitcnt lgkmcnt(4)
	v_pk_fma_f32 v[240:241], v[218:219], v[54:55], v[240:241] neg_lo:[1,0,0] neg_hi:[1,0,0]
	v_pk_fma_f32 v[248:249], v[220:221], v[56:57], v[248:249] neg_lo:[1,0,0] neg_hi:[1,0,0]
	ds_read_b128 v[218:221], v21 offset:63584
	s_waitcnt lgkmcnt(4)
	v_pk_fma_f32 v[242:243], v[222:223], v[54:55], v[242:243] neg_lo:[1,0,0] neg_hi:[1,0,0]
	v_pk_fma_f32 v[250:251], v[224:225], v[56:57], v[250:251] neg_lo:[1,0,0] neg_hi:[1,0,0]
	ds_read_b128 v[222:225], v21 offset:63840
	s_waitcnt lgkmcnt(4)
	v_pk_fma_f32 v[244:245], v[226:227], v[54:55], v[244:245] neg_lo:[1,0,0] neg_hi:[1,0,0]
	v_pk_fma_f32 v[252:253], v[228:229], v[56:57], v[252:253] neg_lo:[1,0,0] neg_hi:[1,0,0]
	ds_read_b128 v[226:229], v21 offset:64096
	s_waitcnt lgkmcnt(4)
	v_pk_fma_f32 v[246:247], v[230:231], v[54:55], v[246:247] neg_lo:[1,0,0] neg_hi:[1,0,0]
	v_pk_fma_f32 v[254:255], v[232:233], v[56:57], v[254:255] neg_lo:[1,0,0] neg_hi:[1,0,0]
	ds_read_b128 v[230:233], v21 offset:63344
	s_waitcnt lgkmcnt(4)
	v_pk_fma_f32 v[240:241], v[214:215], v[58:59], v[240:241] neg_lo:[1,0,0] neg_hi:[1,0,0]
	v_pk_fma_f32 v[248:249], v[216:217], v[60:61], v[248:249] neg_lo:[1,0,0] neg_hi:[1,0,0]
	ds_read_b128 v[214:217], v21 offset:63600
	s_waitcnt lgkmcnt(4)
	v_pk_fma_f32 v[242:243], v[218:219], v[58:59], v[242:243] neg_lo:[1,0,0] neg_hi:[1,0,0]
	v_pk_fma_f32 v[250:251], v[220:221], v[60:61], v[250:251] neg_lo:[1,0,0] neg_hi:[1,0,0]
	ds_read_b128 v[218:221], v21 offset:63856
	s_waitcnt lgkmcnt(4)
	v_pk_fma_f32 v[244:245], v[222:223], v[58:59], v[244:245] neg_lo:[1,0,0] neg_hi:[1,0,0]
	v_pk_fma_f32 v[252:253], v[224:225], v[60:61], v[252:253] neg_lo:[1,0,0] neg_hi:[1,0,0]
	ds_read_b128 v[222:225], v21 offset:64112
	s_waitcnt lgkmcnt(4)
	v_pk_fma_f32 v[246:247], v[226:227], v[58:59], v[246:247] neg_lo:[1,0,0] neg_hi:[1,0,0]
	v_pk_fma_f32 v[254:255], v[228:229], v[60:61], v[254:255] neg_lo:[1,0,0] neg_hi:[1,0,0]
	ds_read_b128 v[226:229], v21 offset:63360
	s_waitcnt lgkmcnt(4)
	v_pk_fma_f32 v[240:241], v[230:231], v[62:63], v[240:241] neg_lo:[1,0,0] neg_hi:[1,0,0]
	v_pk_fma_f32 v[248:249], v[232:233], v[64:65], v[248:249] neg_lo:[1,0,0] neg_hi:[1,0,0]
	ds_read_b128 v[230:233], v21 offset:63616
	s_waitcnt lgkmcnt(4)
	v_pk_fma_f32 v[242:243], v[214:215], v[62:63], v[242:243] neg_lo:[1,0,0] neg_hi:[1,0,0]
	v_pk_fma_f32 v[250:251], v[216:217], v[64:65], v[250:251] neg_lo:[1,0,0] neg_hi:[1,0,0]
	ds_read_b128 v[214:217], v21 offset:63872
	s_waitcnt lgkmcnt(4)
	v_pk_fma_f32 v[244:245], v[218:219], v[62:63], v[244:245] neg_lo:[1,0,0] neg_hi:[1,0,0]
	v_pk_fma_f32 v[252:253], v[220:221], v[64:65], v[252:253] neg_lo:[1,0,0] neg_hi:[1,0,0]
	ds_read_b128 v[218:221], v21 offset:64128
	s_waitcnt lgkmcnt(4)
	v_pk_fma_f32 v[246:247], v[222:223], v[62:63], v[246:247] neg_lo:[1,0,0] neg_hi:[1,0,0]
	v_pk_fma_f32 v[254:255], v[224:225], v[64:65], v[254:255] neg_lo:[1,0,0] neg_hi:[1,0,0]
	ds_read_b128 v[222:225], v21 offset:63376
	s_waitcnt lgkmcnt(4)
	v_pk_fma_f32 v[240:241], v[226:227], v[66:67], v[240:241] neg_lo:[1,0,0] neg_hi:[1,0,0]
	v_pk_fma_f32 v[248:249], v[228:229], v[68:69], v[248:249] neg_lo:[1,0,0] neg_hi:[1,0,0]
	ds_read_b128 v[226:229], v21 offset:63632
	s_waitcnt lgkmcnt(4)
	v_pk_fma_f32 v[242:243], v[230:231], v[66:67], v[242:243] neg_lo:[1,0,0] neg_hi:[1,0,0]
	v_pk_fma_f32 v[250:251], v[232:233], v[68:69], v[250:251] neg_lo:[1,0,0] neg_hi:[1,0,0]
	ds_read_b128 v[230:233], v21 offset:63888
	s_waitcnt lgkmcnt(4)
	v_pk_fma_f32 v[244:245], v[214:215], v[66:67], v[244:245] neg_lo:[1,0,0] neg_hi:[1,0,0]
	v_pk_fma_f32 v[252:253], v[216:217], v[68:69], v[252:253] neg_lo:[1,0,0] neg_hi:[1,0,0]
	ds_read_b128 v[214:217], v21 offset:64144
	s_waitcnt lgkmcnt(4)
	v_pk_fma_f32 v[246:247], v[218:219], v[66:67], v[246:247] neg_lo:[1,0,0] neg_hi:[1,0,0]
	v_pk_fma_f32 v[254:255], v[220:221], v[68:69], v[254:255] neg_lo:[1,0,0] neg_hi:[1,0,0]
	ds_read_b128 v[218:221], v21 offset:63392
	s_waitcnt lgkmcnt(4)
	v_pk_fma_f32 v[240:241], v[222:223], v[184:185], v[240:241] neg_lo:[1,0,0] neg_hi:[1,0,0]
	v_pk_fma_f32 v[248:249], v[224:225], v[186:187], v[248:249] neg_lo:[1,0,0] neg_hi:[1,0,0]
	ds_read_b128 v[222:225], v21 offset:63648
	s_waitcnt lgkmcnt(4)
	v_pk_fma_f32 v[242:243], v[226:227], v[184:185], v[242:243] neg_lo:[1,0,0] neg_hi:[1,0,0]
	v_pk_fma_f32 v[250:251], v[228:229], v[186:187], v[250:251] neg_lo:[1,0,0] neg_hi:[1,0,0]
	ds_read_b128 v[226:229], v21 offset:63904
	s_waitcnt lgkmcnt(4)
	v_pk_fma_f32 v[244:245], v[230:231], v[184:185], v[244:245] neg_lo:[1,0,0] neg_hi:[1,0,0]
	v_pk_fma_f32 v[252:253], v[232:233], v[186:187], v[252:253] neg_lo:[1,0,0] neg_hi:[1,0,0]
	ds_read_b128 v[230:233], v21 offset:64160
	s_waitcnt lgkmcnt(4)
	v_pk_fma_f32 v[246:247], v[214:215], v[184:185], v[246:247] neg_lo:[1,0,0] neg_hi:[1,0,0]
	v_pk_fma_f32 v[254:255], v[216:217], v[186:187], v[254:255] neg_lo:[1,0,0] neg_hi:[1,0,0]
	ds_read_b128 v[214:217], v21 offset:63408
	s_waitcnt lgkmcnt(4)
	v_pk_fma_f32 v[240:241], v[218:219], v[188:189], v[240:241] neg_lo:[1,0,0] neg_hi:[1,0,0]
	v_pk_fma_f32 v[248:249], v[220:221], v[190:191], v[248:249] neg_lo:[1,0,0] neg_hi:[1,0,0]
	ds_read_b128 v[218:221], v21 offset:63664
	s_waitcnt lgkmcnt(4)
	v_pk_fma_f32 v[242:243], v[222:223], v[188:189], v[242:243] neg_lo:[1,0,0] neg_hi:[1,0,0]
	v_pk_fma_f32 v[250:251], v[224:225], v[190:191], v[250:251] neg_lo:[1,0,0] neg_hi:[1,0,0]
	ds_read_b128 v[222:225], v21 offset:63920
	s_waitcnt lgkmcnt(4)
	v_pk_fma_f32 v[244:245], v[226:227], v[188:189], v[244:245] neg_lo:[1,0,0] neg_hi:[1,0,0]
	v_pk_fma_f32 v[252:253], v[228:229], v[190:191], v[252:253] neg_lo:[1,0,0] neg_hi:[1,0,0]
	ds_read_b128 v[226:229], v21 offset:64176
	s_waitcnt lgkmcnt(4)
	v_pk_fma_f32 v[246:247], v[230:231], v[188:189], v[246:247] neg_lo:[1,0,0] neg_hi:[1,0,0]
	v_pk_fma_f32 v[254:255], v[232:233], v[190:191], v[254:255] neg_lo:[1,0,0] neg_hi:[1,0,0]
	ds_read_b128 v[230:233], v21 offset:63424
	s_waitcnt lgkmcnt(4)
	v_pk_fma_f32 v[240:241], v[214:215], v[192:193], v[240:241] neg_lo:[1,0,0] neg_hi:[1,0,0]
	v_pk_fma_f32 v[248:249], v[216:217], v[194:195], v[248:249] neg_lo:[1,0,0] neg_hi:[1,0,0]
	ds_read_b128 v[214:217], v21 offset:63680
	s_waitcnt lgkmcnt(4)
	v_pk_fma_f32 v[242:243], v[218:219], v[192:193], v[242:243] neg_lo:[1,0,0] neg_hi:[1,0,0]
	v_pk_fma_f32 v[250:251], v[220:221], v[194:195], v[250:251] neg_lo:[1,0,0] neg_hi:[1,0,0]
	ds_read_b128 v[218:221], v21 offset:63936
	s_waitcnt lgkmcnt(4)
	v_pk_fma_f32 v[244:245], v[222:223], v[192:193], v[244:245] neg_lo:[1,0,0] neg_hi:[1,0,0]
	v_pk_fma_f32 v[252:253], v[224:225], v[194:195], v[252:253] neg_lo:[1,0,0] neg_hi:[1,0,0]
	ds_read_b128 v[222:225], v21 offset:64192
	s_waitcnt lgkmcnt(4)
	v_pk_fma_f32 v[246:247], v[226:227], v[192:193], v[246:247] neg_lo:[1,0,0] neg_hi:[1,0,0]
	v_pk_fma_f32 v[254:255], v[228:229], v[194:195], v[254:255] neg_lo:[1,0,0] neg_hi:[1,0,0]
	ds_read_b128 v[226:229], v21 offset:63696
	s_waitcnt lgkmcnt(4)
	v_pk_fma_f32 v[240:241], v[230:231], v[196:197], v[240:241] neg_lo:[1,0,0] neg_hi:[1,0,0]
	v_pk_fma_f32 v[248:249], v[232:233], v[198:199], v[248:249] neg_lo:[1,0,0] neg_hi:[1,0,0]
	ds_read_b128 v[230:233], v21 offset:63952
	s_waitcnt lgkmcnt(4)
	v_pk_fma_f32 v[242:243], v[214:215], v[196:197], v[242:243] neg_lo:[1,0,0] neg_hi:[1,0,0]
	v_pk_fma_f32 v[250:251], v[216:217], v[198:199], v[250:251] neg_lo:[1,0,0] neg_hi:[1,0,0]
	ds_read_b128 v[214:217], v21 offset:64208
	s_waitcnt lgkmcnt(4)
	v_pk_fma_f32 v[244:245], v[218:219], v[196:197], v[244:245] neg_lo:[1,0,0] neg_hi:[1,0,0]
	v_pk_fma_f32 v[252:253], v[220:221], v[198:199], v[252:253] neg_lo:[1,0,0] neg_hi:[1,0,0]
	ds_read_b128 v[218:221], v21 offset:64256
	s_waitcnt lgkmcnt(4)
	v_pk_fma_f32 v[246:247], v[222:223], v[196:197], v[246:247] neg_lo:[1,0,0] neg_hi:[1,0,0]
	v_pk_fma_f32 v[254:255], v[224:225], v[198:199], v[254:255] neg_lo:[1,0,0] neg_hi:[1,0,0]
	v_pk_add_f32 v[240:241], v[240:241], v[248:249]
	v_add_f32_e32 v200, v240, v241
	ds_read_b128 v[222:225], v21 offset:64512
	s_waitcnt lgkmcnt(4)
	v_fma_f32 v242, -v200, v226, v242
	v_pk_add_f32 v[242:243], v[242:243], v[250:251]
	v_add_f32_e32 v201, v242, v243
	ds_read_b128 v[226:229], v21 offset:64768
	s_waitcnt lgkmcnt(4)
	v_pk_fma_f32 v[244:245], v[230:231], v[200:201], v[244:245] neg_lo:[1,0,0] neg_hi:[1,0,0]
	v_pk_add_f32 v[244:245], v[244:245], v[252:253]
	v_add_f32_e32 v202, v244, v245
	ds_read_b128 v[230:233], v21 offset:65024
	s_waitcnt lgkmcnt(4)
	v_pk_fma_f32 v[246:247], v[214:215], v[200:201], v[246:247] neg_lo:[1,0,0] neg_hi:[1,0,0]
	v_fma_f32 v254, -v202, v216, v254
	v_pk_add_f32 v[246:247], v[246:247], v[254:255]
	v_add_f32_e32 v203, v246, v247
	ds_read_b32 v240, v88 offset:14560
	ds_read_b32 v242, v88 offset:14820
	ds_read_b32 v244, v88 offset:15080
	ds_read_b32 v246, v88 offset:15340
	ds_read_b128 v[234:237], v123
	ds_read_b128 v[248:251], v124
	ds_read_b128 v[214:217], v21 offset:64272
	s_waitcnt lgkmcnt(1)
	v_mul_f32_e32 v240, v240, v234
	v_mul_f32_e32 v242, v242, v235
	v_mul_f32_e32 v244, v244, v236
	v_mul_f32_e32 v246, v246, v237
	v_mul_f32_e32 v238, v240, v248
	v_cndmask_b32_e64 v240, v240, v238, s[26:27]
	v_mov_b32_e32 v241, 0
	v_mul_f32_e32 v6, v242, v249
	v_cndmask_b32_e64 v242, v242, v6, s[26:27]
	v_mov_b32_e32 v243, 0
	v_mul_f32_e32 v7, v244, v250
	v_cndmask_b32_e64 v244, v244, v7, s[26:27]
	v_mov_b32_e32 v245, 0
	v_mul_f32_e32 v238, v246, v251
	v_cndmask_b32_e64 v246, v246, v238, s[26:27]
	v_mov_b32_e32 v247, 0
	v_pk_fma_f32 v[240:241], v[218:219], v[8:9], v[240:241] neg_lo:[1,0,0] neg_hi:[1,0,0]
	v_pk_fma_f32 v[248:249], v[220:221], v[10:11], 0 neg_lo:[1,0,0] neg_hi:[1,0,0]
	ds_read_b128 v[218:221], v21 offset:64528
	v_pk_fma_f32 v[242:243], v[222:223], v[8:9], v[242:243] neg_lo:[1,0,0] neg_hi:[1,0,0]
	v_pk_fma_f32 v[250:251], v[224:225], v[10:11], 0 neg_lo:[1,0,0] neg_hi:[1,0,0]
	ds_read_b128 v[222:225], v21 offset:64784
	v_pk_fma_f32 v[244:245], v[226:227], v[8:9], v[244:245] neg_lo:[1,0,0] neg_hi:[1,0,0]
	v_pk_fma_f32 v[252:253], v[228:229], v[10:11], 0 neg_lo:[1,0,0] neg_hi:[1,0,0]
	ds_read_b128 v[226:229], v21 offset:65040
	v_pk_fma_f32 v[246:247], v[230:231], v[8:9], v[246:247] neg_lo:[1,0,0] neg_hi:[1,0,0]
	v_pk_fma_f32 v[254:255], v[232:233], v[10:11], 0 neg_lo:[1,0,0] neg_hi:[1,0,0]
	ds_read_b128 v[230:233], v21 offset:64288
	s_waitcnt lgkmcnt(4)
	v_pk_fma_f32 v[240:241], v[214:215], v[12:13], v[240:241] neg_lo:[1,0,0] neg_hi:[1,0,0]
	v_pk_fma_f32 v[248:249], v[216:217], v[14:15], v[248:249] neg_lo:[1,0,0] neg_hi:[1,0,0]
	ds_read_b128 v[214:217], v21 offset:64544
	s_waitcnt lgkmcnt(4)
	v_pk_fma_f32 v[242:243], v[218:219], v[12:13], v[242:243] neg_lo:[1,0,0] neg_hi:[1,0,0]
	v_pk_fma_f32 v[250:251], v[220:221], v[14:15], v[250:251] neg_lo:[1,0,0] neg_hi:[1,0,0]
	ds_read_b128 v[218:221], v21 offset:64800
	s_waitcnt lgkmcnt(4)
	v_pk_fma_f32 v[244:245], v[222:223], v[12:13], v[244:245] neg_lo:[1,0,0] neg_hi:[1,0,0]
	v_pk_fma_f32 v[252:253], v[224:225], v[14:15], v[252:253] neg_lo:[1,0,0] neg_hi:[1,0,0]
	ds_read_b128 v[222:225], v21 offset:65056
	s_waitcnt lgkmcnt(4)
	v_pk_fma_f32 v[246:247], v[226:227], v[12:13], v[246:247] neg_lo:[1,0,0] neg_hi:[1,0,0]
	v_pk_fma_f32 v[254:255], v[228:229], v[14:15], v[254:255] neg_lo:[1,0,0] neg_hi:[1,0,0]
	ds_read_b128 v[226:229], v21 offset:64304
	s_waitcnt lgkmcnt(4)
	v_pk_fma_f32 v[240:241], v[230:231], v[4:5], v[240:241] neg_lo:[1,0,0] neg_hi:[1,0,0]
	v_pk_fma_f32 v[248:249], v[232:233], v[44:45], v[248:249] neg_lo:[1,0,0] neg_hi:[1,0,0]
	ds_read_b128 v[230:233], v21 offset:64560
	s_waitcnt lgkmcnt(4)
	v_pk_fma_f32 v[242:243], v[214:215], v[4:5], v[242:243] neg_lo:[1,0,0] neg_hi:[1,0,0]
	v_pk_fma_f32 v[250:251], v[216:217], v[44:45], v[250:251] neg_lo:[1,0,0] neg_hi:[1,0,0]
	ds_read_b128 v[214:217], v21 offset:64816
	s_waitcnt lgkmcnt(4)
	v_pk_fma_f32 v[244:245], v[218:219], v[4:5], v[244:245] neg_lo:[1,0,0] neg_hi:[1,0,0]
	v_pk_fma_f32 v[252:253], v[220:221], v[44:45], v[252:253] neg_lo:[1,0,0] neg_hi:[1,0,0]
	ds_read_b128 v[218:221], v21 offset:65072
	s_waitcnt lgkmcnt(4)
	v_pk_fma_f32 v[246:247], v[222:223], v[4:5], v[246:247] neg_lo:[1,0,0] neg_hi:[1,0,0]
	v_pk_fma_f32 v[254:255], v[224:225], v[44:45], v[254:255] neg_lo:[1,0,0] neg_hi:[1,0,0]
	ds_read_b128 v[222:225], v21 offset:64320
	s_waitcnt lgkmcnt(4)
	v_pk_fma_f32 v[240:241], v[226:227], v[46:47], v[240:241] neg_lo:[1,0,0] neg_hi:[1,0,0]
	v_pk_fma_f32 v[248:249], v[228:229], v[48:49], v[248:249] neg_lo:[1,0,0] neg_hi:[1,0,0]
	ds_read_b128 v[226:229], v21 offset:64576
	s_waitcnt lgkmcnt(4)
	v_pk_fma_f32 v[242:243], v[230:231], v[46:47], v[242:243] neg_lo:[1,0,0] neg_hi:[1,0,0]
	v_pk_fma_f32 v[250:251], v[232:233], v[48:49], v[250:251] neg_lo:[1,0,0] neg_hi:[1,0,0]
	ds_read_b128 v[230:233], v21 offset:64832
	s_waitcnt lgkmcnt(4)
	v_pk_fma_f32 v[244:245], v[214:215], v[46:47], v[244:245] neg_lo:[1,0,0] neg_hi:[1,0,0]
	v_pk_fma_f32 v[252:253], v[216:217], v[48:49], v[252:253] neg_lo:[1,0,0] neg_hi:[1,0,0]
	ds_read_b128 v[214:217], v21 offset:65088
	s_waitcnt lgkmcnt(4)
	v_pk_fma_f32 v[246:247], v[218:219], v[46:47], v[246:247] neg_lo:[1,0,0] neg_hi:[1,0,0]
	v_pk_fma_f32 v[254:255], v[220:221], v[48:49], v[254:255] neg_lo:[1,0,0] neg_hi:[1,0,0]
	ds_read_b128 v[218:221], v21 offset:64336
	s_waitcnt lgkmcnt(4)
	v_pk_fma_f32 v[240:241], v[222:223], v[50:51], v[240:241] neg_lo:[1,0,0] neg_hi:[1,0,0]
	v_pk_fma_f32 v[248:249], v[224:225], v[52:53], v[248:249] neg_lo:[1,0,0] neg_hi:[1,0,0]
	ds_read_b128 v[222:225], v21 offset:64592
	s_waitcnt lgkmcnt(4)
	v_pk_fma_f32 v[242:243], v[226:227], v[50:51], v[242:243] neg_lo:[1,0,0] neg_hi:[1,0,0]
	v_pk_fma_f32 v[250:251], v[228:229], v[52:53], v[250:251] neg_lo:[1,0,0] neg_hi:[1,0,0]
	ds_read_b128 v[226:229], v21 offset:64848
	s_waitcnt lgkmcnt(4)
	v_pk_fma_f32 v[244:245], v[230:231], v[50:51], v[244:245] neg_lo:[1,0,0] neg_hi:[1,0,0]
	v_pk_fma_f32 v[252:253], v[232:233], v[52:53], v[252:253] neg_lo:[1,0,0] neg_hi:[1,0,0]
	ds_read_b128 v[230:233], v21 offset:65104
	s_waitcnt lgkmcnt(4)
	v_pk_fma_f32 v[246:247], v[214:215], v[50:51], v[246:247] neg_lo:[1,0,0] neg_hi:[1,0,0]
	v_pk_fma_f32 v[254:255], v[216:217], v[52:53], v[254:255] neg_lo:[1,0,0] neg_hi:[1,0,0]
	ds_read_b128 v[214:217], v21 offset:64352
	s_waitcnt lgkmcnt(4)
	v_pk_fma_f32 v[240:241], v[218:219], v[54:55], v[240:241] neg_lo:[1,0,0] neg_hi:[1,0,0]
	v_pk_fma_f32 v[248:249], v[220:221], v[56:57], v[248:249] neg_lo:[1,0,0] neg_hi:[1,0,0]
	ds_read_b128 v[218:221], v21 offset:64608
	s_waitcnt lgkmcnt(4)
	v_pk_fma_f32 v[242:243], v[222:223], v[54:55], v[242:243] neg_lo:[1,0,0] neg_hi:[1,0,0]
	v_pk_fma_f32 v[250:251], v[224:225], v[56:57], v[250:251] neg_lo:[1,0,0] neg_hi:[1,0,0]
	ds_read_b128 v[222:225], v21 offset:64864
	s_waitcnt lgkmcnt(4)
	v_pk_fma_f32 v[244:245], v[226:227], v[54:55], v[244:245] neg_lo:[1,0,0] neg_hi:[1,0,0]
	v_pk_fma_f32 v[252:253], v[228:229], v[56:57], v[252:253] neg_lo:[1,0,0] neg_hi:[1,0,0]
	ds_read_b128 v[226:229], v21 offset:65120
	s_waitcnt lgkmcnt(4)
	v_pk_fma_f32 v[246:247], v[230:231], v[54:55], v[246:247] neg_lo:[1,0,0] neg_hi:[1,0,0]
	v_pk_fma_f32 v[254:255], v[232:233], v[56:57], v[254:255] neg_lo:[1,0,0] neg_hi:[1,0,0]
	ds_read_b128 v[230:233], v21 offset:64368
	s_waitcnt lgkmcnt(4)
	v_pk_fma_f32 v[240:241], v[214:215], v[58:59], v[240:241] neg_lo:[1,0,0] neg_hi:[1,0,0]
	v_pk_fma_f32 v[248:249], v[216:217], v[60:61], v[248:249] neg_lo:[1,0,0] neg_hi:[1,0,0]
	ds_read_b128 v[214:217], v21 offset:64624
	s_waitcnt lgkmcnt(4)
	v_pk_fma_f32 v[242:243], v[218:219], v[58:59], v[242:243] neg_lo:[1,0,0] neg_hi:[1,0,0]
	v_pk_fma_f32 v[250:251], v[220:221], v[60:61], v[250:251] neg_lo:[1,0,0] neg_hi:[1,0,0]
	ds_read_b128 v[218:221], v21 offset:64880
	s_waitcnt lgkmcnt(4)
	v_pk_fma_f32 v[244:245], v[222:223], v[58:59], v[244:245] neg_lo:[1,0,0] neg_hi:[1,0,0]
	v_pk_fma_f32 v[252:253], v[224:225], v[60:61], v[252:253] neg_lo:[1,0,0] neg_hi:[1,0,0]
	ds_read_b128 v[222:225], v21 offset:65136
	s_waitcnt lgkmcnt(4)
	v_pk_fma_f32 v[246:247], v[226:227], v[58:59], v[246:247] neg_lo:[1,0,0] neg_hi:[1,0,0]
	v_pk_fma_f32 v[254:255], v[228:229], v[60:61], v[254:255] neg_lo:[1,0,0] neg_hi:[1,0,0]
	ds_read_b128 v[226:229], v21 offset:64384
	s_waitcnt lgkmcnt(4)
	v_pk_fma_f32 v[240:241], v[230:231], v[62:63], v[240:241] neg_lo:[1,0,0] neg_hi:[1,0,0]
	v_pk_fma_f32 v[248:249], v[232:233], v[64:65], v[248:249] neg_lo:[1,0,0] neg_hi:[1,0,0]
	ds_read_b128 v[230:233], v21 offset:64640
	s_waitcnt lgkmcnt(4)
	v_pk_fma_f32 v[242:243], v[214:215], v[62:63], v[242:243] neg_lo:[1,0,0] neg_hi:[1,0,0]
	v_pk_fma_f32 v[250:251], v[216:217], v[64:65], v[250:251] neg_lo:[1,0,0] neg_hi:[1,0,0]
	ds_read_b128 v[214:217], v21 offset:64896
	s_waitcnt lgkmcnt(4)
	v_pk_fma_f32 v[244:245], v[218:219], v[62:63], v[244:245] neg_lo:[1,0,0] neg_hi:[1,0,0]
	v_pk_fma_f32 v[252:253], v[220:221], v[64:65], v[252:253] neg_lo:[1,0,0] neg_hi:[1,0,0]
	ds_read_b128 v[218:221], v21 offset:65152
	s_waitcnt lgkmcnt(4)
	v_pk_fma_f32 v[246:247], v[222:223], v[62:63], v[246:247] neg_lo:[1,0,0] neg_hi:[1,0,0]
	v_pk_fma_f32 v[254:255], v[224:225], v[64:65], v[254:255] neg_lo:[1,0,0] neg_hi:[1,0,0]
	ds_read_b128 v[222:225], v21 offset:64400
	s_waitcnt lgkmcnt(4)
	v_pk_fma_f32 v[240:241], v[226:227], v[66:67], v[240:241] neg_lo:[1,0,0] neg_hi:[1,0,0]
	v_pk_fma_f32 v[248:249], v[228:229], v[68:69], v[248:249] neg_lo:[1,0,0] neg_hi:[1,0,0]
	ds_read_b128 v[226:229], v21 offset:64656
	s_waitcnt lgkmcnt(4)
	v_pk_fma_f32 v[242:243], v[230:231], v[66:67], v[242:243] neg_lo:[1,0,0] neg_hi:[1,0,0]
	v_pk_fma_f32 v[250:251], v[232:233], v[68:69], v[250:251] neg_lo:[1,0,0] neg_hi:[1,0,0]
	ds_read_b128 v[230:233], v21 offset:64912
	s_waitcnt lgkmcnt(4)
	v_pk_fma_f32 v[244:245], v[214:215], v[66:67], v[244:245] neg_lo:[1,0,0] neg_hi:[1,0,0]
	v_pk_fma_f32 v[252:253], v[216:217], v[68:69], v[252:253] neg_lo:[1,0,0] neg_hi:[1,0,0]
	ds_read_b128 v[214:217], v21 offset:65168
	s_waitcnt lgkmcnt(4)
	v_pk_fma_f32 v[246:247], v[218:219], v[66:67], v[246:247] neg_lo:[1,0,0] neg_hi:[1,0,0]
	v_pk_fma_f32 v[254:255], v[220:221], v[68:69], v[254:255] neg_lo:[1,0,0] neg_hi:[1,0,0]
	ds_read_b128 v[218:221], v21 offset:64416
	s_waitcnt lgkmcnt(4)
	v_pk_fma_f32 v[240:241], v[222:223], v[184:185], v[240:241] neg_lo:[1,0,0] neg_hi:[1,0,0]
	v_pk_fma_f32 v[248:249], v[224:225], v[186:187], v[248:249] neg_lo:[1,0,0] neg_hi:[1,0,0]
	ds_read_b128 v[222:225], v21 offset:64672
	s_waitcnt lgkmcnt(4)
	v_pk_fma_f32 v[242:243], v[226:227], v[184:185], v[242:243] neg_lo:[1,0,0] neg_hi:[1,0,0]
	v_pk_fma_f32 v[250:251], v[228:229], v[186:187], v[250:251] neg_lo:[1,0,0] neg_hi:[1,0,0]
	ds_read_b128 v[226:229], v21 offset:64928
	s_waitcnt lgkmcnt(4)
	v_pk_fma_f32 v[244:245], v[230:231], v[184:185], v[244:245] neg_lo:[1,0,0] neg_hi:[1,0,0]
	v_pk_fma_f32 v[252:253], v[232:233], v[186:187], v[252:253] neg_lo:[1,0,0] neg_hi:[1,0,0]
	ds_read_b128 v[230:233], v21 offset:65184
	s_waitcnt lgkmcnt(4)
	v_pk_fma_f32 v[246:247], v[214:215], v[184:185], v[246:247] neg_lo:[1,0,0] neg_hi:[1,0,0]
	v_pk_fma_f32 v[254:255], v[216:217], v[186:187], v[254:255] neg_lo:[1,0,0] neg_hi:[1,0,0]
	ds_read_b128 v[214:217], v21 offset:64432
	s_waitcnt lgkmcnt(4)
	v_pk_fma_f32 v[240:241], v[218:219], v[188:189], v[240:241] neg_lo:[1,0,0] neg_hi:[1,0,0]
	v_pk_fma_f32 v[248:249], v[220:221], v[190:191], v[248:249] neg_lo:[1,0,0] neg_hi:[1,0,0]
	ds_read_b128 v[218:221], v21 offset:64688
	s_waitcnt lgkmcnt(4)
	v_pk_fma_f32 v[242:243], v[222:223], v[188:189], v[242:243] neg_lo:[1,0,0] neg_hi:[1,0,0]
	v_pk_fma_f32 v[250:251], v[224:225], v[190:191], v[250:251] neg_lo:[1,0,0] neg_hi:[1,0,0]
	ds_read_b128 v[222:225], v21 offset:64944
	s_waitcnt lgkmcnt(4)
	v_pk_fma_f32 v[244:245], v[226:227], v[188:189], v[244:245] neg_lo:[1,0,0] neg_hi:[1,0,0]
	v_pk_fma_f32 v[252:253], v[228:229], v[190:191], v[252:253] neg_lo:[1,0,0] neg_hi:[1,0,0]
	ds_read_b128 v[226:229], v21 offset:65200
	s_waitcnt lgkmcnt(4)
	v_pk_fma_f32 v[246:247], v[230:231], v[188:189], v[246:247] neg_lo:[1,0,0] neg_hi:[1,0,0]
	v_pk_fma_f32 v[254:255], v[232:233], v[190:191], v[254:255] neg_lo:[1,0,0] neg_hi:[1,0,0]
	ds_read_b128 v[230:233], v21 offset:64448
	s_waitcnt lgkmcnt(4)
	v_pk_fma_f32 v[240:241], v[214:215], v[192:193], v[240:241] neg_lo:[1,0,0] neg_hi:[1,0,0]
	v_pk_fma_f32 v[248:249], v[216:217], v[194:195], v[248:249] neg_lo:[1,0,0] neg_hi:[1,0,0]
	ds_read_b128 v[214:217], v21 offset:64704
	s_waitcnt lgkmcnt(4)
	v_pk_fma_f32 v[242:243], v[218:219], v[192:193], v[242:243] neg_lo:[1,0,0] neg_hi:[1,0,0]
	v_pk_fma_f32 v[250:251], v[220:221], v[194:195], v[250:251] neg_lo:[1,0,0] neg_hi:[1,0,0]
	ds_read_b128 v[218:221], v21 offset:64960
	s_waitcnt lgkmcnt(4)
	v_pk_fma_f32 v[244:245], v[222:223], v[192:193], v[244:245] neg_lo:[1,0,0] neg_hi:[1,0,0]
	v_pk_fma_f32 v[252:253], v[224:225], v[194:195], v[252:253] neg_lo:[1,0,0] neg_hi:[1,0,0]
	ds_read_b128 v[222:225], v21 offset:65216
	s_waitcnt lgkmcnt(4)
	v_pk_fma_f32 v[246:247], v[226:227], v[192:193], v[246:247] neg_lo:[1,0,0] neg_hi:[1,0,0]
	v_pk_fma_f32 v[254:255], v[228:229], v[194:195], v[254:255] neg_lo:[1,0,0] neg_hi:[1,0,0]
	ds_read_b128 v[226:229], v21 offset:64464
	s_waitcnt lgkmcnt(4)
	v_pk_fma_f32 v[240:241], v[230:231], v[196:197], v[240:241] neg_lo:[1,0,0] neg_hi:[1,0,0]
	v_pk_fma_f32 v[248:249], v[232:233], v[198:199], v[248:249] neg_lo:[1,0,0] neg_hi:[1,0,0]
	ds_read_b128 v[230:233], v21 offset:64720
	s_waitcnt lgkmcnt(4)
	v_pk_fma_f32 v[242:243], v[214:215], v[196:197], v[242:243] neg_lo:[1,0,0] neg_hi:[1,0,0]
	v_pk_fma_f32 v[250:251], v[216:217], v[198:199], v[250:251] neg_lo:[1,0,0] neg_hi:[1,0,0]
	ds_read_b128 v[214:217], v21 offset:64976
	s_waitcnt lgkmcnt(4)
	v_pk_fma_f32 v[244:245], v[218:219], v[196:197], v[244:245] neg_lo:[1,0,0] neg_hi:[1,0,0]
	v_pk_fma_f32 v[252:253], v[220:221], v[198:199], v[252:253] neg_lo:[1,0,0] neg_hi:[1,0,0]
	ds_read_b128 v[218:221], v21 offset:65232
	s_waitcnt lgkmcnt(4)
	v_pk_fma_f32 v[246:247], v[222:223], v[196:197], v[246:247] neg_lo:[1,0,0] neg_hi:[1,0,0]
	v_pk_fma_f32 v[254:255], v[224:225], v[198:199], v[254:255] neg_lo:[1,0,0] neg_hi:[1,0,0]
	ds_read_b128 v[222:225], v21 offset:64736
	s_waitcnt lgkmcnt(4)
	v_pk_fma_f32 v[240:241], v[226:227], v[200:201], v[240:241] neg_lo:[1,0,0] neg_hi:[1,0,0]
	v_pk_fma_f32 v[248:249], v[228:229], v[202:203], v[248:249] neg_lo:[1,0,0] neg_hi:[1,0,0]
	ds_read_b128 v[226:229], v21 offset:64992
	s_waitcnt lgkmcnt(4)
	v_pk_fma_f32 v[242:243], v[230:231], v[200:201], v[242:243] neg_lo:[1,0,0] neg_hi:[1,0,0]
	v_pk_fma_f32 v[250:251], v[232:233], v[202:203], v[250:251] neg_lo:[1,0,0] neg_hi:[1,0,0]
	ds_read_b128 v[230:233], v21 offset:65248
	s_waitcnt lgkmcnt(4)
	v_pk_fma_f32 v[244:245], v[214:215], v[200:201], v[244:245] neg_lo:[1,0,0] neg_hi:[1,0,0]
	v_pk_fma_f32 v[252:253], v[216:217], v[202:203], v[252:253] neg_lo:[1,0,0] neg_hi:[1,0,0]
	ds_read_b128 v[214:217], v21 offset:65280
	s_waitcnt lgkmcnt(4)
	v_pk_fma_f32 v[246:247], v[218:219], v[200:201], v[246:247] neg_lo:[1,0,0] neg_hi:[1,0,0]
	v_pk_fma_f32 v[254:255], v[220:221], v[202:203], v[254:255] neg_lo:[1,0,0] neg_hi:[1,0,0]
	v_pk_add_f32 v[240:241], v[240:241], v[248:249]
	v_add_f32_e32 v204, v240, v241
	ds_read_b128 v[218:221], v20 offset:32768
	s_waitcnt lgkmcnt(4)
	v_fma_f32 v242, -v204, v222, v242
	v_pk_add_f32 v[242:243], v[242:243], v[250:251]
	v_add_f32_e32 v205, v242, v243
	ds_read_b128 v[222:225], v20 offset:33024
	s_waitcnt lgkmcnt(4)
	v_pk_fma_f32 v[244:245], v[226:227], v[204:205], v[244:245] neg_lo:[1,0,0] neg_hi:[1,0,0]
	v_pk_add_f32 v[244:245], v[244:245], v[252:253]
	v_add_f32_e32 v206, v244, v245
	ds_read_b128 v[226:229], v20 offset:33280
	s_waitcnt lgkmcnt(4)
	v_pk_fma_f32 v[246:247], v[230:231], v[204:205], v[246:247] neg_lo:[1,0,0] neg_hi:[1,0,0]
	v_fma_f32 v254, -v206, v232, v254
	v_pk_add_f32 v[246:247], v[246:247], v[254:255]
	v_add_f32_e32 v207, v246, v247
	ds_read_b32 v240, v88 offset:15600
	ds_read_b32 v242, v88 offset:15860
	ds_read_b32 v244, v88 offset:16120
	ds_read_b32 v246, v88 offset:16380
	ds_read_b128 v[234:237], v125
	ds_read_b128 v[248:251], v126
	ds_read_b128 v[230:233], v21 offset:65296
	s_waitcnt lgkmcnt(1)
	v_mul_f32_e32 v240, v240, v234
	v_mul_f32_e32 v242, v242, v235
	v_mul_f32_e32 v244, v244, v236
	v_mul_f32_e32 v246, v246, v237
	v_mul_f32_e32 v238, v240, v248
	v_cndmask_b32_e64 v240, v240, v238, s[26:27]
	v_mov_b32_e32 v241, 0
	v_mul_f32_e32 v6, v242, v249
	v_cndmask_b32_e64 v242, v242, v6, s[26:27]
	v_mov_b32_e32 v243, 0
	v_mul_f32_e32 v7, v244, v250
	v_cndmask_b32_e64 v244, v244, v7, s[26:27]
	v_mov_b32_e32 v245, 0
	v_mul_f32_e32 v238, v246, v251
	v_cndmask_b32_e64 v246, v246, v238, s[26:27]
	v_mov_b32_e32 v247, 0
	v_pk_fma_f32 v[240:241], v[214:215], v[8:9], v[240:241] neg_lo:[1,0,0] neg_hi:[1,0,0]
	v_pk_fma_f32 v[248:249], v[216:217], v[10:11], 0 neg_lo:[1,0,0] neg_hi:[1,0,0]
	ds_read_b128 v[214:217], v20 offset:32784
	v_pk_fma_f32 v[242:243], v[218:219], v[8:9], v[242:243] neg_lo:[1,0,0] neg_hi:[1,0,0]
	v_pk_fma_f32 v[250:251], v[220:221], v[10:11], 0 neg_lo:[1,0,0] neg_hi:[1,0,0]
	ds_read_b128 v[218:221], v20 offset:33040
	v_pk_fma_f32 v[244:245], v[222:223], v[8:9], v[244:245] neg_lo:[1,0,0] neg_hi:[1,0,0]
	v_pk_fma_f32 v[252:253], v[224:225], v[10:11], 0 neg_lo:[1,0,0] neg_hi:[1,0,0]
	ds_read_b128 v[222:225], v20 offset:33296
	v_pk_fma_f32 v[246:247], v[226:227], v[8:9], v[246:247] neg_lo:[1,0,0] neg_hi:[1,0,0]
	v_pk_fma_f32 v[254:255], v[228:229], v[10:11], 0 neg_lo:[1,0,0] neg_hi:[1,0,0]
	ds_read_b128 v[226:229], v21 offset:65312
	s_waitcnt lgkmcnt(4)
	v_pk_fma_f32 v[240:241], v[230:231], v[12:13], v[240:241] neg_lo:[1,0,0] neg_hi:[1,0,0]
	v_pk_fma_f32 v[248:249], v[232:233], v[14:15], v[248:249] neg_lo:[1,0,0] neg_hi:[1,0,0]
	ds_read_b128 v[230:233], v20 offset:32800
	s_waitcnt lgkmcnt(4)
	v_pk_fma_f32 v[242:243], v[214:215], v[12:13], v[242:243] neg_lo:[1,0,0] neg_hi:[1,0,0]
	v_pk_fma_f32 v[250:251], v[216:217], v[14:15], v[250:251] neg_lo:[1,0,0] neg_hi:[1,0,0]
	ds_read_b128 v[214:217], v20 offset:33056
	s_waitcnt lgkmcnt(4)
	v_pk_fma_f32 v[244:245], v[218:219], v[12:13], v[244:245] neg_lo:[1,0,0] neg_hi:[1,0,0]
	v_pk_fma_f32 v[252:253], v[220:221], v[14:15], v[252:253] neg_lo:[1,0,0] neg_hi:[1,0,0]
	ds_read_b128 v[218:221], v20 offset:33312
	s_waitcnt lgkmcnt(4)
	v_pk_fma_f32 v[246:247], v[222:223], v[12:13], v[246:247] neg_lo:[1,0,0] neg_hi:[1,0,0]
	v_pk_fma_f32 v[254:255], v[224:225], v[14:15], v[254:255] neg_lo:[1,0,0] neg_hi:[1,0,0]
	ds_read_b128 v[222:225], v21 offset:65328
	s_waitcnt lgkmcnt(4)
	v_pk_fma_f32 v[240:241], v[226:227], v[4:5], v[240:241] neg_lo:[1,0,0] neg_hi:[1,0,0]
	v_pk_fma_f32 v[248:249], v[228:229], v[44:45], v[248:249] neg_lo:[1,0,0] neg_hi:[1,0,0]
	ds_read_b128 v[226:229], v20 offset:32816
	s_waitcnt lgkmcnt(4)
	v_pk_fma_f32 v[242:243], v[230:231], v[4:5], v[242:243] neg_lo:[1,0,0] neg_hi:[1,0,0]
	v_pk_fma_f32 v[250:251], v[232:233], v[44:45], v[250:251] neg_lo:[1,0,0] neg_hi:[1,0,0]
	ds_read_b128 v[230:233], v20 offset:33072
	s_waitcnt lgkmcnt(4)
	v_pk_fma_f32 v[244:245], v[214:215], v[4:5], v[244:245] neg_lo:[1,0,0] neg_hi:[1,0,0]
	v_pk_fma_f32 v[252:253], v[216:217], v[44:45], v[252:253] neg_lo:[1,0,0] neg_hi:[1,0,0]
	ds_read_b128 v[214:217], v20 offset:33328
	s_waitcnt lgkmcnt(4)
	v_pk_fma_f32 v[246:247], v[218:219], v[4:5], v[246:247] neg_lo:[1,0,0] neg_hi:[1,0,0]
	v_pk_fma_f32 v[254:255], v[220:221], v[44:45], v[254:255] neg_lo:[1,0,0] neg_hi:[1,0,0]
	ds_read_b128 v[218:221], v21 offset:65344
	s_waitcnt lgkmcnt(4)
	v_pk_fma_f32 v[240:241], v[222:223], v[46:47], v[240:241] neg_lo:[1,0,0] neg_hi:[1,0,0]
	v_pk_fma_f32 v[248:249], v[224:225], v[48:49], v[248:249] neg_lo:[1,0,0] neg_hi:[1,0,0]
	ds_read_b128 v[222:225], v20 offset:32832
	s_waitcnt lgkmcnt(4)
	v_pk_fma_f32 v[242:243], v[226:227], v[46:47], v[242:243] neg_lo:[1,0,0] neg_hi:[1,0,0]
	v_pk_fma_f32 v[250:251], v[228:229], v[48:49], v[250:251] neg_lo:[1,0,0] neg_hi:[1,0,0]
	ds_read_b128 v[226:229], v20 offset:33088
	s_waitcnt lgkmcnt(4)
	v_pk_fma_f32 v[244:245], v[230:231], v[46:47], v[244:245] neg_lo:[1,0,0] neg_hi:[1,0,0]
	v_pk_fma_f32 v[252:253], v[232:233], v[48:49], v[252:253] neg_lo:[1,0,0] neg_hi:[1,0,0]
	ds_read_b128 v[230:233], v20 offset:33344
	s_waitcnt lgkmcnt(4)
	v_pk_fma_f32 v[246:247], v[214:215], v[46:47], v[246:247] neg_lo:[1,0,0] neg_hi:[1,0,0]
	v_pk_fma_f32 v[254:255], v[216:217], v[48:49], v[254:255] neg_lo:[1,0,0] neg_hi:[1,0,0]
	ds_read_b128 v[214:217], v21 offset:65360
	s_waitcnt lgkmcnt(4)
	v_pk_fma_f32 v[240:241], v[218:219], v[50:51], v[240:241] neg_lo:[1,0,0] neg_hi:[1,0,0]
	v_pk_fma_f32 v[248:249], v[220:221], v[52:53], v[248:249] neg_lo:[1,0,0] neg_hi:[1,0,0]
	ds_read_b128 v[218:221], v20 offset:32848
	s_waitcnt lgkmcnt(4)
	v_pk_fma_f32 v[242:243], v[222:223], v[50:51], v[242:243] neg_lo:[1,0,0] neg_hi:[1,0,0]
	v_pk_fma_f32 v[250:251], v[224:225], v[52:53], v[250:251] neg_lo:[1,0,0] neg_hi:[1,0,0]
	ds_read_b128 v[222:225], v20 offset:33104
	s_waitcnt lgkmcnt(4)
	v_pk_fma_f32 v[244:245], v[226:227], v[50:51], v[244:245] neg_lo:[1,0,0] neg_hi:[1,0,0]
	v_pk_fma_f32 v[252:253], v[228:229], v[52:53], v[252:253] neg_lo:[1,0,0] neg_hi:[1,0,0]
	ds_read_b128 v[226:229], v20 offset:33360
	s_waitcnt lgkmcnt(4)
	v_pk_fma_f32 v[246:247], v[230:231], v[50:51], v[246:247] neg_lo:[1,0,0] neg_hi:[1,0,0]
	v_pk_fma_f32 v[254:255], v[232:233], v[52:53], v[254:255] neg_lo:[1,0,0] neg_hi:[1,0,0]
	ds_read_b128 v[230:233], v21 offset:65376
	s_waitcnt lgkmcnt(4)
	v_pk_fma_f32 v[240:241], v[214:215], v[54:55], v[240:241] neg_lo:[1,0,0] neg_hi:[1,0,0]
	v_pk_fma_f32 v[248:249], v[216:217], v[56:57], v[248:249] neg_lo:[1,0,0] neg_hi:[1,0,0]
	ds_read_b128 v[214:217], v20 offset:32864
	s_waitcnt lgkmcnt(4)
	v_pk_fma_f32 v[242:243], v[218:219], v[54:55], v[242:243] neg_lo:[1,0,0] neg_hi:[1,0,0]
	v_pk_fma_f32 v[250:251], v[220:221], v[56:57], v[250:251] neg_lo:[1,0,0] neg_hi:[1,0,0]
	ds_read_b128 v[218:221], v20 offset:33120
	s_waitcnt lgkmcnt(4)
	v_pk_fma_f32 v[244:245], v[222:223], v[54:55], v[244:245] neg_lo:[1,0,0] neg_hi:[1,0,0]
	v_pk_fma_f32 v[252:253], v[224:225], v[56:57], v[252:253] neg_lo:[1,0,0] neg_hi:[1,0,0]
	ds_read_b128 v[222:225], v20 offset:33376
	s_waitcnt lgkmcnt(4)
	v_pk_fma_f32 v[246:247], v[226:227], v[54:55], v[246:247] neg_lo:[1,0,0] neg_hi:[1,0,0]
	v_pk_fma_f32 v[254:255], v[228:229], v[56:57], v[254:255] neg_lo:[1,0,0] neg_hi:[1,0,0]
	ds_read_b128 v[226:229], v21 offset:65392
	s_waitcnt lgkmcnt(4)
	v_pk_fma_f32 v[240:241], v[230:231], v[58:59], v[240:241] neg_lo:[1,0,0] neg_hi:[1,0,0]
	v_pk_fma_f32 v[248:249], v[232:233], v[60:61], v[248:249] neg_lo:[1,0,0] neg_hi:[1,0,0]
	ds_read_b128 v[230:233], v20 offset:32880
	s_waitcnt lgkmcnt(4)
	v_pk_fma_f32 v[242:243], v[214:215], v[58:59], v[242:243] neg_lo:[1,0,0] neg_hi:[1,0,0]
	v_pk_fma_f32 v[250:251], v[216:217], v[60:61], v[250:251] neg_lo:[1,0,0] neg_hi:[1,0,0]
	ds_read_b128 v[214:217], v20 offset:33136
	s_waitcnt lgkmcnt(4)
	v_pk_fma_f32 v[244:245], v[218:219], v[58:59], v[244:245] neg_lo:[1,0,0] neg_hi:[1,0,0]
	v_pk_fma_f32 v[252:253], v[220:221], v[60:61], v[252:253] neg_lo:[1,0,0] neg_hi:[1,0,0]
	ds_read_b128 v[218:221], v20 offset:33392
	s_waitcnt lgkmcnt(4)
	v_pk_fma_f32 v[246:247], v[222:223], v[58:59], v[246:247] neg_lo:[1,0,0] neg_hi:[1,0,0]
	v_pk_fma_f32 v[254:255], v[224:225], v[60:61], v[254:255] neg_lo:[1,0,0] neg_hi:[1,0,0]
	ds_read_b128 v[222:225], v21 offset:65408
	s_waitcnt lgkmcnt(4)
	v_pk_fma_f32 v[240:241], v[226:227], v[62:63], v[240:241] neg_lo:[1,0,0] neg_hi:[1,0,0]
	v_pk_fma_f32 v[248:249], v[228:229], v[64:65], v[248:249] neg_lo:[1,0,0] neg_hi:[1,0,0]
	ds_read_b128 v[226:229], v20 offset:32896
	s_waitcnt lgkmcnt(4)
	v_pk_fma_f32 v[242:243], v[230:231], v[62:63], v[242:243] neg_lo:[1,0,0] neg_hi:[1,0,0]
	v_pk_fma_f32 v[250:251], v[232:233], v[64:65], v[250:251] neg_lo:[1,0,0] neg_hi:[1,0,0]
	ds_read_b128 v[230:233], v20 offset:33152
	s_waitcnt lgkmcnt(4)
	v_pk_fma_f32 v[244:245], v[214:215], v[62:63], v[244:245] neg_lo:[1,0,0] neg_hi:[1,0,0]
	v_pk_fma_f32 v[252:253], v[216:217], v[64:65], v[252:253] neg_lo:[1,0,0] neg_hi:[1,0,0]
	ds_read_b128 v[214:217], v20 offset:33408
	s_waitcnt lgkmcnt(4)
	v_pk_fma_f32 v[246:247], v[218:219], v[62:63], v[246:247] neg_lo:[1,0,0] neg_hi:[1,0,0]
	v_pk_fma_f32 v[254:255], v[220:221], v[64:65], v[254:255] neg_lo:[1,0,0] neg_hi:[1,0,0]
	ds_read_b128 v[218:221], v21 offset:65424
	s_waitcnt lgkmcnt(4)
	v_pk_fma_f32 v[240:241], v[222:223], v[66:67], v[240:241] neg_lo:[1,0,0] neg_hi:[1,0,0]
	v_pk_fma_f32 v[248:249], v[224:225], v[68:69], v[248:249] neg_lo:[1,0,0] neg_hi:[1,0,0]
	ds_read_b128 v[222:225], v20 offset:32912
	s_waitcnt lgkmcnt(4)
	v_pk_fma_f32 v[242:243], v[226:227], v[66:67], v[242:243] neg_lo:[1,0,0] neg_hi:[1,0,0]
	v_pk_fma_f32 v[250:251], v[228:229], v[68:69], v[250:251] neg_lo:[1,0,0] neg_hi:[1,0,0]
	ds_read_b128 v[226:229], v20 offset:33168
	s_waitcnt lgkmcnt(4)
	v_pk_fma_f32 v[244:245], v[230:231], v[66:67], v[244:245] neg_lo:[1,0,0] neg_hi:[1,0,0]
	v_pk_fma_f32 v[252:253], v[232:233], v[68:69], v[252:253] neg_lo:[1,0,0] neg_hi:[1,0,0]
	ds_read_b128 v[230:233], v20 offset:33424
	s_waitcnt lgkmcnt(4)
	v_pk_fma_f32 v[246:247], v[214:215], v[66:67], v[246:247] neg_lo:[1,0,0] neg_hi:[1,0,0]
	v_pk_fma_f32 v[254:255], v[216:217], v[68:69], v[254:255] neg_lo:[1,0,0] neg_hi:[1,0,0]
	ds_read_b128 v[214:217], v21 offset:65440
	s_waitcnt lgkmcnt(4)
	v_pk_fma_f32 v[240:241], v[218:219], v[184:185], v[240:241] neg_lo:[1,0,0] neg_hi:[1,0,0]
	v_pk_fma_f32 v[248:249], v[220:221], v[186:187], v[248:249] neg_lo:[1,0,0] neg_hi:[1,0,0]
	ds_read_b128 v[218:221], v20 offset:32928
	s_waitcnt lgkmcnt(4)
	v_pk_fma_f32 v[242:243], v[222:223], v[184:185], v[242:243] neg_lo:[1,0,0] neg_hi:[1,0,0]
	v_pk_fma_f32 v[250:251], v[224:225], v[186:187], v[250:251] neg_lo:[1,0,0] neg_hi:[1,0,0]
	ds_read_b128 v[222:225], v20 offset:33184
	s_waitcnt lgkmcnt(4)
	v_pk_fma_f32 v[244:245], v[226:227], v[184:185], v[244:245] neg_lo:[1,0,0] neg_hi:[1,0,0]
	v_pk_fma_f32 v[252:253], v[228:229], v[186:187], v[252:253] neg_lo:[1,0,0] neg_hi:[1,0,0]
	ds_read_b128 v[226:229], v20 offset:33440
	s_waitcnt lgkmcnt(4)
	v_pk_fma_f32 v[246:247], v[230:231], v[184:185], v[246:247] neg_lo:[1,0,0] neg_hi:[1,0,0]
	v_pk_fma_f32 v[254:255], v[232:233], v[186:187], v[254:255] neg_lo:[1,0,0] neg_hi:[1,0,0]
	ds_read_b128 v[230:233], v21 offset:65456
	s_waitcnt lgkmcnt(4)
	v_pk_fma_f32 v[240:241], v[214:215], v[188:189], v[240:241] neg_lo:[1,0,0] neg_hi:[1,0,0]
	v_pk_fma_f32 v[248:249], v[216:217], v[190:191], v[248:249] neg_lo:[1,0,0] neg_hi:[1,0,0]
	ds_read_b128 v[214:217], v20 offset:32944
	s_waitcnt lgkmcnt(4)
	v_pk_fma_f32 v[242:243], v[218:219], v[188:189], v[242:243] neg_lo:[1,0,0] neg_hi:[1,0,0]
	v_pk_fma_f32 v[250:251], v[220:221], v[190:191], v[250:251] neg_lo:[1,0,0] neg_hi:[1,0,0]
	ds_read_b128 v[218:221], v20 offset:33200
	s_waitcnt lgkmcnt(4)
	v_pk_fma_f32 v[244:245], v[222:223], v[188:189], v[244:245] neg_lo:[1,0,0] neg_hi:[1,0,0]
	v_pk_fma_f32 v[252:253], v[224:225], v[190:191], v[252:253] neg_lo:[1,0,0] neg_hi:[1,0,0]
	ds_read_b128 v[222:225], v20 offset:33456
	s_waitcnt lgkmcnt(4)
	v_pk_fma_f32 v[246:247], v[226:227], v[188:189], v[246:247] neg_lo:[1,0,0] neg_hi:[1,0,0]
	v_pk_fma_f32 v[254:255], v[228:229], v[190:191], v[254:255] neg_lo:[1,0,0] neg_hi:[1,0,0]
	ds_read_b128 v[226:229], v21 offset:65472
	s_waitcnt lgkmcnt(4)
	v_pk_fma_f32 v[240:241], v[230:231], v[192:193], v[240:241] neg_lo:[1,0,0] neg_hi:[1,0,0]
	v_pk_fma_f32 v[248:249], v[232:233], v[194:195], v[248:249] neg_lo:[1,0,0] neg_hi:[1,0,0]
	ds_read_b128 v[230:233], v20 offset:32960
	s_waitcnt lgkmcnt(4)
	v_pk_fma_f32 v[242:243], v[214:215], v[192:193], v[242:243] neg_lo:[1,0,0] neg_hi:[1,0,0]
	v_pk_fma_f32 v[250:251], v[216:217], v[194:195], v[250:251] neg_lo:[1,0,0] neg_hi:[1,0,0]
	ds_read_b128 v[214:217], v20 offset:33216
	s_waitcnt lgkmcnt(4)
	v_pk_fma_f32 v[244:245], v[218:219], v[192:193], v[244:245] neg_lo:[1,0,0] neg_hi:[1,0,0]
	v_pk_fma_f32 v[252:253], v[220:221], v[194:195], v[252:253] neg_lo:[1,0,0] neg_hi:[1,0,0]
	ds_read_b128 v[218:221], v20 offset:33472
	s_waitcnt lgkmcnt(4)
	v_pk_fma_f32 v[246:247], v[222:223], v[192:193], v[246:247] neg_lo:[1,0,0] neg_hi:[1,0,0]
	v_pk_fma_f32 v[254:255], v[224:225], v[194:195], v[254:255] neg_lo:[1,0,0] neg_hi:[1,0,0]
	ds_read_b128 v[222:225], v21 offset:65488
	s_waitcnt lgkmcnt(4)
	v_pk_fma_f32 v[240:241], v[226:227], v[196:197], v[240:241] neg_lo:[1,0,0] neg_hi:[1,0,0]
	v_pk_fma_f32 v[248:249], v[228:229], v[198:199], v[248:249] neg_lo:[1,0,0] neg_hi:[1,0,0]
	ds_read_b128 v[226:229], v20 offset:32976
	s_waitcnt lgkmcnt(4)
	v_pk_fma_f32 v[242:243], v[230:231], v[196:197], v[242:243] neg_lo:[1,0,0] neg_hi:[1,0,0]
	v_pk_fma_f32 v[250:251], v[232:233], v[198:199], v[250:251] neg_lo:[1,0,0] neg_hi:[1,0,0]
	ds_read_b128 v[230:233], v20 offset:33232
	s_waitcnt lgkmcnt(4)
	v_pk_fma_f32 v[244:245], v[214:215], v[196:197], v[244:245] neg_lo:[1,0,0] neg_hi:[1,0,0]
	v_pk_fma_f32 v[252:253], v[216:217], v[198:199], v[252:253] neg_lo:[1,0,0] neg_hi:[1,0,0]
	ds_read_b128 v[214:217], v20 offset:33488
	s_waitcnt lgkmcnt(4)
	v_pk_fma_f32 v[246:247], v[218:219], v[196:197], v[246:247] neg_lo:[1,0,0] neg_hi:[1,0,0]
	v_pk_fma_f32 v[254:255], v[220:221], v[198:199], v[254:255] neg_lo:[1,0,0] neg_hi:[1,0,0]
	ds_read_b128 v[218:221], v21 offset:65504
	s_waitcnt lgkmcnt(4)
	v_pk_fma_f32 v[240:241], v[222:223], v[200:201], v[240:241] neg_lo:[1,0,0] neg_hi:[1,0,0]
	v_pk_fma_f32 v[248:249], v[224:225], v[202:203], v[248:249] neg_lo:[1,0,0] neg_hi:[1,0,0]
	ds_read_b128 v[222:225], v20 offset:32992
	s_waitcnt lgkmcnt(4)
	v_pk_fma_f32 v[242:243], v[226:227], v[200:201], v[242:243] neg_lo:[1,0,0] neg_hi:[1,0,0]
	v_pk_fma_f32 v[250:251], v[228:229], v[202:203], v[250:251] neg_lo:[1,0,0] neg_hi:[1,0,0]
	ds_read_b128 v[226:229], v20 offset:33248
	s_waitcnt lgkmcnt(4)
	v_pk_fma_f32 v[244:245], v[230:231], v[200:201], v[244:245] neg_lo:[1,0,0] neg_hi:[1,0,0]
	v_pk_fma_f32 v[252:253], v[232:233], v[202:203], v[252:253] neg_lo:[1,0,0] neg_hi:[1,0,0]
	ds_read_b128 v[230:233], v20 offset:33504
	s_waitcnt lgkmcnt(4)
	v_pk_fma_f32 v[246:247], v[214:215], v[200:201], v[246:247] neg_lo:[1,0,0] neg_hi:[1,0,0]
	v_pk_fma_f32 v[254:255], v[216:217], v[202:203], v[254:255] neg_lo:[1,0,0] neg_hi:[1,0,0]
	ds_read_b128 v[214:217], v20 offset:33008
	s_waitcnt lgkmcnt(4)
	v_pk_fma_f32 v[240:241], v[218:219], v[204:205], v[240:241] neg_lo:[1,0,0] neg_hi:[1,0,0]
	v_pk_fma_f32 v[248:249], v[220:221], v[206:207], v[248:249] neg_lo:[1,0,0] neg_hi:[1,0,0]
	ds_read_b128 v[218:221], v20 offset:33264
	s_waitcnt lgkmcnt(4)
	v_pk_fma_f32 v[242:243], v[222:223], v[204:205], v[242:243] neg_lo:[1,0,0] neg_hi:[1,0,0]
	v_pk_fma_f32 v[250:251], v[224:225], v[206:207], v[250:251] neg_lo:[1,0,0] neg_hi:[1,0,0]
	ds_read_b128 v[222:225], v20 offset:33520
	s_waitcnt lgkmcnt(4)
	v_pk_fma_f32 v[244:245], v[226:227], v[204:205], v[244:245] neg_lo:[1,0,0] neg_hi:[1,0,0]
	v_pk_fma_f32 v[252:253], v[228:229], v[206:207], v[252:253] neg_lo:[1,0,0] neg_hi:[1,0,0]
	s_waitcnt lgkmcnt(3)
	v_pk_fma_f32 v[246:247], v[230:231], v[204:205], v[246:247] neg_lo:[1,0,0] neg_hi:[1,0,0]
	v_pk_fma_f32 v[254:255], v[232:233], v[206:207], v[254:255] neg_lo:[1,0,0] neg_hi:[1,0,0]
	v_pk_add_f32 v[240:241], v[240:241], v[248:249]
	v_add_f32_e32 v0, v240, v241
	s_waitcnt lgkmcnt(2)
	v_fma_f32 v242, -v0, v214, v242
	v_pk_add_f32 v[242:243], v[242:243], v[250:251]
	v_add_f32_e32 v1, v242, v243
	s_waitcnt lgkmcnt(1)
	v_pk_fma_f32 v[244:245], v[218:219], v[0:1], v[244:245] neg_lo:[1,0,0] neg_hi:[1,0,0]
	v_pk_add_f32 v[244:245], v[244:245], v[252:253]
	v_add_f32_e32 v2, v244, v245
	s_waitcnt lgkmcnt(0)
	v_pk_fma_f32 v[246:247], v[222:223], v[0:1], v[246:247] neg_lo:[1,0,0] neg_hi:[1,0,0]
	v_fma_f32 v254, -v2, v224, v254
	v_pk_add_f32 v[246:247], v[246:247], v[254:255]
	v_add_f32_e32 v3, v246, v247
	v_mov_b32_e32 v41, v4
	v_mov_b32_e32 v43, v5
	s_and_saveexec_b64 s[28:29], s[2:3]
	s_xor_b64 s[28:29], exec, s[28:29]
	s_cbranch_execz .LBB0_3021
	v_cvt_pk_bf16_f32 v4, v8, v9
	v_cvt_pk_bf16_f32 v5, v10, v11
	v_cvt_pk_bf16_f32 v6, v12, v13
	v_cvt_pk_bf16_f32 v7, v14, v15
	global_store_dwordx4 v175, v[4:7], s[30:31]
	s_nop 1
	v_cvt_pk_bf16_f32 v4, v41, v43
	v_cvt_pk_bf16_f32 v5, v44, v45
	v_cvt_pk_bf16_f32 v6, v46, v47
	v_cvt_pk_bf16_f32 v7, v48, v49
	global_store_dwordx4 v175, v[4:7], s[30:31] offset:16
	s_nop 1
	v_cvt_pk_bf16_f32 v4, v50, v51
	v_cvt_pk_bf16_f32 v5, v52, v53
	v_cvt_pk_bf16_f32 v6, v54, v55
	v_cvt_pk_bf16_f32 v7, v56, v57
	global_store_dwordx4 v175, v[4:7], s[30:31] offset:32
	s_nop 1
	v_cvt_pk_bf16_f32 v4, v58, v59
	v_cvt_pk_bf16_f32 v5, v60, v61
	v_cvt_pk_bf16_f32 v6, v62, v63
	v_cvt_pk_bf16_f32 v7, v64, v65
	global_store_dwordx4 v175, v[4:7], s[30:31] offset:48
	s_nop 1
	v_cvt_pk_bf16_f32 v4, v66, v67
	v_cvt_pk_bf16_f32 v5, v68, v69
	v_cvt_pk_bf16_f32 v6, v184, v185
	v_cvt_pk_bf16_f32 v7, v186, v187
	global_store_dwordx4 v175, v[4:7], s[30:31] offset:64
	s_nop 1
	v_cvt_pk_bf16_f32 v4, v188, v189
	v_cvt_pk_bf16_f32 v5, v190, v191
	v_cvt_pk_bf16_f32 v6, v192, v193
	v_cvt_pk_bf16_f32 v7, v194, v195
	global_store_dwordx4 v175, v[4:7], s[30:31] offset:80
	s_nop 1
	v_cvt_pk_bf16_f32 v4, v196, v197
	v_cvt_pk_bf16_f32 v5, v198, v199
	v_cvt_pk_bf16_f32 v6, v200, v201
	v_cvt_pk_bf16_f32 v7, v202, v203
	global_store_dwordx4 v175, v[4:7], s[30:31] offset:96
	s_nop 1
	v_cvt_pk_bf16_f32 v4, v204, v205
	v_cvt_pk_bf16_f32 v5, v206, v207
	v_cvt_pk_bf16_f32 v6, v0, v1
	v_cvt_pk_bf16_f32 v7, v2, v3
	global_store_dwordx4 v175, v[4:7], s[30:31] offset:112
